# tail units of phases 7,13,16: K loop rewritten with coalesced loads staged through per-wave LDS
# speedup vs baseline: 1.0323x; 1.0323x over previous
; #define STAGE(P, g) do { const char* g_ = (const char*)(g); \
;         __builtin_amdgcn_global_load_lds((const unsigned*)(g_ + so0), (lds_u32*)((lds_u8*)(P) + sb0), 16, 0, 0); \
;         __builtin_amdgcn_global_load_lds((const unsigned*)(g_ + so1), (lds_u32*)((lds_u8*)(P) + sb0 + 8192), 16, 0, 0); } while (0)
; #define LDA(dst, b, h) for (int m = 0; m < 4; ++m) for (int k = 0; k < 2; ++k) \
;         dst[m][k] = *reinterpret_cast<const bf16x8*>((char*)SA(b, h) + lds_byte(wr * 64 + m * 16 + fr, k * 32 + fq * 8))
; #define LDB(dst, b, h) for (int n = 0; n < 2; ++n) for (int k = 0; k < 2; ++k) \
;         dst[n][k] = *reinterpret_cast<const bf16x8*>((char*)SB(b, h) + lds_byte(wc * 32 + n * 16 + fr, k * 32 + fq * 8))
; #define MMA(ai, bj, At_, Bt_) do { __builtin_amdgcn_s_setprio(1); \
;         for (int m = 0; m < 4; ++m) for (int n = 0; n < 2; ++n) for (int k = 0; k < 2; ++k) \
;             acc[ai][bj][m][n] = __builtin_amdgcn_mfma_f32_16x16x32_bf16(At_[m][k], Bt_[n][k], acc[ai][bj][m][n], 0, 0, 0); \
;         __builtin_amdgcn_s_setprio(0); } while (0)
; #define WAIT_V(n) asm volatile("s_waitcnt vmcnt(" #n ")" ::: "memory")
; #define WAIT_L(n) asm volatile("s_waitcnt lgkmcnt(" #n ")" ::: "memory")
; #define BAR __builtin_amdgcn_s_barrier()
; template <int EPI, int K, int LNI = -1>
; DI void ph_gemm(const Params& p, const bf16_t* __restrict__ A, const bf16_t* __restrict__ Bt, int N, float* s_aux) {
;     ...
;         for (int t = 0; t < nt; t += 2) {
;             const bool last = (t == nt - 2);
;             const bf16_t* a1 = cA + (size_t)(t + 1) * kstep;
;             const bf16_t* a2 = last ? nA : cA + (size_t)(t + 2) * kstep; const bf16_t* b2 = last ? nB : cB + (size_t)(t + 2) * kstep;
;             const bf16_t* a3 = a2 + kstep; const bf16_t* b3 = b2 + kstep;
;             LDB(B0, 0, 0); LDB(B1, 0, 1); SCHED; LDA(At, 0, 0); STAGE(SA(1, 1), a1 + hstep);
;             WAIT_V(8); WAIT_L(0); BAR; MMA(0, 0, At, B0); MMA(0, 1, At, B1); BAR; SCHED;
;             LDA(At, 0, 1); STAGE(SB(0, 0), b2); STAGE(SB(0, 1), b2 + hstep); STAGE(SA(0, 0), a2);
;             WAIT_V(8); WAIT_L(0); BAR; MMA(1, 0, At, B0); MMA(1, 1, At, B1); BAR; SCHED;
;             LDB(B0, 1, 0); LDB(B1, 1, 1); SCHED; LDA(At, 1, 0); STAGE(SA(0, 1), a2 + hstep);
;             WAIT_V(8); WAIT_L(0); BAR; MMA(0, 0, At, B0); MMA(0, 1, At, B1); BAR; SCHED;
.LBB0_928:
	ds_read_b128 v[166:169], v156
	ds_read_b128 v[170:173], v156 offset:1024
	ds_read_b128 v[174:177], v156 offset:2048
	ds_read_b128 v[178:181], v156 offset:3072
	ds_read_b128 v[182:185], v157
	ds_read_b128 v[186:189], v157 offset:1024
	ds_read_b128 v[190:193], v157 offset:2048
	ds_read_b128 v[194:197], v157 offset:3072
	s_add_u32 s44, s50, s28
	s_addc_u32 s45, s51, s29
	s_add_u32 s44, s44, 0xb840100
	s_addc_u32 s45, s45, 0
	s_add_u32 s61, s52, s28
	s_addc_u32 s66, s53, s29
	s_cmpk_eq_i32 s28, 0x700
	s_cselect_b32 s47, s42, s45
	s_cselect_b32 s46, s15, s44
	s_cselect_b32 s45, s43, s66
	s_cselect_b32 s44, s19, s61
	v_readfirstlane_b32 s61, v162
	v_lshl_add_u64 v[232:233], v[136:137], 0, s[28:29]
	s_mov_b32 m0, s61
	v_readfirstlane_b32 s61, v163
	ds_read_b128 v[198:201], v158
	ds_read_b128 v[202:205], v158 offset:1024
	ds_read_b128 v[206:209], v159
	ds_read_b128 v[212:215], v159 offset:1024
	ds_read_b128 v[216:219], v160
	ds_read_b128 v[220:223], v160 offset:1024
	ds_read_b128 v[224:227], v161
	ds_read_b128 v[228:231], v161 offset:1024
	global_load_lds_dwordx4 v[232:233], off
	v_lshl_add_u64 v[232:233], v[138:139], 0, s[28:29]
	s_mov_b32 m0, s61
	s_nop 0
	global_load_lds_dwordx4 v[232:233], off
	s_waitcnt vmcnt(8)
	s_waitcnt lgkmcnt(0)
	s_barrier
	s_setprio 1
	s_waitcnt lgkmcnt(0)
	v_mfma_f32_16x16x32_bf16 v[124:127], v[198:201], v[166:169], v[124:127]
	v_mfma_f32_16x16x32_bf16 v[120:123], v[198:201], v[174:177], v[120:123]
	v_mfma_f32_16x16x32_bf16 v[108:111], v[206:209], v[166:169], v[108:111]
	v_mfma_f32_16x16x32_bf16 v[104:107], v[206:209], v[174:177], v[104:107]
	v_mfma_f32_16x16x32_bf16 v[92:95], v[216:219], v[166:169], v[92:95]
	v_mfma_f32_16x16x32_bf16 v[88:91], v[216:219], v[174:177], v[88:91]
	v_mfma_f32_16x16x32_bf16 v[76:79], v[224:227], v[166:169], v[76:79]
	v_mfma_f32_16x16x32_bf16 v[72:75], v[224:227], v[174:177], v[72:75]
	v_mfma_f32_16x16x32_bf16 v[124:127], v[202:205], v[170:173], v[124:127]
	v_mfma_f32_16x16x32_bf16 v[120:123], v[202:205], v[178:181], v[120:123]
	v_mfma_f32_16x16x32_bf16 v[108:111], v[212:215], v[170:173], v[108:111]
	v_mfma_f32_16x16x32_bf16 v[104:107], v[212:215], v[178:181], v[104:107]
	v_mfma_f32_16x16x32_bf16 v[92:95], v[220:223], v[170:173], v[92:95]
	v_mfma_f32_16x16x32_bf16 v[88:91], v[220:223], v[178:181], v[88:91]
	v_mfma_f32_16x16x32_bf16 v[76:79], v[228:231], v[170:173], v[76:79]
	v_mfma_f32_16x16x32_bf16 v[72:75], v[228:231], v[178:181], v[72:75]
	s_setprio 0
	s_setprio 1
	v_mfma_f32_16x16x32_bf16 v[116:119], v[198:201], v[182:185], v[116:119]
	v_mfma_f32_16x16x32_bf16 v[112:115], v[198:201], v[190:193], v[112:115]
	v_mfma_f32_16x16x32_bf16 v[100:103], v[206:209], v[182:185], v[100:103]
	v_mfma_f32_16x16x32_bf16 v[96:99], v[206:209], v[190:193], v[96:99]
	v_mfma_f32_16x16x32_bf16 v[84:87], v[216:219], v[182:185], v[84:87]
	v_mfma_f32_16x16x32_bf16 v[80:83], v[216:219], v[190:193], v[80:83]
	v_mfma_f32_16x16x32_bf16 v[68:71], v[224:227], v[182:185], v[68:71]
	v_mfma_f32_16x16x32_bf16 v[64:67], v[224:227], v[190:193], v[64:67]
	v_mfma_f32_16x16x32_bf16 v[116:119], v[202:205], v[186:189], v[116:119]
	v_mfma_f32_16x16x32_bf16 v[112:115], v[202:205], v[194:197], v[112:115]
	v_mfma_f32_16x16x32_bf16 v[100:103], v[212:215], v[186:189], v[100:103]
	v_mfma_f32_16x16x32_bf16 v[96:99], v[212:215], v[194:197], v[96:99]
	v_mfma_f32_16x16x32_bf16 v[84:87], v[220:223], v[186:189], v[84:87]
	v_mfma_f32_16x16x32_bf16 v[80:83], v[220:223], v[194:197], v[80:83]
	v_mfma_f32_16x16x32_bf16 v[68:71], v[228:231], v[186:189], v[68:71]
	v_mfma_f32_16x16x32_bf16 v[64:67], v[228:231], v[194:197], v[64:67]
	s_setprio 0
	s_barrier
	v_readfirstlane_b32 s61, v140
	v_lshl_add_u64 v[232:233], s[44:45], 0, v[128:129]
	s_mov_b32 m0, s61
	v_readfirstlane_b32 s61, v141
	s_add_u32 s66, s44, 0x40000
	ds_read_b128 v[198:201], v158 offset:16384
	ds_read_b128 v[202:205], v158 offset:17408
	ds_read_b128 v[206:209], v159 offset:16384
	ds_read_b128 v[212:215], v159 offset:17408
	ds_read_b128 v[216:219], v160 offset:16384
	ds_read_b128 v[220:223], v160 offset:17408
	ds_read_b128 v[224:227], v161 offset:16384
	ds_read_b128 v[228:231], v161 offset:17408
	global_load_lds_dwordx4 v[232:233], off
	v_lshl_add_u64 v[234:235], s[44:45], 0, v[130:131]
	s_mov_b32 m0, s61
	s_addc_u32 s67, s45, 0
	v_readfirstlane_b32 s61, v142
	global_load_lds_dwordx4 v[234:235], off
	v_lshl_add_u64 v[236:237], s[66:67], 0, v[128:129]
	s_mov_b32 m0, s61
	v_readfirstlane_b32 s61, v143
	global_load_lds_dwordx4 v[236:237], off
	v_lshl_add_u64 v[236:237], s[66:67], 0, v[130:131]
	s_mov_b32 m0, s61
	v_readfirstlane_b32 s61, v144
	global_load_lds_dwordx4 v[236:237], off
	v_lshl_add_u64 v[236:237], s[46:47], 0, v[128:129]
	s_mov_b32 m0, s61
	v_readfirstlane_b32 s61, v145
	global_load_lds_dwordx4 v[236:237], off
	v_lshl_add_u64 v[238:239], s[46:47], 0, v[130:131]
	s_mov_b32 m0, s61
	s_nop 0
	global_load_lds_dwordx4 v[238:239], off
	s_waitcnt vmcnt(8)
	s_waitcnt lgkmcnt(0)
	s_barrier
; #define STAGE(P, g) do { const char* g_ = (const char*)(g); \
;         __builtin_amdgcn_global_load_lds((const unsigned*)(g_ + so0), (lds_u32*)((lds_u8*)(P) + sb0), 16, 0, 0); \
;         __builtin_amdgcn_global_load_lds((const unsigned*)(g_ + so1), (lds_u32*)((lds_u8*)(P) + sb0 + 8192), 16, 0, 0); } while (0)
; #define LDA(dst, b, h) for (int m = 0; m < 4; ++m) for (int k = 0; k < 2; ++k) \
;         dst[m][k] = *reinterpret_cast<const bf16x8*>((char*)SA(b, h) + lds_byte(wr * 64 + m * 16 + fr, k * 32 + fq * 8))
; #define LDB(dst, b, h) for (int n = 0; n < 2; ++n) for (int k = 0; k < 2; ++k) \
;         dst[n][k] = *reinterpret_cast<const bf16x8*>((char*)SB(b, h) + lds_byte(wc * 32 + n * 16 + fr, k * 32 + fq * 8))
; #define MMA(ai, bj, At_, Bt_) do { __builtin_amdgcn_s_setprio(1); \
;         for (int m = 0; m < 4; ++m) for (int n = 0; n < 2; ++n) for (int k = 0; k < 2; ++k) \
;             acc[ai][bj][m][n] = __builtin_amdgcn_mfma_f32_16x16x32_bf16(At_[m][k], Bt_[n][k], acc[ai][bj][m][n], 0, 0, 0); \
;         __builtin_amdgcn_s_setprio(0); } while (0)
; #define WAIT_V(n) asm volatile("s_waitcnt vmcnt(" #n ")" ::: "memory")
; #define WAIT_L(n) asm volatile("s_waitcnt lgkmcnt(" #n ")" ::: "memory")
; #define BAR __builtin_amdgcn_s_barrier()
; #define SCHED __builtin_amdgcn_sched_barrier(0)
; template <int EPI, int K, int LNI = -1>
; DI void ph_gemm(const Params& p, const bf16_t* __restrict__ A, const bf16_t* __restrict__ Bt, int N, float* s_aux) {
;     ...
;             WAIT_V(8); WAIT_L(0); BAR; MMA(0, 0, At, B0); MMA(0, 1, At, B1); BAR; SCHED;
;             LDA(At, 0, 1); STAGE(SB(0, 0), b2); STAGE(SB(0, 1), b2 + hstep); STAGE(SA(0, 0), a2);
;             WAIT_V(8); WAIT_L(0); BAR; MMA(1, 0, At, B0); MMA(1, 1, At, B1); BAR; SCHED;
;             LDB(B0, 1, 0); LDB(B1, 1, 1); SCHED; LDA(At, 1, 0); STAGE(SA(0, 1), a2 + hstep);
;             WAIT_V(8); WAIT_L(0); BAR; MMA(0, 0, At, B0); MMA(0, 1, At, B1); BAR; SCHED;
;             LDA(At, 1, 1); STAGE(SB(1, 0), b3); STAGE(SB(1, 1), b3 + hstep); STAGE(SA(1, 0), a3);
	s_setprio 1
	s_waitcnt lgkmcnt(0)
	v_mfma_f32_16x16x32_bf16 v[60:63], v[198:201], v[166:169], v[60:63]
	v_mfma_f32_16x16x32_bf16 v[56:59], v[198:201], v[174:177], v[56:59]
	v_mfma_f32_16x16x32_bf16 v[44:47], v[206:209], v[166:169], v[44:47]
	v_mfma_f32_16x16x32_bf16 v[40:43], v[206:209], v[174:177], v[40:43]
	v_mfma_f32_16x16x32_bf16 v[28:31], v[216:219], v[166:169], v[28:31]
	v_mfma_f32_16x16x32_bf16 v[24:27], v[216:219], v[174:177], v[24:27]
	v_mfma_f32_16x16x32_bf16 v[12:15], v[224:227], v[166:169], v[12:15]
	v_mfma_f32_16x16x32_bf16 v[8:11], v[224:227], v[174:177], v[8:11]
	v_mfma_f32_16x16x32_bf16 v[60:63], v[202:205], v[170:173], v[60:63]
	v_mfma_f32_16x16x32_bf16 v[56:59], v[202:205], v[178:181], v[56:59]
	v_mfma_f32_16x16x32_bf16 v[44:47], v[212:215], v[170:173], v[44:47]
	v_mfma_f32_16x16x32_bf16 v[40:43], v[212:215], v[178:181], v[40:43]
	v_mfma_f32_16x16x32_bf16 v[28:31], v[220:223], v[170:173], v[28:31]
	v_mfma_f32_16x16x32_bf16 v[24:27], v[220:223], v[178:181], v[24:27]
	v_mfma_f32_16x16x32_bf16 v[12:15], v[228:231], v[170:173], v[12:15]
	v_mfma_f32_16x16x32_bf16 v[8:11], v[228:231], v[178:181], v[8:11]
	s_setprio 0
	s_setprio 1
	v_mfma_f32_16x16x32_bf16 v[52:55], v[198:201], v[182:185], v[52:55]
	v_mfma_f32_16x16x32_bf16 v[48:51], v[198:201], v[190:193], v[48:51]
	v_mfma_f32_16x16x32_bf16 v[36:39], v[206:209], v[182:185], v[36:39]
	v_mfma_f32_16x16x32_bf16 v[32:35], v[206:209], v[190:193], v[32:35]
	v_mfma_f32_16x16x32_bf16 v[20:23], v[216:219], v[182:185], v[20:23]
	v_mfma_f32_16x16x32_bf16 v[16:19], v[216:219], v[190:193], v[16:19]
	v_mfma_f32_16x16x32_bf16 v[4:7], v[224:227], v[182:185], v[4:7]
	v_mfma_f32_16x16x32_bf16 v[0:3], v[224:227], v[190:193], v[0:3]
	v_mfma_f32_16x16x32_bf16 v[52:55], v[202:205], v[186:189], v[52:55]
	v_mfma_f32_16x16x32_bf16 v[48:51], v[202:205], v[194:197], v[48:51]
	v_mfma_f32_16x16x32_bf16 v[36:39], v[212:215], v[186:189], v[36:39]
	v_mfma_f32_16x16x32_bf16 v[32:35], v[212:215], v[194:197], v[32:35]
	v_mfma_f32_16x16x32_bf16 v[20:23], v[220:223], v[186:189], v[20:23]
	v_mfma_f32_16x16x32_bf16 v[16:19], v[220:223], v[194:197], v[16:19]
	v_mfma_f32_16x16x32_bf16 v[4:7], v[228:231], v[186:189], v[4:7]
	v_mfma_f32_16x16x32_bf16 v[0:3], v[228:231], v[194:197], v[0:3]
	s_setprio 0
	s_barrier
	ds_read_b128 v[166:169], v164
	ds_read_b128 v[170:173], v164 offset:1024
	ds_read_b128 v[174:177], v164 offset:2048
	ds_read_b128 v[178:181], v164 offset:3072
	ds_read_b128 v[182:185], v165
	ds_read_b128 v[186:189], v165 offset:1024
	ds_read_b128 v[190:193], v165 offset:2048
	ds_read_b128 v[194:197], v165 offset:3072
	s_add_u32 s46, s46, 0x40000
	s_addc_u32 s47, s47, 0
	v_readfirstlane_b32 s61, v146
	v_lshl_add_u64 v[240:241], s[46:47], 0, v[128:129]
	s_mov_b32 m0, s61
	ds_read_b128 v[198:201], v158 offset:32768
	ds_read_b128 v[202:205], v158 offset:33792
	ds_read_b128 v[206:209], v159 offset:32768
	ds_read_b128 v[212:215], v159 offset:33792
	ds_read_b128 v[216:219], v160 offset:32768
	ds_read_b128 v[220:223], v160 offset:33792
	ds_read_b128 v[224:227], v161 offset:32768
	ds_read_b128 v[228:231], v161 offset:33792
	global_load_lds_dwordx4 v[240:241], off
	v_lshl_add_u64 v[240:241], s[46:47], 0, v[130:131]
	v_readfirstlane_b32 s46, v147
	s_mov_b32 m0, s46
	s_nop 0
	global_load_lds_dwordx4 v[240:241], off
	s_waitcnt vmcnt(8)
	s_waitcnt lgkmcnt(0)
	s_barrier
	s_setprio 1
	s_waitcnt lgkmcnt(0)
	v_mfma_f32_16x16x32_bf16 v[124:127], v[198:201], v[166:169], v[124:127]
	v_mfma_f32_16x16x32_bf16 v[120:123], v[198:201], v[174:177], v[120:123]
	v_mfma_f32_16x16x32_bf16 v[108:111], v[206:209], v[166:169], v[108:111]
	v_mfma_f32_16x16x32_bf16 v[104:107], v[206:209], v[174:177], v[104:107]
	v_mfma_f32_16x16x32_bf16 v[92:95], v[216:219], v[166:169], v[92:95]
	v_mfma_f32_16x16x32_bf16 v[88:91], v[216:219], v[174:177], v[88:91]
	v_mfma_f32_16x16x32_bf16 v[76:79], v[224:227], v[166:169], v[76:79]
	v_mfma_f32_16x16x32_bf16 v[72:75], v[224:227], v[174:177], v[72:75]
	v_mfma_f32_16x16x32_bf16 v[124:127], v[202:205], v[170:173], v[124:127]
	v_mfma_f32_16x16x32_bf16 v[120:123], v[202:205], v[178:181], v[120:123]
	v_mfma_f32_16x16x32_bf16 v[108:111], v[212:215], v[170:173], v[108:111]
	v_mfma_f32_16x16x32_bf16 v[104:107], v[212:215], v[178:181], v[104:107]
	v_mfma_f32_16x16x32_bf16 v[92:95], v[220:223], v[170:173], v[92:95]
	v_mfma_f32_16x16x32_bf16 v[88:91], v[220:223], v[178:181], v[88:91]
	v_mfma_f32_16x16x32_bf16 v[76:79], v[228:231], v[170:173], v[76:79]
	v_mfma_f32_16x16x32_bf16 v[72:75], v[228:231], v[178:181], v[72:75]
	s_setprio 0
	s_setprio 1
	v_mfma_f32_16x16x32_bf16 v[116:119], v[198:201], v[182:185], v[116:119]
	v_mfma_f32_16x16x32_bf16 v[112:115], v[198:201], v[190:193], v[112:115]
	v_mfma_f32_16x16x32_bf16 v[100:103], v[206:209], v[182:185], v[100:103]
	v_mfma_f32_16x16x32_bf16 v[96:99], v[206:209], v[190:193], v[96:99]
	v_mfma_f32_16x16x32_bf16 v[84:87], v[216:219], v[182:185], v[84:87]
	v_mfma_f32_16x16x32_bf16 v[80:83], v[216:219], v[190:193], v[80:83]
	v_mfma_f32_16x16x32_bf16 v[68:71], v[224:227], v[182:185], v[68:71]
	v_mfma_f32_16x16x32_bf16 v[64:67], v[224:227], v[190:193], v[64:67]
	v_mfma_f32_16x16x32_bf16 v[116:119], v[202:205], v[186:189], v[116:119]
	v_mfma_f32_16x16x32_bf16 v[112:115], v[202:205], v[194:197], v[112:115]
	v_mfma_f32_16x16x32_bf16 v[100:103], v[212:215], v[186:189], v[100:103]
	v_mfma_f32_16x16x32_bf16 v[96:99], v[212:215], v[194:197], v[96:99]
	v_mfma_f32_16x16x32_bf16 v[84:87], v[220:223], v[186:189], v[84:87]
	v_mfma_f32_16x16x32_bf16 v[80:83], v[220:223], v[194:197], v[80:83]
	v_mfma_f32_16x16x32_bf16 v[68:71], v[228:231], v[186:189], v[68:71]
	v_mfma_f32_16x16x32_bf16 v[64:67], v[228:231], v[194:197], v[64:67]
	s_setprio 0
	s_barrier
; DI bf16_t f2bf(float x) { return (bf16_t)(cvt_pk(x, 0.f) & 0xffffu); }
; #define STAGE(P, g) do { const char* g_ = (const char*)(g); \
;         __builtin_amdgcn_global_load_lds((const unsigned*)(g_ + so0), (lds_u32*)((lds_u8*)(P) + sb0), 16, 0, 0); \
;         __builtin_amdgcn_global_load_lds((const unsigned*)(g_ + so1), (lds_u32*)((lds_u8*)(P) + sb0 + 8192), 16, 0, 0); } while (0)
; #define LDA(dst, b, h) for (int m = 0; m < 4; ++m) for (int k = 0; k < 2; ++k) \
;         dst[m][k] = *reinterpret_cast<const bf16x8*>((char*)SA(b, h) + lds_byte(wr * 64 + m * 16 + fr, k * 32 + fq * 8))
; #define MMA(ai, bj, At_, Bt_) do { __builtin_amdgcn_s_setprio(1); \
;         for (int m = 0; m < 4; ++m) for (int n = 0; n < 2; ++n) for (int k = 0; k < 2; ++k) \
;             acc[ai][bj][m][n] = __builtin_amdgcn_mfma_f32_16x16x32_bf16(At_[m][k], Bt_[n][k], acc[ai][bj][m][n], 0, 0, 0); \
;         __builtin_amdgcn_s_setprio(0); } while (0)
; #define WAIT_V(n) asm volatile("s_waitcnt vmcnt(" #n ")" ::: "memory")
; #define WAIT_L(n) asm volatile("s_waitcnt lgkmcnt(" #n ")" ::: "memory")
; #define BAR __builtin_amdgcn_s_barrier()
; #define SCHED __builtin_amdgcn_sched_barrier(0)
;     ...
;     } else if (EPI == EPI_FFN1) {
;         bf16_t* d = (bf16_t*)(p.ws + OFF_U) + (size_t)row0 * 4096 + col;
; #pragma unroll
;         for (int e = 0; e < 4; ++e) { const float t = fmaxf(v[e], 0.f); d[(size_t)e * 4096] = f2bf(t * t); }
; template <int EPI, int K, int LNI = -1>
; DI void ph_gemm(const Params& p, const bf16_t* __restrict__ A, const bf16_t* __restrict__ Bt, int N, float* s_aux) {
;     ...
;             LDA(At, 1, 1); STAGE(SB(1, 0), b3); STAGE(SB(1, 1), b3 + hstep); STAGE(SA(1, 0), a3);
;             WAIT_V(8); WAIT_L(0); BAR; MMA(1, 0, At, B0); MMA(1, 1, At, B1); BAR; SCHED;
;         }
;         if (wr == 0) BAR;
	v_readfirstlane_b32 s46, v148
	v_lshl_add_u64 v[232:233], v[232:233], 0, s[10:11]
	s_mov_b32 m0, s46
	v_readfirstlane_b32 s46, v149
	s_add_u32 s44, s44, 0x40080
	ds_read_b128 v[198:201], v158 offset:49152
	ds_read_b128 v[202:205], v158 offset:50176
	ds_read_b128 v[206:209], v159 offset:49152
	ds_read_b128 v[212:215], v159 offset:50176
	ds_read_b128 v[216:219], v160 offset:49152
	ds_read_b128 v[220:223], v160 offset:50176
	ds_read_b128 v[224:227], v161 offset:49152
	ds_read_b128 v[228:231], v161 offset:50176
	global_load_lds_dwordx4 v[232:233], off
	v_lshl_add_u64 v[232:233], v[234:235], 0, s[10:11]
	s_mov_b32 m0, s46
	s_addc_u32 s45, s45, 0
	v_readfirstlane_b32 s46, v152
	global_load_lds_dwordx4 v[232:233], off
	v_lshl_add_u64 v[232:233], s[44:45], 0, v[128:129]
	s_mov_b32 m0, s46
	s_nop 0
	global_load_lds_dwordx4 v[232:233], off
	v_lshl_add_u64 v[232:233], s[44:45], 0, v[130:131]
	v_readfirstlane_b32 s44, v153
	s_mov_b32 m0, s44
	v_readfirstlane_b32 s44, v150
	global_load_lds_dwordx4 v[232:233], off
	v_lshl_add_u64 v[232:233], v[236:237], 0, s[10:11]
	s_mov_b32 m0, s44
	v_readfirstlane_b32 s44, v151
	global_load_lds_dwordx4 v[232:233], off
	v_lshl_add_u64 v[232:233], v[238:239], 0, s[10:11]
	s_mov_b32 m0, s44
	s_nop 0
	global_load_lds_dwordx4 v[232:233], off
	s_waitcnt vmcnt(8)
	s_waitcnt lgkmcnt(0)
	s_barrier
	s_setprio 1
	s_waitcnt lgkmcnt(0)
	v_mfma_f32_16x16x32_bf16 v[60:63], v[198:201], v[166:169], v[60:63]
	v_mfma_f32_16x16x32_bf16 v[56:59], v[198:201], v[174:177], v[56:59]
	v_mfma_f32_16x16x32_bf16 v[44:47], v[206:209], v[166:169], v[44:47]
	v_mfma_f32_16x16x32_bf16 v[40:43], v[206:209], v[174:177], v[40:43]
	v_mfma_f32_16x16x32_bf16 v[28:31], v[216:219], v[166:169], v[28:31]
	v_mfma_f32_16x16x32_bf16 v[24:27], v[216:219], v[174:177], v[24:27]
	v_mfma_f32_16x16x32_bf16 v[12:15], v[224:227], v[166:169], v[12:15]
	v_mfma_f32_16x16x32_bf16 v[8:11], v[224:227], v[174:177], v[8:11]
	v_mfma_f32_16x16x32_bf16 v[60:63], v[202:205], v[170:173], v[60:63]
	v_mfma_f32_16x16x32_bf16 v[56:59], v[202:205], v[178:181], v[56:59]
	v_mfma_f32_16x16x32_bf16 v[44:47], v[212:215], v[170:173], v[44:47]
	v_mfma_f32_16x16x32_bf16 v[40:43], v[212:215], v[178:181], v[40:43]
	v_mfma_f32_16x16x32_bf16 v[28:31], v[220:223], v[170:173], v[28:31]
	v_mfma_f32_16x16x32_bf16 v[24:27], v[220:223], v[178:181], v[24:27]
	v_mfma_f32_16x16x32_bf16 v[12:15], v[228:231], v[170:173], v[12:15]
	v_mfma_f32_16x16x32_bf16 v[8:11], v[228:231], v[178:181], v[8:11]
	s_setprio 0
	s_setprio 1
	v_mfma_f32_16x16x32_bf16 v[52:55], v[198:201], v[182:185], v[52:55]
	v_mfma_f32_16x16x32_bf16 v[48:51], v[198:201], v[190:193], v[48:51]
	v_mfma_f32_16x16x32_bf16 v[36:39], v[206:209], v[182:185], v[36:39]
	v_mfma_f32_16x16x32_bf16 v[32:35], v[206:209], v[190:193], v[32:35]
	v_mfma_f32_16x16x32_bf16 v[20:23], v[216:219], v[182:185], v[20:23]
	v_mfma_f32_16x16x32_bf16 v[16:19], v[216:219], v[190:193], v[16:19]
	v_mfma_f32_16x16x32_bf16 v[4:7], v[224:227], v[182:185], v[4:7]
	v_mfma_f32_16x16x32_bf16 v[0:3], v[224:227], v[190:193], v[0:3]
	v_mfma_f32_16x16x32_bf16 v[52:55], v[202:205], v[186:189], v[52:55]
	v_mfma_f32_16x16x32_bf16 v[48:51], v[202:205], v[194:197], v[48:51]
	v_mfma_f32_16x16x32_bf16 v[36:39], v[212:215], v[186:189], v[36:39]
	v_mfma_f32_16x16x32_bf16 v[32:35], v[212:215], v[194:197], v[32:35]
	v_mfma_f32_16x16x32_bf16 v[20:23], v[220:223], v[186:189], v[20:23]
	v_mfma_f32_16x16x32_bf16 v[16:19], v[220:223], v[194:197], v[16:19]
	v_mfma_f32_16x16x32_bf16 v[4:7], v[228:231], v[186:189], v[4:7]
	v_mfma_f32_16x16x32_bf16 v[0:3], v[228:231], v[194:197], v[0:3]
	s_setprio 0
	s_barrier
	s_add_i32 s60, s60, 2
	s_add_u32 s28, s28, 0x100
	s_addc_u32 s29, s29, 0
	s_cmp_gt_u32 s60, 13
	s_cbranch_scc0 .LBB0_928
	s_and_saveexec_b64 s[28:29], s[4:5]
	s_cbranch_execz .LBB0_931
	s_barrier
.LBB0_931:
	s_or_b64 exec, exec, s[28:29]
	s_lshl_b32 s15, s26, 8
	v_mov_b32_e32 v137, 0
	v_lshl_or_b32 v138, s24, 8, v155
	v_add3_u32 v136, v154, s15, v137
	v_add_u32_e32 v138, v138, v137
	v_ashrrev_i32_e32 v137, 31, v136
	v_max_f32_e32 v124, v124, v124
	v_lshlrev_b64 v[166:167], 13, v[136:137]
	v_ashrrev_i32_e32 v139, 31, v138
	v_max_f32_e32 v124, 0, v124
	v_max_f32_e32 v112, v112, v112
	v_lshl_add_u64 v[166:167], s[36:37], 0, v[166:167]
	v_lshlrev_b64 v[138:139], 1, v[138:139]
	v_mul_f32_e32 v124, v124, v124
	v_max_f32_e32 v112, 0, v112
	v_lshl_add_u64 v[166:167], v[166:167], 0, v[138:139]
	v_cvt_pk_bf16_f32 v124, v124, s0
	v_mul_f32_e32 v112, v112, v112
	global_store_short v[166:167], v124, off
	v_max_f32_e32 v124, v125, v125
	v_cvt_pk_bf16_f32 v112, v112, s0
	v_max_f32_e32 v124, 0, v124
	global_store_short v[166:167], v112, off offset:288
	v_max_f32_e32 v112, v113, v113
	v_mul_f32_e32 v124, v124, v124
	v_max_f32_e32 v112, 0, v112
	v_cvt_pk_bf16_f32 v137, v124, s0
	v_add_co_u32_e32 v124, vcc, s3, v166
	v_mul_f32_e32 v112, v112, v112
	s_nop 0
	v_addc_co_u32_e32 v125, vcc, 0, v167, vcc
	v_max_f32_e32 v126, v126, v126
	v_cvt_pk_bf16_f32 v112, v112, s0
	v_max_f32_e32 v126, 0, v126
	global_store_short v[124:125], v112, off offset:288
	v_max_f32_e32 v112, v114, v114
	v_mul_f32_e32 v126, v126, v126
	v_add_co_u32_e32 v168, vcc, s25, v166
	v_max_f32_e32 v112, 0, v112
	v_cvt_pk_bf16_f32 v126, v126, s0
	v_addc_co_u32_e32 v169, vcc, 0, v167, vcc
	v_mul_f32_e32 v112, v112, v112
	global_store_short v[168:169], v126, off
	v_max_f32_e32 v126, v127, v127
	v_cvt_pk_bf16_f32 v112, v112, s0
	v_max_f32_e32 v126, 0, v126
	global_store_short v[168:169], v112, off offset:288
	v_max_f32_e32 v112, v115, v115
	v_mul_f32_e32 v126, v126, v126
	v_max_f32_e32 v112, 0, v112
	global_store_short v[124:125], v137, off
; DI bf16_t f2bf(float x) { return (bf16_t)(cvt_pk(x, 0.f) & 0xffffu); }
; DI float ex2(float x) { return __builtin_amdgcn_exp2f(x); }
;     ...
;     } else if (EPI == EPI_FFN1) {
;         bf16_t* d = (bf16_t*)(p.ws + OFF_U) + (size_t)row0 * 4096 + col;
; #pragma unroll
;         for (int e = 0; e < 4; ++e) { const float t = fmaxf(v[e], 0.f); d[(size_t)e * 4096] = f2bf(t * t); }
; template <int EPI, int K, int LNI = -1>
; DI void ph_gemm(const Params& p, const bf16_t* __restrict__ A, const bf16_t* __restrict__ Bt, int N, float* s_aux) {
;     ...
;             for (int ai = 0; ai < 2; ++ai)
; #pragma unroll
;                 for (int m = 0; m < 4; ++m) {
;                     const int lrow0 = ai * 128 + wr * 64 + m * 16 + fq * 4, row0 = brow + lrow0 + oz;
;                     f32x2 rs[4];
;                     if (EPI == EPI_RESID && LNI >= 0) {
;                         const f32x2* st_ = (const f32x2*)((unsigned char*)p.out + OFFO_STATS) + row0;
; #pragma unroll
;                         for (int e = 0; e < 4; ++e) rs[e] = st_[e];
;                     }
;                     if (EPI == EPI_E5) {
;                         const int idx_ = ((row0 % LT) + 48) & 63; const float lgh = lg_[0][0];
; #pragma unroll
;                         for (int e = 0; e < 4; ++e) rs[e] = (f32x2){ex2(lgh * (float)(idx_ + e + 1)), 0.0625f * ex2(lgh * (float)(63 - idx_ - e))};
;                     }
; #pragma unroll
;                     for (int bj = 0; bj < 2; ++bj)
; #pragma unroll
;                         for (int n = 0; n < 2; ++n) {
;                             float v[4];
; #pragma unroll
;                             for (int e = 0; e < 4; ++e) v[e] = acc[ai][bj][m][n][e];
;                             epi_store<EPI, LNI>(p, row0, bcol + bj * 128 + wc * 32 + n * 16 + fr + oz, lrow0, v, sa, rs, lg_[bj][n], lb_[bj][n]);
;                         }
	v_cvt_pk_bf16_f32 v137, v126, s0
	v_add_co_u32_e32 v126, vcc, s27, v166
	v_mul_f32_e32 v112, v112, v112
	s_nop 0
	v_addc_co_u32_e32 v127, vcc, 0, v167, vcc
	v_cvt_pk_bf16_f32 v112, v112, s0
	v_max_f32_e32 v116, v116, v116
	global_store_short v[126:127], v112, off offset:288
	v_add_u32_e32 v112, 16, v136
	v_max_f32_e32 v116, 0, v116
	v_ashrrev_i32_e32 v113, 31, v112
	v_max_f32_e32 v108, v108, v108
	v_mul_f32_e32 v116, v116, v116
	v_lshlrev_b64 v[112:113], 13, v[112:113]
	v_max_f32_e32 v108, 0, v108
	v_max_f32_e32 v96, v96, v96
	v_cvt_pk_bf16_f32 v116, v116, s0
	v_lshl_add_u64 v[112:113], s[36:37], 0, v[112:113]
	v_mul_f32_e32 v108, v108, v108
	v_max_f32_e32 v96, 0, v96
	global_store_short v[166:167], v116, off offset:256
	v_max_f32_e32 v116, v117, v117
	v_lshl_add_u64 v[112:113], v[112:113], 0, v[138:139]
	v_cvt_pk_bf16_f32 v108, v108, s0
	v_mul_f32_e32 v96, v96, v96
	v_max_f32_e32 v116, 0, v116
	global_store_short v[112:113], v108, off
	v_max_f32_e32 v108, v109, v109
	v_cvt_pk_bf16_f32 v96, v96, s0
	v_mul_f32_e32 v116, v116, v116
	v_max_f32_e32 v108, 0, v108
	global_store_short v[112:113], v96, off offset:288
	v_max_f32_e32 v96, v97, v97
	v_cvt_pk_bf16_f32 v116, v116, s0
	v_mul_f32_e32 v108, v108, v108
	v_max_f32_e32 v96, 0, v96
	global_store_short v[124:125], v116, off offset:256
	v_max_f32_e32 v116, v118, v118
	v_cvt_pk_bf16_f32 v114, v108, s0
	v_add_co_u32_e32 v108, vcc, s3, v112
	v_mul_f32_e32 v96, v96, v96
	v_max_f32_e32 v116, 0, v116
	v_addc_co_u32_e32 v109, vcc, 0, v113, vcc
	v_max_f32_e32 v110, v110, v110
	v_cvt_pk_bf16_f32 v96, v96, s0
	v_mul_f32_e32 v116, v116, v116
	v_max_f32_e32 v110, 0, v110
	global_store_short v[108:109], v96, off offset:288
	v_max_f32_e32 v96, v98, v98
	v_cvt_pk_bf16_f32 v116, v116, s0
	global_store_short v[108:109], v114, off
	v_mul_f32_e32 v110, v110, v110
	v_add_co_u32_e32 v114, vcc, s25, v112
	v_max_f32_e32 v96, 0, v96
	global_store_short v[168:169], v116, off offset:256
	v_max_f32_e32 v116, v119, v119
	v_cvt_pk_bf16_f32 v110, v110, s0
	v_addc_co_u32_e32 v115, vcc, 0, v113, vcc
	v_mul_f32_e32 v96, v96, v96
	v_max_f32_e32 v116, 0, v116
	global_store_short v[114:115], v110, off
	v_max_f32_e32 v110, v111, v111
	v_cvt_pk_bf16_f32 v96, v96, s0
	v_mul_f32_e32 v116, v116, v116
	v_max_f32_e32 v110, 0, v110
	global_store_short v[114:115], v96, off offset:288
	v_max_f32_e32 v96, v99, v99
	v_cvt_pk_bf16_f32 v116, v116, s0
	v_mul_f32_e32 v110, v110, v110
	v_max_f32_e32 v96, 0, v96
	global_store_short v[126:127], v116, off offset:256
	v_cvt_pk_bf16_f32 v116, v110, s0
	v_add_co_u32_e32 v110, vcc, s27, v112
	v_mul_f32_e32 v96, v96, v96
	s_nop 0
	v_addc_co_u32_e32 v111, vcc, 0, v113, vcc
	v_cvt_pk_bf16_f32 v96, v96, s0
	v_max_f32_e32 v100, v100, v100
	global_store_short v[110:111], v96, off offset:288
	v_add_u32_e32 v96, 32, v136
	v_max_f32_e32 v100, 0, v100
	v_ashrrev_i32_e32 v97, 31, v96
	v_max_f32_e32 v92, v92, v92
	v_mul_f32_e32 v100, v100, v100
	v_lshlrev_b64 v[96:97], 13, v[96:97]
	v_max_f32_e32 v92, 0, v92
	v_max_f32_e32 v80, v80, v80
	v_cvt_pk_bf16_f32 v100, v100, s0
	v_lshl_add_u64 v[96:97], s[36:37], 0, v[96:97]
	v_mul_f32_e32 v92, v92, v92
	v_max_f32_e32 v80, 0, v80
	global_store_short v[112:113], v100, off offset:256
	v_max_f32_e32 v100, v101, v101
	v_lshl_add_u64 v[96:97], v[96:97], 0, v[138:139]
	v_cvt_pk_bf16_f32 v92, v92, s0
	v_mul_f32_e32 v80, v80, v80
	v_max_f32_e32 v100, 0, v100
	global_store_short v[96:97], v92, off
	v_max_f32_e32 v92, v93, v93
	v_cvt_pk_bf16_f32 v80, v80, s0
	v_mul_f32_e32 v100, v100, v100
	v_max_f32_e32 v92, 0, v92
	global_store_short v[96:97], v80, off offset:288
	v_max_f32_e32 v80, v81, v81
	v_cvt_pk_bf16_f32 v100, v100, s0
	v_mul_f32_e32 v92, v92, v92
	v_max_f32_e32 v80, 0, v80
	global_store_short v[108:109], v100, off offset:256
	v_max_f32_e32 v100, v102, v102
	v_cvt_pk_bf16_f32 v98, v92, s0
	v_add_co_u32_e32 v92, vcc, s3, v96
	v_mul_f32_e32 v80, v80, v80
	v_max_f32_e32 v100, 0, v100
	v_addc_co_u32_e32 v93, vcc, 0, v97, vcc
	v_max_f32_e32 v94, v94, v94
	v_cvt_pk_bf16_f32 v80, v80, s0
	v_mul_f32_e32 v100, v100, v100
	v_max_f32_e32 v94, 0, v94
	global_store_short v[92:93], v80, off offset:288
	v_max_f32_e32 v80, v82, v82
	v_cvt_pk_bf16_f32 v100, v100, s0
	global_store_short v[92:93], v98, off
	v_mul_f32_e32 v94, v94, v94
	v_add_co_u32_e32 v98, vcc, s25, v96
	v_max_f32_e32 v80, 0, v80
	global_store_short v[114:115], v100, off offset:256
	v_max_f32_e32 v100, v103, v103
	v_cvt_pk_bf16_f32 v94, v94, s0
	v_addc_co_u32_e32 v99, vcc, 0, v97, vcc
	v_mul_f32_e32 v80, v80, v80
	v_max_f32_e32 v100, 0, v100
	global_store_short v[98:99], v94, off
	v_max_f32_e32 v94, v95, v95
	v_cvt_pk_bf16_f32 v80, v80, s0
	v_mul_f32_e32 v100, v100, v100
	v_max_f32_e32 v94, 0, v94
	global_store_short v[98:99], v80, off offset:288
	v_max_f32_e32 v80, v83, v83
	v_cvt_pk_bf16_f32 v100, v100, s0
	v_mul_f32_e32 v94, v94, v94
	v_max_f32_e32 v80, 0, v80
	global_store_short v[110:111], v100, off offset:256
	v_cvt_pk_bf16_f32 v100, v94, s0
	v_add_co_u32_e32 v94, vcc, s27, v96
	v_mul_f32_e32 v80, v80, v80
	s_nop 0
	v_addc_co_u32_e32 v95, vcc, 0, v97, vcc
	v_cvt_pk_bf16_f32 v80, v80, s0
	v_max_f32_e32 v84, v84, v84
	global_store_short v[94:95], v80, off offset:288
	v_add_u32_e32 v80, 48, v136
	v_max_f32_e32 v84, 0, v84
	v_ashrrev_i32_e32 v81, 31, v80
	v_max_f32_e32 v76, v76, v76
	v_mul_f32_e32 v84, v84, v84
	v_lshlrev_b64 v[80:81], 13, v[80:81]
	v_max_f32_e32 v76, 0, v76
	v_max_f32_e32 v64, v64, v64
	v_cvt_pk_bf16_f32 v84, v84, s0
	v_lshl_add_u64 v[80:81], s[36:37], 0, v[80:81]
	v_mul_f32_e32 v76, v76, v76
	v_max_f32_e32 v64, 0, v64
	global_store_short v[96:97], v84, off offset:256
	v_max_f32_e32 v84, v85, v85
; DI bf16_t f2bf(float x) { return (bf16_t)(cvt_pk(x, 0.f) & 0xffffu); }
; DI float ex2(float x) { return __builtin_amdgcn_exp2f(x); }
;     ...
;     } else if (EPI == EPI_FFN1) {
;         bf16_t* d = (bf16_t*)(p.ws + OFF_U) + (size_t)row0 * 4096 + col;
; #pragma unroll
;         for (int e = 0; e < 4; ++e) { const float t = fmaxf(v[e], 0.f); d[(size_t)e * 4096] = f2bf(t * t); }
; template <int EPI, int K, int LNI = -1>
; DI void ph_gemm(const Params& p, const bf16_t* __restrict__ A, const bf16_t* __restrict__ Bt, int N, float* s_aux) {
;     ...
;             for (int ai = 0; ai < 2; ++ai)
; #pragma unroll
;                 for (int m = 0; m < 4; ++m) {
;                     const int lrow0 = ai * 128 + wr * 64 + m * 16 + fq * 4, row0 = brow + lrow0 + oz;
;                     f32x2 rs[4];
;                     if (EPI == EPI_RESID && LNI >= 0) {
;                         const f32x2* st_ = (const f32x2*)((unsigned char*)p.out + OFFO_STATS) + row0;
; #pragma unroll
;                         for (int e = 0; e < 4; ++e) rs[e] = st_[e];
;                     }
;                     if (EPI == EPI_E5) {
;                         const int idx_ = ((row0 % LT) + 48) & 63; const float lgh = lg_[0][0];
; #pragma unroll
;                         for (int e = 0; e < 4; ++e) rs[e] = (f32x2){ex2(lgh * (float)(idx_ + e + 1)), 0.0625f * ex2(lgh * (float)(63 - idx_ - e))};
;                     }
; #pragma unroll
;                     for (int bj = 0; bj < 2; ++bj)
; #pragma unroll
;                         for (int n = 0; n < 2; ++n) {
;                             float v[4];
; #pragma unroll
;                             for (int e = 0; e < 4; ++e) v[e] = acc[ai][bj][m][n][e];
;                             epi_store<EPI, LNI>(p, row0, bcol + bj * 128 + wc * 32 + n * 16 + fr + oz, lrow0, v, sa, rs, lg_[bj][n], lb_[bj][n]);
;                         }
	v_lshl_add_u64 v[80:81], v[80:81], 0, v[138:139]
	v_cvt_pk_bf16_f32 v76, v76, s0
	v_mul_f32_e32 v64, v64, v64
	v_max_f32_e32 v84, 0, v84
	global_store_short v[80:81], v76, off
	v_max_f32_e32 v76, v77, v77
	v_cvt_pk_bf16_f32 v64, v64, s0
	v_mul_f32_e32 v84, v84, v84
	v_max_f32_e32 v76, 0, v76
	global_store_short v[80:81], v64, off offset:288
	v_max_f32_e32 v64, v65, v65
	v_cvt_pk_bf16_f32 v84, v84, s0
	v_mul_f32_e32 v76, v76, v76
	v_max_f32_e32 v64, 0, v64
	global_store_short v[92:93], v84, off offset:256
	v_max_f32_e32 v84, v86, v86
	v_cvt_pk_bf16_f32 v82, v76, s0
	v_add_co_u32_e32 v76, vcc, s3, v80
	v_mul_f32_e32 v64, v64, v64
	v_max_f32_e32 v84, 0, v84
	v_addc_co_u32_e32 v77, vcc, 0, v81, vcc
	v_max_f32_e32 v78, v78, v78
	v_cvt_pk_bf16_f32 v64, v64, s0
	v_mul_f32_e32 v84, v84, v84
	v_max_f32_e32 v78, 0, v78
	global_store_short v[76:77], v64, off offset:288
	v_max_f32_e32 v64, v66, v66
	v_cvt_pk_bf16_f32 v84, v84, s0
	global_store_short v[76:77], v82, off
	v_mul_f32_e32 v78, v78, v78
	v_add_co_u32_e32 v82, vcc, s25, v80
	v_max_f32_e32 v64, 0, v64
	global_store_short v[98:99], v84, off offset:256
	v_max_f32_e32 v84, v87, v87
	v_cvt_pk_bf16_f32 v78, v78, s0
	v_addc_co_u32_e32 v83, vcc, 0, v81, vcc
	v_mul_f32_e32 v64, v64, v64
	v_max_f32_e32 v84, 0, v84
	global_store_short v[82:83], v78, off
	v_max_f32_e32 v78, v79, v79
	v_cvt_pk_bf16_f32 v64, v64, s0
	v_mul_f32_e32 v84, v84, v84
	v_max_f32_e32 v78, 0, v78
	global_store_short v[82:83], v64, off offset:288
	v_max_f32_e32 v64, v67, v67
	v_cvt_pk_bf16_f32 v84, v84, s0
	v_mul_f32_e32 v78, v78, v78
	v_max_f32_e32 v64, 0, v64
	global_store_short v[94:95], v84, off offset:256
	v_cvt_pk_bf16_f32 v84, v78, s0
	v_add_co_u32_e32 v78, vcc, s27, v80
	v_mul_f32_e32 v64, v64, v64
	s_nop 0
	v_addc_co_u32_e32 v79, vcc, 0, v81, vcc
	v_cvt_pk_bf16_f32 v64, v64, s0
	v_max_f32_e32 v68, v68, v68
	global_store_short v[78:79], v64, off offset:288
	v_add_u32_e32 v64, 0x80, v136
	v_max_f32_e32 v68, 0, v68
	v_ashrrev_i32_e32 v65, 31, v64
	v_max_f32_e32 v60, v60, v60
	v_mul_f32_e32 v68, v68, v68
	v_lshlrev_b64 v[64:65], 13, v[64:65]
	v_max_f32_e32 v60, 0, v60
	v_max_f32_e32 v48, v48, v48
	v_cvt_pk_bf16_f32 v68, v68, s0
	v_lshl_add_u64 v[64:65], s[36:37], 0, v[64:65]
	v_mul_f32_e32 v60, v60, v60
	v_max_f32_e32 v48, 0, v48
	global_store_short v[80:81], v68, off offset:256
	v_max_f32_e32 v68, v69, v69
	v_lshl_add_u64 v[64:65], v[64:65], 0, v[138:139]
	v_cvt_pk_bf16_f32 v60, v60, s0
	v_mul_f32_e32 v48, v48, v48
	v_max_f32_e32 v68, 0, v68
	global_store_short v[64:65], v60, off
	v_max_f32_e32 v60, v61, v61
	v_cvt_pk_bf16_f32 v48, v48, s0
	v_mul_f32_e32 v68, v68, v68
	v_max_f32_e32 v60, 0, v60
	global_store_short v[64:65], v48, off offset:288
	v_max_f32_e32 v48, v49, v49
	v_cvt_pk_bf16_f32 v68, v68, s0
	v_mul_f32_e32 v60, v60, v60
	v_max_f32_e32 v48, 0, v48
	global_store_short v[76:77], v68, off offset:256
	v_max_f32_e32 v68, v70, v70
	v_cvt_pk_bf16_f32 v66, v60, s0
	v_add_co_u32_e32 v60, vcc, s3, v64
	v_mul_f32_e32 v48, v48, v48
	v_max_f32_e32 v68, 0, v68
	v_addc_co_u32_e32 v61, vcc, 0, v65, vcc
	v_max_f32_e32 v62, v62, v62
	v_cvt_pk_bf16_f32 v48, v48, s0
	v_mul_f32_e32 v68, v68, v68
	v_max_f32_e32 v62, 0, v62
	global_store_short v[60:61], v48, off offset:288
	v_max_f32_e32 v48, v50, v50
	v_cvt_pk_bf16_f32 v68, v68, s0
	global_store_short v[60:61], v66, off
	v_mul_f32_e32 v62, v62, v62
	v_add_co_u32_e32 v66, vcc, s25, v64
	v_max_f32_e32 v48, 0, v48
	global_store_short v[82:83], v68, off offset:256
	v_max_f32_e32 v68, v71, v71
	v_cvt_pk_bf16_f32 v62, v62, s0
	v_addc_co_u32_e32 v67, vcc, 0, v65, vcc
	v_mul_f32_e32 v48, v48, v48
	v_max_f32_e32 v68, 0, v68
	global_store_short v[66:67], v62, off
	v_max_f32_e32 v62, v63, v63
	v_cvt_pk_bf16_f32 v48, v48, s0
	v_mul_f32_e32 v68, v68, v68
	v_max_f32_e32 v62, 0, v62
	global_store_short v[66:67], v48, off offset:288
	v_max_f32_e32 v48, v51, v51
	v_cvt_pk_bf16_f32 v68, v68, s0
	v_mul_f32_e32 v62, v62, v62
	v_max_f32_e32 v48, 0, v48
	global_store_short v[78:79], v68, off offset:256
	v_cvt_pk_bf16_f32 v68, v62, s0
	v_add_co_u32_e32 v62, vcc, s27, v64
	v_mul_f32_e32 v48, v48, v48
	s_nop 0
	v_addc_co_u32_e32 v63, vcc, 0, v65, vcc
	v_cvt_pk_bf16_f32 v48, v48, s0
	v_max_f32_e32 v52, v52, v52
	global_store_short v[62:63], v48, off offset:288
	v_add_u32_e32 v48, 0x90, v136
	v_max_f32_e32 v52, 0, v52
	v_ashrrev_i32_e32 v49, 31, v48
	v_max_f32_e32 v44, v44, v44
	v_mul_f32_e32 v52, v52, v52
	v_lshlrev_b64 v[48:49], 13, v[48:49]
	v_max_f32_e32 v44, 0, v44
	v_max_f32_e32 v32, v32, v32
	v_cvt_pk_bf16_f32 v52, v52, s0
	v_lshl_add_u64 v[48:49], s[36:37], 0, v[48:49]
	v_mul_f32_e32 v44, v44, v44
	v_max_f32_e32 v32, 0, v32
	global_store_short v[64:65], v52, off offset:256
	v_max_f32_e32 v52, v53, v53
	v_lshl_add_u64 v[48:49], v[48:49], 0, v[138:139]
	v_cvt_pk_bf16_f32 v44, v44, s0
	v_mul_f32_e32 v32, v32, v32
	v_max_f32_e32 v52, 0, v52
	global_store_short v[48:49], v44, off
	v_max_f32_e32 v44, v45, v45
	v_cvt_pk_bf16_f32 v32, v32, s0
	v_mul_f32_e32 v52, v52, v52
	v_max_f32_e32 v44, 0, v44
	global_store_short v[48:49], v32, off offset:288
	v_max_f32_e32 v32, v33, v33
	v_cvt_pk_bf16_f32 v52, v52, s0
	v_mul_f32_e32 v44, v44, v44
	v_max_f32_e32 v32, 0, v32
	global_store_short v[60:61], v52, off offset:256
	v_max_f32_e32 v52, v54, v54
	v_cvt_pk_bf16_f32 v50, v44, s0
	v_add_co_u32_e32 v44, vcc, s3, v48
	v_mul_f32_e32 v32, v32, v32
	v_max_f32_e32 v52, 0, v52
	v_addc_co_u32_e32 v45, vcc, 0, v49, vcc
	v_max_f32_e32 v46, v46, v46
	v_cvt_pk_bf16_f32 v32, v32, s0
	v_mul_f32_e32 v52, v52, v52
	v_max_f32_e32 v46, 0, v46
	global_store_short v[44:45], v32, off offset:288
	v_max_f32_e32 v32, v34, v34
; DI bf16_t f2bf(float x) { return (bf16_t)(cvt_pk(x, 0.f) & 0xffffu); }
; DI float ex2(float x) { return __builtin_amdgcn_exp2f(x); }
;     ...
;     } else if (EPI == EPI_FFN1) {
;         bf16_t* d = (bf16_t*)(p.ws + OFF_U) + (size_t)row0 * 4096 + col;
; #pragma unroll
;         for (int e = 0; e < 4; ++e) { const float t = fmaxf(v[e], 0.f); d[(size_t)e * 4096] = f2bf(t * t); }
; template <int EPI, int K, int LNI = -1>
; DI void ph_gemm(const Params& p, const bf16_t* __restrict__ A, const bf16_t* __restrict__ Bt, int N, float* s_aux) {
;     ...
;             for (int ai = 0; ai < 2; ++ai)
; #pragma unroll
;                 for (int m = 0; m < 4; ++m) {
;                     const int lrow0 = ai * 128 + wr * 64 + m * 16 + fq * 4, row0 = brow + lrow0 + oz;
;                     f32x2 rs[4];
;                     if (EPI == EPI_RESID && LNI >= 0) {
;                         const f32x2* st_ = (const f32x2*)((unsigned char*)p.out + OFFO_STATS) + row0;
; #pragma unroll
;                         for (int e = 0; e < 4; ++e) rs[e] = st_[e];
;                     }
;                     if (EPI == EPI_E5) {
;                         const int idx_ = ((row0 % LT) + 48) & 63; const float lgh = lg_[0][0];
; #pragma unroll
;                         for (int e = 0; e < 4; ++e) rs[e] = (f32x2){ex2(lgh * (float)(idx_ + e + 1)), 0.0625f * ex2(lgh * (float)(63 - idx_ - e))};
;                     }
; #pragma unroll
;                     for (int bj = 0; bj < 2; ++bj)
; #pragma unroll
;                         for (int n = 0; n < 2; ++n) {
;                             float v[4];
; #pragma unroll
;                             for (int e = 0; e < 4; ++e) v[e] = acc[ai][bj][m][n][e];
;                             epi_store<EPI, LNI>(p, row0, bcol + bj * 128 + wc * 32 + n * 16 + fr + oz, lrow0, v, sa, rs, lg_[bj][n], lb_[bj][n]);
;                         }
	v_cvt_pk_bf16_f32 v52, v52, s0
	global_store_short v[44:45], v50, off
	v_mul_f32_e32 v46, v46, v46
	v_add_co_u32_e32 v50, vcc, s25, v48
	v_max_f32_e32 v32, 0, v32
	global_store_short v[66:67], v52, off offset:256
	v_max_f32_e32 v52, v55, v55
	v_cvt_pk_bf16_f32 v46, v46, s0
	v_addc_co_u32_e32 v51, vcc, 0, v49, vcc
	v_mul_f32_e32 v32, v32, v32
	v_max_f32_e32 v52, 0, v52
	global_store_short v[50:51], v46, off
	v_max_f32_e32 v46, v47, v47
	v_cvt_pk_bf16_f32 v32, v32, s0
	v_mul_f32_e32 v52, v52, v52
	v_max_f32_e32 v46, 0, v46
	global_store_short v[50:51], v32, off offset:288
	v_max_f32_e32 v32, v35, v35
	v_cvt_pk_bf16_f32 v52, v52, s0
	v_mul_f32_e32 v46, v46, v46
	v_max_f32_e32 v32, 0, v32
	global_store_short v[62:63], v52, off offset:256
	v_cvt_pk_bf16_f32 v52, v46, s0
	v_add_co_u32_e32 v46, vcc, s27, v48
	v_mul_f32_e32 v32, v32, v32
	s_nop 0
	v_addc_co_u32_e32 v47, vcc, 0, v49, vcc
	v_cvt_pk_bf16_f32 v32, v32, s0
	v_max_f32_e32 v36, v36, v36
	global_store_short v[46:47], v32, off offset:288
	v_add_u32_e32 v32, 0xa0, v136
	v_max_f32_e32 v36, 0, v36
	v_ashrrev_i32_e32 v33, 31, v32
	v_max_f32_e32 v28, v28, v28
	v_mul_f32_e32 v36, v36, v36
	v_lshlrev_b64 v[32:33], 13, v[32:33]
	v_max_f32_e32 v28, 0, v28
	v_max_f32_e32 v16, v16, v16
	v_cvt_pk_bf16_f32 v36, v36, s0
	v_lshl_add_u64 v[32:33], s[36:37], 0, v[32:33]
	v_mul_f32_e32 v28, v28, v28
	v_max_f32_e32 v16, 0, v16
	global_store_short v[48:49], v36, off offset:256
	v_max_f32_e32 v36, v37, v37
	v_lshl_add_u64 v[32:33], v[32:33], 0, v[138:139]
	v_cvt_pk_bf16_f32 v28, v28, s0
	v_mul_f32_e32 v16, v16, v16
	v_max_f32_e32 v36, 0, v36
	global_store_short v[32:33], v28, off
	v_max_f32_e32 v28, v29, v29
	v_cvt_pk_bf16_f32 v16, v16, s0
	v_mul_f32_e32 v36, v36, v36
	v_max_f32_e32 v28, 0, v28
	global_store_short v[32:33], v16, off offset:288
	v_max_f32_e32 v16, v17, v17
	v_cvt_pk_bf16_f32 v36, v36, s0
	v_mul_f32_e32 v28, v28, v28
	v_max_f32_e32 v16, 0, v16
	global_store_short v[44:45], v36, off offset:256
	v_max_f32_e32 v36, v38, v38
	v_cvt_pk_bf16_f32 v34, v28, s0
	v_add_co_u32_e32 v28, vcc, s3, v32
	v_mul_f32_e32 v16, v16, v16
	v_max_f32_e32 v36, 0, v36
	v_addc_co_u32_e32 v29, vcc, 0, v33, vcc
	v_max_f32_e32 v30, v30, v30
	v_cvt_pk_bf16_f32 v16, v16, s0
	v_mul_f32_e32 v36, v36, v36
	v_max_f32_e32 v30, 0, v30
	global_store_short v[28:29], v16, off offset:288
	v_max_f32_e32 v16, v18, v18
	v_cvt_pk_bf16_f32 v36, v36, s0
	global_store_short v[28:29], v34, off
	v_mul_f32_e32 v30, v30, v30
	v_add_co_u32_e32 v34, vcc, s25, v32
	v_max_f32_e32 v16, 0, v16
	global_store_short v[50:51], v36, off offset:256
	v_max_f32_e32 v36, v39, v39
	v_cvt_pk_bf16_f32 v30, v30, s0
	v_addc_co_u32_e32 v35, vcc, 0, v33, vcc
	v_mul_f32_e32 v16, v16, v16
	v_max_f32_e32 v36, 0, v36
	global_store_short v[34:35], v30, off
	v_max_f32_e32 v30, v31, v31
	v_cvt_pk_bf16_f32 v16, v16, s0
	v_mul_f32_e32 v36, v36, v36
	v_max_f32_e32 v30, 0, v30
	global_store_short v[34:35], v16, off offset:288
	v_max_f32_e32 v16, v19, v19
	v_cvt_pk_bf16_f32 v36, v36, s0
	v_mul_f32_e32 v30, v30, v30
	v_max_f32_e32 v16, 0, v16
	global_store_short v[46:47], v36, off offset:256
	v_cvt_pk_bf16_f32 v36, v30, s0
	v_add_co_u32_e32 v30, vcc, s27, v32
	v_mul_f32_e32 v16, v16, v16
	s_nop 0
	v_addc_co_u32_e32 v31, vcc, 0, v33, vcc
	v_max_f32_e32 v20, v20, v20
	v_cvt_pk_bf16_f32 v16, v16, s0
	v_max_f32_e32 v20, 0, v20
	global_store_short v[30:31], v16, off offset:288
	v_add_u32_e32 v16, 0xb0, v136
	v_mul_f32_e32 v20, v20, v20
	v_ashrrev_i32_e32 v17, 31, v16
	v_max_f32_e32 v12, v12, v12
	v_max_f32_e32 v120, v120, v120
	v_max_f32_e32 v104, v104, v104
	v_max_f32_e32 v88, v88, v88
	v_max_f32_e32 v72, v72, v72
	v_max_f32_e32 v56, v56, v56
	v_max_f32_e32 v40, v40, v40
	v_max_f32_e32 v24, v24, v24
	v_cvt_pk_bf16_f32 v20, v20, s0
	v_lshlrev_b64 v[16:17], 13, v[16:17]
	v_max_f32_e32 v12, 0, v12
	v_max_f32_e32 v8, v8, v8
	v_max_f32_e32 v4, v4, v4
	v_max_f32_e32 v0, v0, v0
	v_max_f32_e32 v120, 0, v120
	v_max_f32_e32 v104, 0, v104
	v_max_f32_e32 v88, 0, v88
	v_max_f32_e32 v72, 0, v72
	v_max_f32_e32 v56, 0, v56
	v_max_f32_e32 v40, 0, v40
	v_max_f32_e32 v24, 0, v24
	global_store_short v[32:33], v20, off offset:256
	v_max_f32_e32 v20, v21, v21
	v_lshl_add_u64 v[16:17], s[36:37], 0, v[16:17]
	v_mul_f32_e32 v12, v12, v12
	v_max_f32_e32 v8, 0, v8
	v_max_f32_e32 v4, 0, v4
	v_max_f32_e32 v0, 0, v0
	v_mul_f32_e32 v120, v120, v120
	v_mul_f32_e32 v104, v104, v104
	v_mul_f32_e32 v88, v88, v88
	v_mul_f32_e32 v72, v72, v72
	v_mul_f32_e32 v56, v56, v56
	v_mul_f32_e32 v40, v40, v40
	v_mul_f32_e32 v24, v24, v24
	v_max_f32_e32 v20, 0, v20
	v_lshl_add_u64 v[16:17], v[16:17], 0, v[138:139]
	v_cvt_pk_bf16_f32 v12, v12, s0
	v_mul_f32_e32 v8, v8, v8
	v_mul_f32_e32 v4, v4, v4
	v_mul_f32_e32 v0, v0, v0
	v_cvt_pk_bf16_f32 v120, v120, s0
	v_cvt_pk_bf16_f32 v104, v104, s0
	v_cvt_pk_bf16_f32 v88, v88, s0
	v_cvt_pk_bf16_f32 v72, v72, s0
	v_cvt_pk_bf16_f32 v56, v56, s0
	v_cvt_pk_bf16_f32 v40, v40, s0
	v_cvt_pk_bf16_f32 v24, v24, s0
	v_mul_f32_e32 v20, v20, v20
	global_store_short v[16:17], v12, off
	v_max_f32_e32 v12, v13, v13
	v_cvt_pk_bf16_f32 v8, v8, s0
	v_cvt_pk_bf16_f32 v4, v4, s0
	v_cvt_pk_bf16_f32 v0, v0, s0
	global_store_short v[166:167], v120, off offset:32
	v_max_f32_e32 v120, v121, v121
	global_store_short v[112:113], v104, off offset:32
	v_max_f32_e32 v104, v105, v105
	global_store_short v[96:97], v88, off offset:32
	v_max_f32_e32 v88, v89, v89
	global_store_short v[80:81], v72, off offset:32
	v_max_f32_e32 v72, v73, v73
	global_store_short v[64:65], v56, off offset:32
	v_max_f32_e32 v56, v57, v57
	global_store_short v[48:49], v40, off offset:32
	v_max_f32_e32 v40, v41, v41
	global_store_short v[32:33], v24, off offset:32
; DI bf16_t f2bf(float x) { return (bf16_t)(cvt_pk(x, 0.f) & 0xffffu); }
; #define BAR __builtin_amdgcn_s_barrier()
;     ...
;     } else if (EPI == EPI_FFN1) {
;         bf16_t* d = (bf16_t*)(p.ws + OFF_U) + (size_t)row0 * 4096 + col;
; #pragma unroll
;         for (int e = 0; e < 4; ++e) { const float t = fmaxf(v[e], 0.f); d[(size_t)e * 4096] = f2bf(t * t); }
; template <int EPI, int K, int LNI = -1>
; DI void ph_gemm(const Params& p, const bf16_t* __restrict__ A, const bf16_t* __restrict__ Bt, int N, float* s_aux) {
;     ...
; #pragma unroll
;                     for (int bj = 0; bj < 2; ++bj)
; #pragma unroll
;                         for (int n = 0; n < 2; ++n) {
;                             float v[4];
; #pragma unroll
;                             for (int e = 0; e < 4; ++e) v[e] = acc[ai][bj][m][n][e];
;                             epi_store<EPI, LNI>(p, row0, bcol + bj * 128 + wc * 32 + n * 16 + fr + oz, lrow0, v, sa, rs, lg_[bj][n], lb_[bj][n]);
;                         }
;                 }
;         }
;         if (!has_next) break;
; #pragma unroll
;         for (int a = 0; a < 2; ++a)
; #pragma unroll
;             for (int b = 0; b < 2; ++b)
; #pragma unroll
;                 for (int m = 0; m < 4; ++m)
; #pragma unroll
;                     for (int n = 0; n < 2; ++n) acc[a][b][m][n] = (f32x4){0.f, 0.f, 0.f, 0.f};
;         pm = npm; pn = npn; cA = nA; cB = nB; it = itn; ++cnt;
;         if (wr == 1) BAR;
	v_max_f32_e32 v24, v25, v25
	v_cvt_pk_bf16_f32 v20, v20, s0
	v_max_f32_e32 v12, 0, v12
	global_store_short v[16:17], v8, off offset:32
	v_max_f32_e32 v8, v9, v9
	global_store_short v[16:17], v4, off offset:256
	v_max_f32_e32 v4, v5, v5
	global_store_short v[16:17], v0, off offset:288
	v_max_f32_e32 v0, v1, v1
	v_max_f32_e32 v120, 0, v120
	v_max_f32_e32 v104, 0, v104
	v_max_f32_e32 v88, 0, v88
	v_max_f32_e32 v72, 0, v72
	v_max_f32_e32 v56, 0, v56
	v_max_f32_e32 v40, 0, v40
	v_max_f32_e32 v24, 0, v24
	global_store_short v[28:29], v20, off offset:256
	v_max_f32_e32 v20, v22, v22
	v_mul_f32_e32 v12, v12, v12
	v_max_f32_e32 v8, 0, v8
	v_max_f32_e32 v4, 0, v4
	v_max_f32_e32 v0, 0, v0
	v_mul_f32_e32 v120, v120, v120
	v_mul_f32_e32 v104, v104, v104
	v_mul_f32_e32 v88, v88, v88
	v_mul_f32_e32 v72, v72, v72
	v_mul_f32_e32 v56, v56, v56
	v_mul_f32_e32 v40, v40, v40
	v_mul_f32_e32 v24, v24, v24
	v_max_f32_e32 v20, 0, v20
	v_cvt_pk_bf16_f32 v18, v12, s0
	v_add_co_u32_e32 v12, vcc, s3, v16
	v_max_f32_e32 v14, v14, v14
	v_mul_f32_e32 v8, v8, v8
	v_mul_f32_e32 v4, v4, v4
	v_mul_f32_e32 v0, v0, v0
	v_cvt_pk_bf16_f32 v120, v120, s0
	v_cvt_pk_bf16_f32 v104, v104, s0
	v_cvt_pk_bf16_f32 v88, v88, s0
	v_cvt_pk_bf16_f32 v72, v72, s0
	v_cvt_pk_bf16_f32 v56, v56, s0
	v_cvt_pk_bf16_f32 v40, v40, s0
	v_cvt_pk_bf16_f32 v24, v24, s0
	v_mul_f32_e32 v20, v20, v20
	v_addc_co_u32_e32 v13, vcc, 0, v17, vcc
	v_max_f32_e32 v14, 0, v14
	v_cvt_pk_bf16_f32 v8, v8, s0
	v_cvt_pk_bf16_f32 v4, v4, s0
	v_cvt_pk_bf16_f32 v0, v0, s0
	global_store_short v[124:125], v120, off offset:32
	v_max_f32_e32 v120, v122, v122
	global_store_short v[108:109], v104, off offset:32
	v_max_f32_e32 v104, v106, v106
	global_store_short v[92:93], v88, off offset:32
	v_max_f32_e32 v88, v90, v90
	global_store_short v[76:77], v72, off offset:32
	v_max_f32_e32 v72, v74, v74
	global_store_short v[60:61], v56, off offset:32
	v_max_f32_e32 v56, v58, v58
	global_store_short v[44:45], v40, off offset:32
	v_max_f32_e32 v40, v42, v42
	global_store_short v[28:29], v24, off offset:32
	v_max_f32_e32 v24, v26, v26
	v_cvt_pk_bf16_f32 v20, v20, s0
	global_store_short v[12:13], v18, off
	v_mul_f32_e32 v14, v14, v14
	v_add_co_u32_e32 v18, vcc, s25, v16
	global_store_short v[12:13], v8, off offset:32
	v_max_f32_e32 v8, v10, v10
	global_store_short v[12:13], v4, off offset:256
	v_max_f32_e32 v4, v6, v6
	global_store_short v[12:13], v0, off offset:288
	v_max_f32_e32 v0, v2, v2
	v_max_f32_e32 v120, 0, v120
	v_max_f32_e32 v104, 0, v104
	v_max_f32_e32 v88, 0, v88
	v_max_f32_e32 v72, 0, v72
	v_max_f32_e32 v56, 0, v56
	v_max_f32_e32 v40, 0, v40
	v_max_f32_e32 v24, 0, v24
	global_store_short v[34:35], v20, off offset:256
	v_max_f32_e32 v20, v23, v23
	v_cvt_pk_bf16_f32 v14, v14, s0
	v_addc_co_u32_e32 v19, vcc, 0, v17, vcc
	v_max_f32_e32 v8, 0, v8
	v_max_f32_e32 v4, 0, v4
	v_max_f32_e32 v0, 0, v0
	v_mul_f32_e32 v120, v120, v120
	v_mul_f32_e32 v104, v104, v104
	v_mul_f32_e32 v88, v88, v88
	v_mul_f32_e32 v72, v72, v72
	v_mul_f32_e32 v56, v56, v56
	v_mul_f32_e32 v40, v40, v40
	v_mul_f32_e32 v24, v24, v24
	v_max_f32_e32 v20, 0, v20
	global_store_short v[18:19], v14, off
	v_max_f32_e32 v14, v15, v15
	v_mul_f32_e32 v8, v8, v8
	v_mul_f32_e32 v4, v4, v4
	v_mul_f32_e32 v0, v0, v0
	v_cvt_pk_bf16_f32 v120, v120, s0
	v_cvt_pk_bf16_f32 v104, v104, s0
	v_cvt_pk_bf16_f32 v88, v88, s0
	v_cvt_pk_bf16_f32 v72, v72, s0
	v_cvt_pk_bf16_f32 v56, v56, s0
	v_cvt_pk_bf16_f32 v40, v40, s0
	v_cvt_pk_bf16_f32 v24, v24, s0
	v_mul_f32_e32 v20, v20, v20
	v_max_f32_e32 v14, 0, v14
	v_cvt_pk_bf16_f32 v8, v8, s0
	v_cvt_pk_bf16_f32 v4, v4, s0
	v_cvt_pk_bf16_f32 v0, v0, s0
	global_store_short v[168:169], v120, off offset:32
	v_max_f32_e32 v120, v123, v123
	global_store_short v[114:115], v104, off offset:32
	v_max_f32_e32 v104, v107, v107
	global_store_short v[98:99], v88, off offset:32
	v_max_f32_e32 v88, v91, v91
	global_store_short v[82:83], v72, off offset:32
	v_max_f32_e32 v72, v75, v75
	global_store_short v[66:67], v56, off offset:32
	v_max_f32_e32 v56, v59, v59
	global_store_short v[50:51], v40, off offset:32
	v_max_f32_e32 v40, v43, v43
	global_store_short v[34:35], v24, off offset:32
	v_max_f32_e32 v24, v27, v27
	v_cvt_pk_bf16_f32 v20, v20, s0
	v_mul_f32_e32 v14, v14, v14
	global_store_short v[18:19], v8, off offset:32
	v_max_f32_e32 v8, v11, v11
	global_store_short v[18:19], v4, off offset:256
	v_max_f32_e32 v4, v7, v7
	global_store_short v[18:19], v0, off offset:288
	v_max_f32_e32 v0, v3, v3
	v_max_f32_e32 v120, 0, v120
	v_max_f32_e32 v104, 0, v104
	v_max_f32_e32 v88, 0, v88
	v_max_f32_e32 v72, 0, v72
	v_max_f32_e32 v56, 0, v56
	v_max_f32_e32 v40, 0, v40
	v_max_f32_e32 v24, 0, v24
	global_store_short v[30:31], v20, off offset:256
	v_cvt_pk_bf16_f32 v20, v14, s0
	v_add_co_u32_e32 v14, vcc, s27, v16
	v_max_f32_e32 v8, 0, v8
	v_max_f32_e32 v4, 0, v4
	v_max_f32_e32 v0, 0, v0
	v_mul_f32_e32 v120, v120, v120
	v_mul_f32_e32 v104, v104, v104
	v_mul_f32_e32 v88, v88, v88
	v_mul_f32_e32 v72, v72, v72
	v_mul_f32_e32 v56, v56, v56
	v_mul_f32_e32 v40, v40, v40
	v_mul_f32_e32 v24, v24, v24
	v_addc_co_u32_e32 v15, vcc, 0, v17, vcc
	v_mul_f32_e32 v8, v8, v8
	v_mul_f32_e32 v4, v4, v4
	v_mul_f32_e32 v0, v0, v0
	v_cvt_pk_bf16_f32 v120, v120, s0
	v_cvt_pk_bf16_f32 v104, v104, s0
	v_cvt_pk_bf16_f32 v88, v88, s0
	v_cvt_pk_bf16_f32 v72, v72, s0
	v_cvt_pk_bf16_f32 v56, v56, s0
	v_cvt_pk_bf16_f32 v40, v40, s0
	v_cvt_pk_bf16_f32 v24, v24, s0
	v_cvt_pk_bf16_f32 v8, v8, s0
	v_cvt_pk_bf16_f32 v4, v4, s0
	v_cvt_pk_bf16_f32 v0, v0, s0
	s_andn2_b64 vcc, exec, s[12:13]
	s_mov_b64 s[12:13], -1
	global_store_short v[126:127], v137, off
	global_store_short v[126:127], v120, off offset:32
	global_store_short v[110:111], v116, off
	global_store_short v[110:111], v104, off offset:32
	global_store_short v[94:95], v100, off
	global_store_short v[94:95], v88, off offset:32
	global_store_short v[78:79], v84, off
	global_store_short v[78:79], v72, off offset:32
	global_store_short v[62:63], v68, off
	global_store_short v[62:63], v56, off offset:32
	global_store_short v[46:47], v52, off
	global_store_short v[46:47], v40, off offset:32
	global_store_short v[30:31], v36, off
	global_store_short v[30:31], v24, off offset:32
	global_store_short v[14:15], v20, off
	global_store_short v[14:15], v8, off offset:32
	global_store_short v[14:15], v4, off offset:256
	global_store_short v[14:15], v0, off offset:288
	s_cbranch_vccnz .LBB0_920
	s_and_saveexec_b64 s[12:13], s[0:1]
	s_xor_b64 s[12:13], exec, s[12:13]
	s_cbranch_execz .LBB0_919
	s_barrier
	s_branch .LBB0_919

; DI f32x16 mfma32(bf16x8 a, bf16x8 b, f32x16 c) { return __builtin_amdgcn_mfma_f32_32x32x16_bf16(a, b, c, 0, 0, 0); }
; template <int EPI, int K, int LNI>
; DI void gemm_tail_unit(const Params& p, const bf16_t* __restrict__ A, const bf16_t* __restrict__ Bt, const int un, float* s_aux) {
;     ...
;     const bf16_t* ap = A + (size_t)(ROW0 + r) * K + w * KS + h * 8;
;     const bf16_t* bp = Bt + (size_t)(col0 + r) * K + w * KS + h * 8;
; #pragma unroll 8
;     for (int s = 0; s < KS / 16; ++s) {
;         const bf16x8 a0 = *(const bf16x8*)(ap + s * 16), a1 = *(const bf16x8*)(ap + (size_t)32 * K + s * 16);
;         const bf16x8 b0 = *(const bf16x8*)(bp + s * 16), b1 = *(const bf16x8*)(bp + (size_t)32 * K + s * 16);
;         acc[0][0] = mfma32(a0, b0, acc[0][0]); acc[0][1] = mfma32(a0, b1, acc[0][1]);
;         acc[1][0] = mfma32(a1, b0, acc[1][0]); acc[1][1] = mfma32(a1, b1, acc[1][1]);
;     }
.LBB0_1014:
	v_lshl_add_u64 v[74:75], v[68:69], 0, s[6:7]
	v_add_co_u32_e32 v102, vcc, s9, v74
	v_lshl_add_u64 v[76:77], v[66:67], 0, s[6:7]
	s_nop 0
	v_addc_co_u32_e32 v103, vcc, 0, v75, vcc
	v_add_co_u32_e32 v104, vcc, s10, v74
	s_add_u32 s6, s6, 0x100
	s_nop 0
	v_addc_co_u32_e32 v105, vcc, 0, v75, vcc
	v_add_co_u32_e32 v106, vcc, s11, v76
	s_addc_u32 s7, s7, 0
	s_nop 0
	v_addc_co_u32_e32 v107, vcc, 0, v77, vcc
	v_add_co_u32_e32 v108, vcc, s12, v76
	s_cmpk_lg_i32 s6, 0x400
	s_nop 0
	v_addc_co_u32_e32 v109, vcc, 0, v77, vcc
	s_nop 1
	v_readfirstlane_b32 s88, v102
	v_readfirstlane_b32 s89, v103
	v_readfirstlane_b32 s90, v106
	v_readfirstlane_b32 s91, v107
	v_and_b32_e32 v220, 63, v71
	v_lshrrev_b32_e32 v221, 3, v220
	v_and_b32_e32 v222, 7, v220
	v_lshlrev_b32_e32 v223, 13, v221
	v_lshl_add_u32 v223, v222, 4, v223
	v_lshlrev_b32_e32 v224, 14, v72
	v_mul_u32_u24_e32 v221, 0x90, v221
	v_lshl_add_u32 v221, v222, 4, v221
	v_add_u32_e32 v221, v221, v224
	v_lshrrev_b32_e32 v222, 5, v220
	v_mul_u32_u24_e32 v225, 0x90, v70
	v_lshl_add_u32 v222, v222, 4, v225
	v_add_u32_e32 v222, v222, v224
	global_load_dwordx4 v[76:79], v223, s[88:89]
	s_add_u32 s92, s88, 0x10000
	s_addc_u32 s93, s89, 0
	s_nop 0
	global_load_dwordx4 v[80:83], v223, s[92:93]
	s_add_u32 s94, s88, 0x20000
	s_addc_u32 s95, s89, 0
	s_nop 0
	global_load_dwordx4 v[84:87], v223, s[94:95]
	s_add_u32 s92, s88, 0x30000
	s_addc_u32 s93, s89, 0
	s_nop 0
	global_load_dwordx4 v[88:91], v223, s[92:93]
	s_add_u32 s94, s88, 0x40000
	s_addc_u32 s95, s89, 0
	s_nop 0
	global_load_dwordx4 v[92:95], v223, s[94:95]
	s_add_u32 s92, s88, 0x50000
	s_addc_u32 s93, s89, 0
	s_nop 0
	global_load_dwordx4 v[96:99], v223, s[92:93]
	s_add_u32 s94, s88, 0x60000
	s_addc_u32 s95, s89, 0
	s_nop 0
	global_load_dwordx4 v[112:115], v223, s[94:95]
	s_add_u32 s92, s88, 0x70000
	s_addc_u32 s93, s89, 0
	s_nop 0
	global_load_dwordx4 v[116:119], v223, s[92:93]
	global_load_dwordx4 v[120:123], v223, s[90:91]
	s_add_u32 s94, s90, 0x10000
	s_addc_u32 s95, s91, 0
	s_nop 0
	global_load_dwordx4 v[124:127], v223, s[94:95]
	s_add_u32 s92, s90, 0x20000
	s_addc_u32 s93, s91, 0
	s_nop 0
	global_load_dwordx4 v[128:131], v223, s[92:93]
	s_add_u32 s94, s90, 0x30000
	s_addc_u32 s95, s91, 0
	s_nop 0
	global_load_dwordx4 v[132:135], v223, s[94:95]
	s_add_u32 s92, s90, 0x40000
	s_addc_u32 s93, s91, 0
	s_nop 0
	global_load_dwordx4 v[136:139], v223, s[92:93]
	s_add_u32 s94, s90, 0x50000
	s_addc_u32 s95, s91, 0
	s_nop 0
	global_load_dwordx4 v[140:143], v223, s[94:95]
	s_add_u32 s92, s90, 0x60000
	s_addc_u32 s93, s91, 0
	s_nop 0
	global_load_dwordx4 v[144:147], v223, s[92:93]
	s_add_u32 s94, s90, 0x70000
	s_addc_u32 s95, s91, 0
	s_nop 0
	global_load_dwordx4 v[148:151], v223, s[94:95]
	global_load_dwordx4 v[152:155], v223, s[88:89] offset:128
	s_add_u32 s92, s88, 0x10000
	s_addc_u32 s93, s89, 0
	s_nop 0
	global_load_dwordx4 v[156:159], v223, s[92:93] offset:128
	s_add_u32 s94, s88, 0x20000
	s_addc_u32 s95, s89, 0
	s_nop 0
	global_load_dwordx4 v[160:163], v223, s[94:95] offset:128
	s_add_u32 s92, s88, 0x30000
	s_addc_u32 s93, s89, 0
	s_nop 0
	global_load_dwordx4 v[164:167], v223, s[92:93] offset:128
	s_add_u32 s94, s88, 0x40000
	s_addc_u32 s95, s89, 0
	s_nop 0
	global_load_dwordx4 v[168:171], v223, s[94:95] offset:128
	s_add_u32 s92, s88, 0x50000
	s_addc_u32 s93, s89, 0
	s_nop 0
	global_load_dwordx4 v[172:175], v223, s[92:93] offset:128
	s_add_u32 s94, s88, 0x60000
	s_addc_u32 s95, s89, 0
	s_nop 0
	global_load_dwordx4 v[176:179], v223, s[94:95] offset:128
	s_add_u32 s92, s88, 0x70000
	s_addc_u32 s93, s89, 0
	s_nop 0
	global_load_dwordx4 v[180:183], v223, s[92:93] offset:128
	global_load_dwordx4 v[184:187], v223, s[90:91] offset:128
	s_add_u32 s94, s90, 0x10000
	s_addc_u32 s95, s91, 0
	s_nop 0
	global_load_dwordx4 v[188:191], v223, s[94:95] offset:128
	s_add_u32 s92, s90, 0x20000
	s_addc_u32 s93, s91, 0
	s_nop 0
	global_load_dwordx4 v[192:195], v223, s[92:93] offset:128
	s_add_u32 s94, s90, 0x30000
	s_addc_u32 s95, s91, 0
	s_nop 0
	global_load_dwordx4 v[196:199], v223, s[94:95] offset:128
	s_add_u32 s92, s90, 0x40000
	s_addc_u32 s93, s91, 0
	s_nop 0
	global_load_dwordx4 v[200:203], v223, s[92:93] offset:128
	s_add_u32 s94, s90, 0x50000
	s_addc_u32 s95, s91, 0
	s_nop 0
	global_load_dwordx4 v[204:207], v223, s[94:95] offset:128
	s_add_u32 s92, s90, 0x60000
	s_addc_u32 s93, s91, 0
	s_nop 0
	global_load_dwordx4 v[212:215], v223, s[92:93] offset:128
	s_add_u32 s94, s90, 0x70000
	s_addc_u32 s95, s91, 0
	s_nop 0
	global_load_dwordx4 v[216:219], v223, s[94:95] offset:128
	s_waitcnt vmcnt(24) lgkmcnt(0)
	ds_write_b128 v221, v[76:79]
	ds_write_b128 v221, v[80:83] offset:1152
	ds_write_b128 v221, v[84:87] offset:2304
	ds_write_b128 v221, v[88:91] offset:3456
	ds_write_b128 v221, v[92:95] offset:4608
	ds_write_b128 v221, v[96:99] offset:5760
	ds_write_b128 v221, v[112:115] offset:6912
	ds_write_b128 v221, v[116:119] offset:8064
	s_waitcnt lgkmcnt(0)
	ds_read_b128 v[76:79], v222
	ds_read_b128 v[80:83], v222 offset:32
	ds_read_b128 v[84:87], v222 offset:64
	ds_read_b128 v[88:91], v222 offset:96
	ds_read_b128 v[92:95], v222 offset:4608
	ds_read_b128 v[96:99], v222 offset:4640
	ds_read_b128 v[112:115], v222 offset:4672
	ds_read_b128 v[116:119], v222 offset:4704
	s_waitcnt vmcnt(16) lgkmcnt(0)
	ds_write_b128 v221, v[120:123]
	ds_write_b128 v221, v[124:127] offset:1152
	ds_write_b128 v221, v[128:131] offset:2304
	ds_write_b128 v221, v[132:135] offset:3456
	ds_write_b128 v221, v[136:139] offset:4608
	ds_write_b128 v221, v[140:143] offset:5760
	ds_write_b128 v221, v[144:147] offset:6912
	ds_write_b128 v221, v[148:151] offset:8064
	s_waitcnt lgkmcnt(0)
; DI f32x16 mfma32(bf16x8 a, bf16x8 b, f32x16 c) { return __builtin_amdgcn_mfma_f32_32x32x16_bf16(a, b, c, 0, 0, 0); }
; template <int EPI, int K, int LNI>
; DI void gemm_tail_unit(const Params& p, const bf16_t* __restrict__ A, const bf16_t* __restrict__ Bt, const int un, float* s_aux) {
;     ...
;     const bf16_t* ap = A + (size_t)(ROW0 + r) * K + w * KS + h * 8;
;     const bf16_t* bp = Bt + (size_t)(col0 + r) * K + w * KS + h * 8;
; #pragma unroll 8
;     for (int s = 0; s < KS / 16; ++s) {
;         const bf16x8 a0 = *(const bf16x8*)(ap + s * 16), a1 = *(const bf16x8*)(ap + (size_t)32 * K + s * 16);
;         const bf16x8 b0 = *(const bf16x8*)(bp + s * 16), b1 = *(const bf16x8*)(bp + (size_t)32 * K + s * 16);
;         acc[0][0] = mfma32(a0, b0, acc[0][0]); acc[0][1] = mfma32(a0, b1, acc[0][1]);
;         acc[1][0] = mfma32(a1, b0, acc[1][0]); acc[1][1] = mfma32(a1, b1, acc[1][1]);
;     }
	ds_read_b128 v[120:123], v222
	ds_read_b128 v[124:127], v222 offset:32
	ds_read_b128 v[128:131], v222 offset:64
	ds_read_b128 v[132:135], v222 offset:96
	ds_read_b128 v[136:139], v222 offset:4608
	ds_read_b128 v[140:143], v222 offset:4640
	ds_read_b128 v[144:147], v222 offset:4672
	ds_read_b128 v[148:151], v222 offset:4704
	s_waitcnt lgkmcnt(0)
	v_mfma_f32_32x32x16_bf16 v[0:15], v[76:79], v[120:123], v[0:15]
	v_mfma_f32_32x32x16_bf16 v[16:31], v[76:79], v[136:139], v[16:31]
	v_mfma_f32_32x32x16_bf16 v[32:47], v[92:95], v[120:123], v[32:47]
	v_mfma_f32_32x32x16_bf16 v[48:63], v[92:95], v[136:139], v[48:63]
	v_mfma_f32_32x32x16_bf16 v[0:15], v[80:83], v[124:127], v[0:15]
	v_mfma_f32_32x32x16_bf16 v[16:31], v[80:83], v[140:143], v[16:31]
	v_mfma_f32_32x32x16_bf16 v[32:47], v[96:99], v[124:127], v[32:47]
	v_mfma_f32_32x32x16_bf16 v[48:63], v[96:99], v[140:143], v[48:63]
	v_mfma_f32_32x32x16_bf16 v[0:15], v[84:87], v[128:131], v[0:15]
	v_mfma_f32_32x32x16_bf16 v[16:31], v[84:87], v[144:147], v[16:31]
	v_mfma_f32_32x32x16_bf16 v[32:47], v[112:115], v[128:131], v[32:47]
	v_mfma_f32_32x32x16_bf16 v[48:63], v[112:115], v[144:147], v[48:63]
	v_mfma_f32_32x32x16_bf16 v[0:15], v[88:91], v[132:135], v[0:15]
	v_mfma_f32_32x32x16_bf16 v[16:31], v[88:91], v[148:151], v[16:31]
	v_mfma_f32_32x32x16_bf16 v[32:47], v[116:119], v[132:135], v[32:47]
	v_mfma_f32_32x32x16_bf16 v[48:63], v[116:119], v[148:151], v[48:63]
	global_load_dwordx4 v[76:79], v223, s[88:89] offset:256
	s_add_u32 s92, s88, 0x10000
	s_addc_u32 s93, s89, 0
	s_nop 0
	global_load_dwordx4 v[80:83], v223, s[92:93] offset:256
	s_add_u32 s94, s88, 0x20000
	s_addc_u32 s95, s89, 0
	s_nop 0
	global_load_dwordx4 v[84:87], v223, s[94:95] offset:256
	s_add_u32 s92, s88, 0x30000
	s_addc_u32 s93, s89, 0
	s_nop 0
	global_load_dwordx4 v[88:91], v223, s[92:93] offset:256
	s_add_u32 s94, s88, 0x40000
	s_addc_u32 s95, s89, 0
	s_nop 0
	global_load_dwordx4 v[92:95], v223, s[94:95] offset:256
	s_add_u32 s92, s88, 0x50000
	s_addc_u32 s93, s89, 0
	s_nop 0
	global_load_dwordx4 v[96:99], v223, s[92:93] offset:256
	s_add_u32 s94, s88, 0x60000
	s_addc_u32 s95, s89, 0
	s_nop 0
	global_load_dwordx4 v[112:115], v223, s[94:95] offset:256
	s_add_u32 s92, s88, 0x70000
	s_addc_u32 s93, s89, 0
	s_nop 0
	global_load_dwordx4 v[116:119], v223, s[92:93] offset:256
	global_load_dwordx4 v[120:123], v223, s[90:91] offset:256
	s_add_u32 s94, s90, 0x10000
	s_addc_u32 s95, s91, 0
	s_nop 0
	global_load_dwordx4 v[124:127], v223, s[94:95] offset:256
	s_add_u32 s92, s90, 0x20000
	s_addc_u32 s93, s91, 0
	s_nop 0
	global_load_dwordx4 v[128:131], v223, s[92:93] offset:256
	s_add_u32 s94, s90, 0x30000
	s_addc_u32 s95, s91, 0
	s_nop 0
	global_load_dwordx4 v[132:135], v223, s[94:95] offset:256
	s_add_u32 s92, s90, 0x40000
	s_addc_u32 s93, s91, 0
	s_nop 0
	global_load_dwordx4 v[136:139], v223, s[92:93] offset:256
	s_add_u32 s94, s90, 0x50000
	s_addc_u32 s95, s91, 0
	s_nop 0
	global_load_dwordx4 v[140:143], v223, s[94:95] offset:256
	s_add_u32 s92, s90, 0x60000
	s_addc_u32 s93, s91, 0
	s_nop 0
	global_load_dwordx4 v[144:147], v223, s[92:93] offset:256
	s_add_u32 s94, s90, 0x70000
	s_addc_u32 s95, s91, 0
	s_nop 0
	global_load_dwordx4 v[148:151], v223, s[94:95] offset:256
	s_waitcnt vmcnt(24) lgkmcnt(0)
	ds_write_b128 v221, v[152:155]
	ds_write_b128 v221, v[156:159] offset:1152
	ds_write_b128 v221, v[160:163] offset:2304
	ds_write_b128 v221, v[164:167] offset:3456
	ds_write_b128 v221, v[168:171] offset:4608
	ds_write_b128 v221, v[172:175] offset:5760
	ds_write_b128 v221, v[176:179] offset:6912
	ds_write_b128 v221, v[180:183] offset:8064
	s_waitcnt lgkmcnt(0)
	ds_read_b128 v[152:155], v222
	ds_read_b128 v[156:159], v222 offset:32
	ds_read_b128 v[160:163], v222 offset:64
	ds_read_b128 v[164:167], v222 offset:96
	ds_read_b128 v[168:171], v222 offset:4608
	ds_read_b128 v[172:175], v222 offset:4640
	ds_read_b128 v[176:179], v222 offset:4672
	ds_read_b128 v[180:183], v222 offset:4704
	s_waitcnt vmcnt(16) lgkmcnt(0)
	ds_write_b128 v221, v[184:187]
	ds_write_b128 v221, v[188:191] offset:1152
	ds_write_b128 v221, v[192:195] offset:2304
	ds_write_b128 v221, v[196:199] offset:3456
	ds_write_b128 v221, v[200:203] offset:4608
	ds_write_b128 v221, v[204:207] offset:5760
	ds_write_b128 v221, v[212:215] offset:6912
	ds_write_b128 v221, v[216:219] offset:8064
	s_waitcnt lgkmcnt(0)
	ds_read_b128 v[184:187], v222
	ds_read_b128 v[188:191], v222 offset:32
	ds_read_b128 v[192:195], v222 offset:64
	ds_read_b128 v[196:199], v222 offset:96
	ds_read_b128 v[200:203], v222 offset:4608
	ds_read_b128 v[204:207], v222 offset:4640
	ds_read_b128 v[212:215], v222 offset:4672
	ds_read_b128 v[216:219], v222 offset:4704
	s_waitcnt lgkmcnt(0)
; DI f32x16 mfma32(bf16x8 a, bf16x8 b, f32x16 c) { return __builtin_amdgcn_mfma_f32_32x32x16_bf16(a, b, c, 0, 0, 0); }
; template <int EPI, int K, int LNI>
; DI void gemm_tail_unit(const Params& p, const bf16_t* __restrict__ A, const bf16_t* __restrict__ Bt, const int un, float* s_aux) {
;     ...
;     const bf16_t* ap = A + (size_t)(ROW0 + r) * K + w * KS + h * 8;
;     const bf16_t* bp = Bt + (size_t)(col0 + r) * K + w * KS + h * 8;
; #pragma unroll 8
;     for (int s = 0; s < KS / 16; ++s) {
;         const bf16x8 a0 = *(const bf16x8*)(ap + s * 16), a1 = *(const bf16x8*)(ap + (size_t)32 * K + s * 16);
;         const bf16x8 b0 = *(const bf16x8*)(bp + s * 16), b1 = *(const bf16x8*)(bp + (size_t)32 * K + s * 16);
;         acc[0][0] = mfma32(a0, b0, acc[0][0]); acc[0][1] = mfma32(a0, b1, acc[0][1]);
;         acc[1][0] = mfma32(a1, b0, acc[1][0]); acc[1][1] = mfma32(a1, b1, acc[1][1]);
;     }
	v_mfma_f32_32x32x16_bf16 v[0:15], v[152:155], v[184:187], v[0:15]
	v_mfma_f32_32x32x16_bf16 v[16:31], v[152:155], v[200:203], v[16:31]
	v_mfma_f32_32x32x16_bf16 v[32:47], v[168:171], v[184:187], v[32:47]
	v_mfma_f32_32x32x16_bf16 v[48:63], v[168:171], v[200:203], v[48:63]
	v_mfma_f32_32x32x16_bf16 v[0:15], v[156:159], v[188:191], v[0:15]
	v_mfma_f32_32x32x16_bf16 v[16:31], v[156:159], v[204:207], v[16:31]
	v_mfma_f32_32x32x16_bf16 v[32:47], v[172:175], v[188:191], v[32:47]
	v_mfma_f32_32x32x16_bf16 v[48:63], v[172:175], v[204:207], v[48:63]
	v_mfma_f32_32x32x16_bf16 v[0:15], v[160:163], v[192:195], v[0:15]
	v_mfma_f32_32x32x16_bf16 v[16:31], v[160:163], v[212:215], v[16:31]
	v_mfma_f32_32x32x16_bf16 v[32:47], v[176:179], v[192:195], v[32:47]
	v_mfma_f32_32x32x16_bf16 v[48:63], v[176:179], v[212:215], v[48:63]
	v_mfma_f32_32x32x16_bf16 v[0:15], v[164:167], v[196:199], v[0:15]
	v_mfma_f32_32x32x16_bf16 v[16:31], v[164:167], v[216:219], v[16:31]
	v_mfma_f32_32x32x16_bf16 v[32:47], v[180:183], v[196:199], v[32:47]
	v_mfma_f32_32x32x16_bf16 v[48:63], v[180:183], v[216:219], v[48:63]
	global_load_dwordx4 v[152:155], v223, s[88:89] offset:384
	s_add_u32 s92, s88, 0x10000
	s_addc_u32 s93, s89, 0
	s_nop 0
	global_load_dwordx4 v[156:159], v223, s[92:93] offset:384
	s_add_u32 s94, s88, 0x20000
	s_addc_u32 s95, s89, 0
	s_nop 0
	global_load_dwordx4 v[160:163], v223, s[94:95] offset:384
	s_add_u32 s92, s88, 0x30000
	s_addc_u32 s93, s89, 0
	s_nop 0
	global_load_dwordx4 v[164:167], v223, s[92:93] offset:384
	s_add_u32 s94, s88, 0x40000
	s_addc_u32 s95, s89, 0
	s_nop 0
	global_load_dwordx4 v[168:171], v223, s[94:95] offset:384
	s_add_u32 s92, s88, 0x50000
	s_addc_u32 s93, s89, 0
	s_nop 0
	global_load_dwordx4 v[172:175], v223, s[92:93] offset:384
	s_add_u32 s94, s88, 0x60000
	s_addc_u32 s95, s89, 0
	s_nop 0
	global_load_dwordx4 v[176:179], v223, s[94:95] offset:384
	s_add_u32 s92, s88, 0x70000
	s_addc_u32 s93, s89, 0
	s_nop 0
	global_load_dwordx4 v[180:183], v223, s[92:93] offset:384
	global_load_dwordx4 v[184:187], v223, s[90:91] offset:384
	s_add_u32 s94, s90, 0x10000
	s_addc_u32 s95, s91, 0
	s_nop 0
	global_load_dwordx4 v[188:191], v223, s[94:95] offset:384
	s_add_u32 s92, s90, 0x20000
	s_addc_u32 s93, s91, 0
	s_nop 0
	global_load_dwordx4 v[192:195], v223, s[92:93] offset:384
	s_add_u32 s94, s90, 0x30000
	s_addc_u32 s95, s91, 0
	s_nop 0
	global_load_dwordx4 v[196:199], v223, s[94:95] offset:384
	s_add_u32 s92, s90, 0x40000
	s_addc_u32 s93, s91, 0
	s_nop 0
	global_load_dwordx4 v[200:203], v223, s[92:93] offset:384
	s_add_u32 s94, s90, 0x50000
	s_addc_u32 s95, s91, 0
	s_nop 0
	global_load_dwordx4 v[204:207], v223, s[94:95] offset:384
	s_add_u32 s92, s90, 0x60000
	s_addc_u32 s93, s91, 0
	s_nop 0
	global_load_dwordx4 v[212:215], v223, s[92:93] offset:384
	s_add_u32 s94, s90, 0x70000
	s_addc_u32 s95, s91, 0
	s_nop 0
	global_load_dwordx4 v[216:219], v223, s[94:95] offset:384
	s_waitcnt vmcnt(24) lgkmcnt(0)
	ds_write_b128 v221, v[76:79]
	ds_write_b128 v221, v[80:83] offset:1152
	ds_write_b128 v221, v[84:87] offset:2304
	ds_write_b128 v221, v[88:91] offset:3456
	ds_write_b128 v221, v[92:95] offset:4608
	ds_write_b128 v221, v[96:99] offset:5760
	ds_write_b128 v221, v[112:115] offset:6912
	ds_write_b128 v221, v[116:119] offset:8064
	s_waitcnt lgkmcnt(0)
	ds_read_b128 v[76:79], v222
	ds_read_b128 v[80:83], v222 offset:32
	ds_read_b128 v[84:87], v222 offset:64
	ds_read_b128 v[88:91], v222 offset:96
	ds_read_b128 v[92:95], v222 offset:4608
	ds_read_b128 v[96:99], v222 offset:4640
	ds_read_b128 v[112:115], v222 offset:4672
	ds_read_b128 v[116:119], v222 offset:4704
	s_waitcnt vmcnt(16) lgkmcnt(0)
	ds_write_b128 v221, v[120:123]
	ds_write_b128 v221, v[124:127] offset:1152
	ds_write_b128 v221, v[128:131] offset:2304
	ds_write_b128 v221, v[132:135] offset:3456
	ds_write_b128 v221, v[136:139] offset:4608
	ds_write_b128 v221, v[140:143] offset:5760
	ds_write_b128 v221, v[144:147] offset:6912
	ds_write_b128 v221, v[148:151] offset:8064
	s_waitcnt lgkmcnt(0)
	ds_read_b128 v[120:123], v222
	ds_read_b128 v[124:127], v222 offset:32
	ds_read_b128 v[128:131], v222 offset:64
	ds_read_b128 v[132:135], v222 offset:96
	ds_read_b128 v[136:139], v222 offset:4608
	ds_read_b128 v[140:143], v222 offset:4640
	ds_read_b128 v[144:147], v222 offset:4672
	ds_read_b128 v[148:151], v222 offset:4704
	s_waitcnt lgkmcnt(0)
; DI f32x16 mfma32(bf16x8 a, bf16x8 b, f32x16 c) { return __builtin_amdgcn_mfma_f32_32x32x16_bf16(a, b, c, 0, 0, 0); }
; template <int EPI, int K, int LNI>
; DI void gemm_tail_unit(const Params& p, const bf16_t* __restrict__ A, const bf16_t* __restrict__ Bt, const int un, float* s_aux) {
;     ...
;     const bf16_t* ap = A + (size_t)(ROW0 + r) * K + w * KS + h * 8;
;     const bf16_t* bp = Bt + (size_t)(col0 + r) * K + w * KS + h * 8;
; #pragma unroll 8
;     for (int s = 0; s < KS / 16; ++s) {
;         const bf16x8 a0 = *(const bf16x8*)(ap + s * 16), a1 = *(const bf16x8*)(ap + (size_t)32 * K + s * 16);
;         const bf16x8 b0 = *(const bf16x8*)(bp + s * 16), b1 = *(const bf16x8*)(bp + (size_t)32 * K + s * 16);
;         acc[0][0] = mfma32(a0, b0, acc[0][0]); acc[0][1] = mfma32(a0, b1, acc[0][1]);
;         acc[1][0] = mfma32(a1, b0, acc[1][0]); acc[1][1] = mfma32(a1, b1, acc[1][1]);
;     }
	v_mfma_f32_32x32x16_bf16 v[0:15], v[76:79], v[120:123], v[0:15]
	v_mfma_f32_32x32x16_bf16 v[16:31], v[76:79], v[136:139], v[16:31]
	v_mfma_f32_32x32x16_bf16 v[32:47], v[92:95], v[120:123], v[32:47]
	v_mfma_f32_32x32x16_bf16 v[48:63], v[92:95], v[136:139], v[48:63]
	v_mfma_f32_32x32x16_bf16 v[0:15], v[80:83], v[124:127], v[0:15]
	v_mfma_f32_32x32x16_bf16 v[16:31], v[80:83], v[140:143], v[16:31]
	v_mfma_f32_32x32x16_bf16 v[32:47], v[96:99], v[124:127], v[32:47]
	v_mfma_f32_32x32x16_bf16 v[48:63], v[96:99], v[140:143], v[48:63]
	v_mfma_f32_32x32x16_bf16 v[0:15], v[84:87], v[128:131], v[0:15]
	v_mfma_f32_32x32x16_bf16 v[16:31], v[84:87], v[144:147], v[16:31]
	v_mfma_f32_32x32x16_bf16 v[32:47], v[112:115], v[128:131], v[32:47]
	v_mfma_f32_32x32x16_bf16 v[48:63], v[112:115], v[144:147], v[48:63]
	v_mfma_f32_32x32x16_bf16 v[0:15], v[88:91], v[132:135], v[0:15]
	v_mfma_f32_32x32x16_bf16 v[16:31], v[88:91], v[148:151], v[16:31]
	v_mfma_f32_32x32x16_bf16 v[32:47], v[116:119], v[132:135], v[32:47]
	v_mfma_f32_32x32x16_bf16 v[48:63], v[116:119], v[148:151], v[48:63]
	global_load_dwordx4 v[76:79], v223, s[88:89] offset:512
	s_add_u32 s92, s88, 0x10000
	s_addc_u32 s93, s89, 0
	s_nop 0
	global_load_dwordx4 v[80:83], v223, s[92:93] offset:512
	s_add_u32 s94, s88, 0x20000
	s_addc_u32 s95, s89, 0
	s_nop 0
	global_load_dwordx4 v[84:87], v223, s[94:95] offset:512
	s_add_u32 s92, s88, 0x30000
	s_addc_u32 s93, s89, 0
	s_nop 0
	global_load_dwordx4 v[88:91], v223, s[92:93] offset:512
	s_add_u32 s94, s88, 0x40000
	s_addc_u32 s95, s89, 0
	s_nop 0
	global_load_dwordx4 v[92:95], v223, s[94:95] offset:512
	s_add_u32 s92, s88, 0x50000
	s_addc_u32 s93, s89, 0
	s_nop 0
	global_load_dwordx4 v[96:99], v223, s[92:93] offset:512
	s_add_u32 s94, s88, 0x60000
	s_addc_u32 s95, s89, 0
	s_nop 0
	global_load_dwordx4 v[112:115], v223, s[94:95] offset:512
	s_add_u32 s92, s88, 0x70000
	s_addc_u32 s93, s89, 0
	s_nop 0
	global_load_dwordx4 v[116:119], v223, s[92:93] offset:512
	global_load_dwordx4 v[120:123], v223, s[90:91] offset:512
	s_add_u32 s94, s90, 0x10000
	s_addc_u32 s95, s91, 0
	s_nop 0
	global_load_dwordx4 v[124:127], v223, s[94:95] offset:512
	s_add_u32 s92, s90, 0x20000
	s_addc_u32 s93, s91, 0
	s_nop 0
	global_load_dwordx4 v[128:131], v223, s[92:93] offset:512
	s_add_u32 s94, s90, 0x30000
	s_addc_u32 s95, s91, 0
	s_nop 0
	global_load_dwordx4 v[132:135], v223, s[94:95] offset:512
	s_add_u32 s92, s90, 0x40000
	s_addc_u32 s93, s91, 0
	s_nop 0
	global_load_dwordx4 v[136:139], v223, s[92:93] offset:512
	s_add_u32 s94, s90, 0x50000
	s_addc_u32 s95, s91, 0
	s_nop 0
	global_load_dwordx4 v[140:143], v223, s[94:95] offset:512
	s_add_u32 s92, s90, 0x60000
	s_addc_u32 s93, s91, 0
	s_nop 0
	global_load_dwordx4 v[144:147], v223, s[92:93] offset:512
	s_add_u32 s94, s90, 0x70000
	s_addc_u32 s95, s91, 0
	s_nop 0
	global_load_dwordx4 v[148:151], v223, s[94:95] offset:512
	s_waitcnt vmcnt(24) lgkmcnt(0)
	ds_write_b128 v221, v[152:155]
	ds_write_b128 v221, v[156:159] offset:1152
	ds_write_b128 v221, v[160:163] offset:2304
	ds_write_b128 v221, v[164:167] offset:3456
	ds_write_b128 v221, v[168:171] offset:4608
	ds_write_b128 v221, v[172:175] offset:5760
	ds_write_b128 v221, v[176:179] offset:6912
	ds_write_b128 v221, v[180:183] offset:8064
	s_waitcnt lgkmcnt(0)
	ds_read_b128 v[152:155], v222
	ds_read_b128 v[156:159], v222 offset:32
	ds_read_b128 v[160:163], v222 offset:64
	ds_read_b128 v[164:167], v222 offset:96
	ds_read_b128 v[168:171], v222 offset:4608
	ds_read_b128 v[172:175], v222 offset:4640
	ds_read_b128 v[176:179], v222 offset:4672
	ds_read_b128 v[180:183], v222 offset:4704
	s_waitcnt vmcnt(16) lgkmcnt(0)
	ds_write_b128 v221, v[184:187]
	ds_write_b128 v221, v[188:191] offset:1152
	ds_write_b128 v221, v[192:195] offset:2304
	ds_write_b128 v221, v[196:199] offset:3456
	ds_write_b128 v221, v[200:203] offset:4608
	ds_write_b128 v221, v[204:207] offset:5760
	ds_write_b128 v221, v[212:215] offset:6912
	ds_write_b128 v221, v[216:219] offset:8064
	s_waitcnt lgkmcnt(0)
	ds_read_b128 v[184:187], v222
	ds_read_b128 v[188:191], v222 offset:32
	ds_read_b128 v[192:195], v222 offset:64
	ds_read_b128 v[196:199], v222 offset:96
	ds_read_b128 v[200:203], v222 offset:4608
	ds_read_b128 v[204:207], v222 offset:4640
	ds_read_b128 v[212:215], v222 offset:4672
	ds_read_b128 v[216:219], v222 offset:4704
	s_waitcnt lgkmcnt(0)
; DI f32x16 mfma32(bf16x8 a, bf16x8 b, f32x16 c) { return __builtin_amdgcn_mfma_f32_32x32x16_bf16(a, b, c, 0, 0, 0); }
; template <int EPI, int K, int LNI>
; DI void gemm_tail_unit(const Params& p, const bf16_t* __restrict__ A, const bf16_t* __restrict__ Bt, const int un, float* s_aux) {
;     ...
;     const bf16_t* ap = A + (size_t)(ROW0 + r) * K + w * KS + h * 8;
;     const bf16_t* bp = Bt + (size_t)(col0 + r) * K + w * KS + h * 8;
; #pragma unroll 8
;     for (int s = 0; s < KS / 16; ++s) {
;         const bf16x8 a0 = *(const bf16x8*)(ap + s * 16), a1 = *(const bf16x8*)(ap + (size_t)32 * K + s * 16);
;         const bf16x8 b0 = *(const bf16x8*)(bp + s * 16), b1 = *(const bf16x8*)(bp + (size_t)32 * K + s * 16);
;         acc[0][0] = mfma32(a0, b0, acc[0][0]); acc[0][1] = mfma32(a0, b1, acc[0][1]);
;         acc[1][0] = mfma32(a1, b0, acc[1][0]); acc[1][1] = mfma32(a1, b1, acc[1][1]);
;     }
	v_mfma_f32_32x32x16_bf16 v[0:15], v[152:155], v[184:187], v[0:15]
	v_mfma_f32_32x32x16_bf16 v[16:31], v[152:155], v[200:203], v[16:31]
	v_mfma_f32_32x32x16_bf16 v[32:47], v[168:171], v[184:187], v[32:47]
	v_mfma_f32_32x32x16_bf16 v[48:63], v[168:171], v[200:203], v[48:63]
	v_mfma_f32_32x32x16_bf16 v[0:15], v[156:159], v[188:191], v[0:15]
	v_mfma_f32_32x32x16_bf16 v[16:31], v[156:159], v[204:207], v[16:31]
	v_mfma_f32_32x32x16_bf16 v[32:47], v[172:175], v[188:191], v[32:47]
	v_mfma_f32_32x32x16_bf16 v[48:63], v[172:175], v[204:207], v[48:63]
	v_mfma_f32_32x32x16_bf16 v[0:15], v[160:163], v[192:195], v[0:15]
	v_mfma_f32_32x32x16_bf16 v[16:31], v[160:163], v[212:215], v[16:31]
	v_mfma_f32_32x32x16_bf16 v[32:47], v[176:179], v[192:195], v[32:47]
	v_mfma_f32_32x32x16_bf16 v[48:63], v[176:179], v[212:215], v[48:63]
	v_mfma_f32_32x32x16_bf16 v[0:15], v[164:167], v[196:199], v[0:15]
	v_mfma_f32_32x32x16_bf16 v[16:31], v[164:167], v[216:219], v[16:31]
	v_mfma_f32_32x32x16_bf16 v[32:47], v[180:183], v[196:199], v[32:47]
	v_mfma_f32_32x32x16_bf16 v[48:63], v[180:183], v[216:219], v[48:63]
	global_load_dwordx4 v[152:155], v223, s[88:89] offset:640
	s_add_u32 s92, s88, 0x10000
	s_addc_u32 s93, s89, 0
	s_nop 0
	global_load_dwordx4 v[156:159], v223, s[92:93] offset:640
	s_add_u32 s94, s88, 0x20000
	s_addc_u32 s95, s89, 0
	s_nop 0
	global_load_dwordx4 v[160:163], v223, s[94:95] offset:640
	s_add_u32 s92, s88, 0x30000
	s_addc_u32 s93, s89, 0
	s_nop 0
	global_load_dwordx4 v[164:167], v223, s[92:93] offset:640
	s_add_u32 s94, s88, 0x40000
	s_addc_u32 s95, s89, 0
	s_nop 0
	global_load_dwordx4 v[168:171], v223, s[94:95] offset:640
	s_add_u32 s92, s88, 0x50000
	s_addc_u32 s93, s89, 0
	s_nop 0
	global_load_dwordx4 v[172:175], v223, s[92:93] offset:640
	s_add_u32 s94, s88, 0x60000
	s_addc_u32 s95, s89, 0
	s_nop 0
	global_load_dwordx4 v[176:179], v223, s[94:95] offset:640
	s_add_u32 s92, s88, 0x70000
	s_addc_u32 s93, s89, 0
	s_nop 0
	global_load_dwordx4 v[180:183], v223, s[92:93] offset:640
	global_load_dwordx4 v[184:187], v223, s[90:91] offset:640
	s_add_u32 s94, s90, 0x10000
	s_addc_u32 s95, s91, 0
	s_nop 0
	global_load_dwordx4 v[188:191], v223, s[94:95] offset:640
	s_add_u32 s92, s90, 0x20000
	s_addc_u32 s93, s91, 0
	s_nop 0
	global_load_dwordx4 v[192:195], v223, s[92:93] offset:640
	s_add_u32 s94, s90, 0x30000
	s_addc_u32 s95, s91, 0
	s_nop 0
	global_load_dwordx4 v[196:199], v223, s[94:95] offset:640
	s_add_u32 s92, s90, 0x40000
	s_addc_u32 s93, s91, 0
	s_nop 0
	global_load_dwordx4 v[200:203], v223, s[92:93] offset:640
	s_add_u32 s94, s90, 0x50000
	s_addc_u32 s95, s91, 0
	s_nop 0
	global_load_dwordx4 v[204:207], v223, s[94:95] offset:640
	s_add_u32 s92, s90, 0x60000
	s_addc_u32 s93, s91, 0
	s_nop 0
	global_load_dwordx4 v[212:215], v223, s[92:93] offset:640
	s_add_u32 s94, s90, 0x70000
	s_addc_u32 s95, s91, 0
	s_nop 0
	global_load_dwordx4 v[216:219], v223, s[94:95] offset:640
	s_waitcnt vmcnt(24) lgkmcnt(0)
	ds_write_b128 v221, v[76:79]
	ds_write_b128 v221, v[80:83] offset:1152
	ds_write_b128 v221, v[84:87] offset:2304
	ds_write_b128 v221, v[88:91] offset:3456
	ds_write_b128 v221, v[92:95] offset:4608
	ds_write_b128 v221, v[96:99] offset:5760
	ds_write_b128 v221, v[112:115] offset:6912
	ds_write_b128 v221, v[116:119] offset:8064
	s_waitcnt lgkmcnt(0)
	ds_read_b128 v[76:79], v222
	ds_read_b128 v[80:83], v222 offset:32
	ds_read_b128 v[84:87], v222 offset:64
	ds_read_b128 v[88:91], v222 offset:96
	ds_read_b128 v[92:95], v222 offset:4608
	ds_read_b128 v[96:99], v222 offset:4640
	ds_read_b128 v[112:115], v222 offset:4672
	ds_read_b128 v[116:119], v222 offset:4704
	s_waitcnt vmcnt(16) lgkmcnt(0)
	ds_write_b128 v221, v[120:123]
	ds_write_b128 v221, v[124:127] offset:1152
	ds_write_b128 v221, v[128:131] offset:2304
	ds_write_b128 v221, v[132:135] offset:3456
	ds_write_b128 v221, v[136:139] offset:4608
	ds_write_b128 v221, v[140:143] offset:5760
	ds_write_b128 v221, v[144:147] offset:6912
	ds_write_b128 v221, v[148:151] offset:8064
	s_waitcnt lgkmcnt(0)
	ds_read_b128 v[120:123], v222
	ds_read_b128 v[124:127], v222 offset:32
	ds_read_b128 v[128:131], v222 offset:64
	ds_read_b128 v[132:135], v222 offset:96
	ds_read_b128 v[136:139], v222 offset:4608
	ds_read_b128 v[140:143], v222 offset:4640
	ds_read_b128 v[144:147], v222 offset:4672
	ds_read_b128 v[148:151], v222 offset:4704
	s_waitcnt lgkmcnt(0)
; DI f32x16 mfma32(bf16x8 a, bf16x8 b, f32x16 c) { return __builtin_amdgcn_mfma_f32_32x32x16_bf16(a, b, c, 0, 0, 0); }
; template <int EPI, int K, int LNI>
; DI void gemm_tail_unit(const Params& p, const bf16_t* __restrict__ A, const bf16_t* __restrict__ Bt, const int un, float* s_aux) {
;     ...
;     const bf16_t* ap = A + (size_t)(ROW0 + r) * K + w * KS + h * 8;
;     const bf16_t* bp = Bt + (size_t)(col0 + r) * K + w * KS + h * 8;
; #pragma unroll 8
;     for (int s = 0; s < KS / 16; ++s) {
;         const bf16x8 a0 = *(const bf16x8*)(ap + s * 16), a1 = *(const bf16x8*)(ap + (size_t)32 * K + s * 16);
;         const bf16x8 b0 = *(const bf16x8*)(bp + s * 16), b1 = *(const bf16x8*)(bp + (size_t)32 * K + s * 16);
;         acc[0][0] = mfma32(a0, b0, acc[0][0]); acc[0][1] = mfma32(a0, b1, acc[0][1]);
;         acc[1][0] = mfma32(a1, b0, acc[1][0]); acc[1][1] = mfma32(a1, b1, acc[1][1]);
;     }
	v_mfma_f32_32x32x16_bf16 v[0:15], v[76:79], v[120:123], v[0:15]
	v_mfma_f32_32x32x16_bf16 v[16:31], v[76:79], v[136:139], v[16:31]
	v_mfma_f32_32x32x16_bf16 v[32:47], v[92:95], v[120:123], v[32:47]
	v_mfma_f32_32x32x16_bf16 v[48:63], v[92:95], v[136:139], v[48:63]
	v_mfma_f32_32x32x16_bf16 v[0:15], v[80:83], v[124:127], v[0:15]
	v_mfma_f32_32x32x16_bf16 v[16:31], v[80:83], v[140:143], v[16:31]
	v_mfma_f32_32x32x16_bf16 v[32:47], v[96:99], v[124:127], v[32:47]
	v_mfma_f32_32x32x16_bf16 v[48:63], v[96:99], v[140:143], v[48:63]
	v_mfma_f32_32x32x16_bf16 v[0:15], v[84:87], v[128:131], v[0:15]
	v_mfma_f32_32x32x16_bf16 v[16:31], v[84:87], v[144:147], v[16:31]
	v_mfma_f32_32x32x16_bf16 v[32:47], v[112:115], v[128:131], v[32:47]
	v_mfma_f32_32x32x16_bf16 v[48:63], v[112:115], v[144:147], v[48:63]
	v_mfma_f32_32x32x16_bf16 v[0:15], v[88:91], v[132:135], v[0:15]
	v_mfma_f32_32x32x16_bf16 v[16:31], v[88:91], v[148:151], v[16:31]
	v_mfma_f32_32x32x16_bf16 v[32:47], v[116:119], v[132:135], v[32:47]
	v_mfma_f32_32x32x16_bf16 v[48:63], v[116:119], v[148:151], v[48:63]
	global_load_dwordx4 v[76:79], v223, s[88:89] offset:768
	s_add_u32 s92, s88, 0x10000
	s_addc_u32 s93, s89, 0
	s_nop 0
	global_load_dwordx4 v[80:83], v223, s[92:93] offset:768
	s_add_u32 s94, s88, 0x20000
	s_addc_u32 s95, s89, 0
	s_nop 0
	global_load_dwordx4 v[84:87], v223, s[94:95] offset:768
	s_add_u32 s92, s88, 0x30000
	s_addc_u32 s93, s89, 0
	s_nop 0
	global_load_dwordx4 v[88:91], v223, s[92:93] offset:768
	s_add_u32 s94, s88, 0x40000
	s_addc_u32 s95, s89, 0
	s_nop 0
	global_load_dwordx4 v[92:95], v223, s[94:95] offset:768
	s_add_u32 s92, s88, 0x50000
	s_addc_u32 s93, s89, 0
	s_nop 0
	global_load_dwordx4 v[96:99], v223, s[92:93] offset:768
	s_add_u32 s94, s88, 0x60000
	s_addc_u32 s95, s89, 0
	s_nop 0
	global_load_dwordx4 v[112:115], v223, s[94:95] offset:768
	s_add_u32 s92, s88, 0x70000
	s_addc_u32 s93, s89, 0
	s_nop 0
	global_load_dwordx4 v[116:119], v223, s[92:93] offset:768
	global_load_dwordx4 v[120:123], v223, s[90:91] offset:768
	s_add_u32 s94, s90, 0x10000
	s_addc_u32 s95, s91, 0
	s_nop 0
	global_load_dwordx4 v[124:127], v223, s[94:95] offset:768
	s_add_u32 s92, s90, 0x20000
	s_addc_u32 s93, s91, 0
	s_nop 0
	global_load_dwordx4 v[128:131], v223, s[92:93] offset:768
	s_add_u32 s94, s90, 0x30000
	s_addc_u32 s95, s91, 0
	s_nop 0
	global_load_dwordx4 v[132:135], v223, s[94:95] offset:768
	s_add_u32 s92, s90, 0x40000
	s_addc_u32 s93, s91, 0
	s_nop 0
	global_load_dwordx4 v[136:139], v223, s[92:93] offset:768
	s_add_u32 s94, s90, 0x50000
	s_addc_u32 s95, s91, 0
	s_nop 0
	global_load_dwordx4 v[140:143], v223, s[94:95] offset:768
	s_add_u32 s92, s90, 0x60000
	s_addc_u32 s93, s91, 0
	s_nop 0
	global_load_dwordx4 v[144:147], v223, s[92:93] offset:768
	s_add_u32 s94, s90, 0x70000
	s_addc_u32 s95, s91, 0
	s_nop 0
	global_load_dwordx4 v[148:151], v223, s[94:95] offset:768
	s_waitcnt vmcnt(24) lgkmcnt(0)
	ds_write_b128 v221, v[152:155]
	ds_write_b128 v221, v[156:159] offset:1152
	ds_write_b128 v221, v[160:163] offset:2304
	ds_write_b128 v221, v[164:167] offset:3456
	ds_write_b128 v221, v[168:171] offset:4608
	ds_write_b128 v221, v[172:175] offset:5760
	ds_write_b128 v221, v[176:179] offset:6912
	ds_write_b128 v221, v[180:183] offset:8064
	s_waitcnt lgkmcnt(0)
	ds_read_b128 v[152:155], v222
	ds_read_b128 v[156:159], v222 offset:32
	ds_read_b128 v[160:163], v222 offset:64
	ds_read_b128 v[164:167], v222 offset:96
	ds_read_b128 v[168:171], v222 offset:4608
	ds_read_b128 v[172:175], v222 offset:4640
	ds_read_b128 v[176:179], v222 offset:4672
	ds_read_b128 v[180:183], v222 offset:4704
	s_waitcnt vmcnt(16) lgkmcnt(0)
	ds_write_b128 v221, v[184:187]
	ds_write_b128 v221, v[188:191] offset:1152
	ds_write_b128 v221, v[192:195] offset:2304
	ds_write_b128 v221, v[196:199] offset:3456
	ds_write_b128 v221, v[200:203] offset:4608
	ds_write_b128 v221, v[204:207] offset:5760
	ds_write_b128 v221, v[212:215] offset:6912
	ds_write_b128 v221, v[216:219] offset:8064
	s_waitcnt lgkmcnt(0)
	ds_read_b128 v[184:187], v222
	ds_read_b128 v[188:191], v222 offset:32
	ds_read_b128 v[192:195], v222 offset:64
	ds_read_b128 v[196:199], v222 offset:96
	ds_read_b128 v[200:203], v222 offset:4608
	ds_read_b128 v[204:207], v222 offset:4640
	ds_read_b128 v[212:215], v222 offset:4672
	ds_read_b128 v[216:219], v222 offset:4704
	s_waitcnt lgkmcnt(0)
; DI f32x16 mfma32(bf16x8 a, bf16x8 b, f32x16 c) { return __builtin_amdgcn_mfma_f32_32x32x16_bf16(a, b, c, 0, 0, 0); }
; template <int EPI, int K, int LNI>
; DI void gemm_tail_unit(const Params& p, const bf16_t* __restrict__ A, const bf16_t* __restrict__ Bt, const int un, float* s_aux) {
;     ...
;     const bf16_t* ap = A + (size_t)(ROW0 + r) * K + w * KS + h * 8;
;     const bf16_t* bp = Bt + (size_t)(col0 + r) * K + w * KS + h * 8;
; #pragma unroll 8
;     for (int s = 0; s < KS / 16; ++s) {
;         const bf16x8 a0 = *(const bf16x8*)(ap + s * 16), a1 = *(const bf16x8*)(ap + (size_t)32 * K + s * 16);
;         const bf16x8 b0 = *(const bf16x8*)(bp + s * 16), b1 = *(const bf16x8*)(bp + (size_t)32 * K + s * 16);
;         acc[0][0] = mfma32(a0, b0, acc[0][0]); acc[0][1] = mfma32(a0, b1, acc[0][1]);
;         acc[1][0] = mfma32(a1, b0, acc[1][0]); acc[1][1] = mfma32(a1, b1, acc[1][1]);
;     }
	v_mfma_f32_32x32x16_bf16 v[0:15], v[152:155], v[184:187], v[0:15]
	v_mfma_f32_32x32x16_bf16 v[16:31], v[152:155], v[200:203], v[16:31]
	v_mfma_f32_32x32x16_bf16 v[32:47], v[168:171], v[184:187], v[32:47]
	v_mfma_f32_32x32x16_bf16 v[48:63], v[168:171], v[200:203], v[48:63]
	v_mfma_f32_32x32x16_bf16 v[0:15], v[156:159], v[188:191], v[0:15]
	v_mfma_f32_32x32x16_bf16 v[16:31], v[156:159], v[204:207], v[16:31]
	v_mfma_f32_32x32x16_bf16 v[32:47], v[172:175], v[188:191], v[32:47]
	v_mfma_f32_32x32x16_bf16 v[48:63], v[172:175], v[204:207], v[48:63]
	v_mfma_f32_32x32x16_bf16 v[0:15], v[160:163], v[192:195], v[0:15]
	v_mfma_f32_32x32x16_bf16 v[16:31], v[160:163], v[212:215], v[16:31]
	v_mfma_f32_32x32x16_bf16 v[32:47], v[176:179], v[192:195], v[32:47]
	v_mfma_f32_32x32x16_bf16 v[48:63], v[176:179], v[212:215], v[48:63]
	v_mfma_f32_32x32x16_bf16 v[0:15], v[164:167], v[196:199], v[0:15]
	v_mfma_f32_32x32x16_bf16 v[16:31], v[164:167], v[216:219], v[16:31]
	v_mfma_f32_32x32x16_bf16 v[32:47], v[180:183], v[196:199], v[32:47]
	v_mfma_f32_32x32x16_bf16 v[48:63], v[180:183], v[216:219], v[48:63]
	global_load_dwordx4 v[152:155], v223, s[88:89] offset:896
	s_add_u32 s92, s88, 0x10000
	s_addc_u32 s93, s89, 0
	s_nop 0
	global_load_dwordx4 v[156:159], v223, s[92:93] offset:896
	s_add_u32 s94, s88, 0x20000
	s_addc_u32 s95, s89, 0
	s_nop 0
	global_load_dwordx4 v[160:163], v223, s[94:95] offset:896
	s_add_u32 s92, s88, 0x30000
	s_addc_u32 s93, s89, 0
	s_nop 0
	global_load_dwordx4 v[164:167], v223, s[92:93] offset:896
	s_add_u32 s94, s88, 0x40000
	s_addc_u32 s95, s89, 0
	s_nop 0
	global_load_dwordx4 v[168:171], v223, s[94:95] offset:896
	s_add_u32 s92, s88, 0x50000
	s_addc_u32 s93, s89, 0
	s_nop 0
	global_load_dwordx4 v[172:175], v223, s[92:93] offset:896
	s_add_u32 s94, s88, 0x60000
	s_addc_u32 s95, s89, 0
	s_nop 0
	global_load_dwordx4 v[176:179], v223, s[94:95] offset:896
	s_add_u32 s92, s88, 0x70000
	s_addc_u32 s93, s89, 0
	s_nop 0
	global_load_dwordx4 v[180:183], v223, s[92:93] offset:896
	global_load_dwordx4 v[184:187], v223, s[90:91] offset:896
	s_add_u32 s94, s90, 0x10000
	s_addc_u32 s95, s91, 0
	s_nop 0
	global_load_dwordx4 v[188:191], v223, s[94:95] offset:896
	s_add_u32 s92, s90, 0x20000
	s_addc_u32 s93, s91, 0
	s_nop 0
	global_load_dwordx4 v[192:195], v223, s[92:93] offset:896
	s_add_u32 s94, s90, 0x30000
	s_addc_u32 s95, s91, 0
	s_nop 0
	global_load_dwordx4 v[196:199], v223, s[94:95] offset:896
	s_add_u32 s92, s90, 0x40000
	s_addc_u32 s93, s91, 0
	s_nop 0
	global_load_dwordx4 v[200:203], v223, s[92:93] offset:896
	s_add_u32 s94, s90, 0x50000
	s_addc_u32 s95, s91, 0
	s_nop 0
	global_load_dwordx4 v[204:207], v223, s[94:95] offset:896
	s_add_u32 s92, s90, 0x60000
	s_addc_u32 s93, s91, 0
	s_nop 0
	global_load_dwordx4 v[212:215], v223, s[92:93] offset:896
	s_add_u32 s94, s90, 0x70000
	s_addc_u32 s95, s91, 0
	s_nop 0
	global_load_dwordx4 v[216:219], v223, s[94:95] offset:896
	s_waitcnt vmcnt(24) lgkmcnt(0)
	ds_write_b128 v221, v[76:79]
	ds_write_b128 v221, v[80:83] offset:1152
	ds_write_b128 v221, v[84:87] offset:2304
	ds_write_b128 v221, v[88:91] offset:3456
	ds_write_b128 v221, v[92:95] offset:4608
	ds_write_b128 v221, v[96:99] offset:5760
	ds_write_b128 v221, v[112:115] offset:6912
	ds_write_b128 v221, v[116:119] offset:8064
	s_waitcnt lgkmcnt(0)
	ds_read_b128 v[76:79], v222
	ds_read_b128 v[80:83], v222 offset:32
	ds_read_b128 v[84:87], v222 offset:64
	ds_read_b128 v[88:91], v222 offset:96
	ds_read_b128 v[92:95], v222 offset:4608
	ds_read_b128 v[96:99], v222 offset:4640
	ds_read_b128 v[112:115], v222 offset:4672
	ds_read_b128 v[116:119], v222 offset:4704
	s_waitcnt vmcnt(16) lgkmcnt(0)
	ds_write_b128 v221, v[120:123]
	ds_write_b128 v221, v[124:127] offset:1152
	ds_write_b128 v221, v[128:131] offset:2304
	ds_write_b128 v221, v[132:135] offset:3456
	ds_write_b128 v221, v[136:139] offset:4608
	ds_write_b128 v221, v[140:143] offset:5760
	ds_write_b128 v221, v[144:147] offset:6912
	ds_write_b128 v221, v[148:151] offset:8064
	s_waitcnt lgkmcnt(0)
	ds_read_b128 v[120:123], v222
	ds_read_b128 v[124:127], v222 offset:32
	ds_read_b128 v[128:131], v222 offset:64
	ds_read_b128 v[132:135], v222 offset:96
	ds_read_b128 v[136:139], v222 offset:4608
	ds_read_b128 v[140:143], v222 offset:4640
	ds_read_b128 v[144:147], v222 offset:4672
	ds_read_b128 v[148:151], v222 offset:4704
	s_waitcnt lgkmcnt(0)
	v_mfma_f32_32x32x16_bf16 v[0:15], v[76:79], v[120:123], v[0:15]
	v_mfma_f32_32x32x16_bf16 v[16:31], v[76:79], v[136:139], v[16:31]
	v_mfma_f32_32x32x16_bf16 v[32:47], v[92:95], v[120:123], v[32:47]
	v_mfma_f32_32x32x16_bf16 v[48:63], v[92:95], v[136:139], v[48:63]
	v_mfma_f32_32x32x16_bf16 v[0:15], v[80:83], v[124:127], v[0:15]
	v_mfma_f32_32x32x16_bf16 v[16:31], v[80:83], v[140:143], v[16:31]
	v_mfma_f32_32x32x16_bf16 v[32:47], v[96:99], v[124:127], v[32:47]
	v_mfma_f32_32x32x16_bf16 v[48:63], v[96:99], v[140:143], v[48:63]
	v_mfma_f32_32x32x16_bf16 v[0:15], v[84:87], v[128:131], v[0:15]
	v_mfma_f32_32x32x16_bf16 v[16:31], v[84:87], v[144:147], v[16:31]
	v_mfma_f32_32x32x16_bf16 v[32:47], v[112:115], v[128:131], v[32:47]
	v_mfma_f32_32x32x16_bf16 v[48:63], v[112:115], v[144:147], v[48:63]
	v_mfma_f32_32x32x16_bf16 v[0:15], v[88:91], v[132:135], v[0:15]
	v_mfma_f32_32x32x16_bf16 v[16:31], v[88:91], v[148:151], v[16:31]
	v_mfma_f32_32x32x16_bf16 v[32:47], v[116:119], v[132:135], v[32:47]
	v_mfma_f32_32x32x16_bf16 v[48:63], v[116:119], v[148:151], v[48:63]
	s_waitcnt vmcnt(8) lgkmcnt(0)
	ds_write_b128 v221, v[152:155]
	ds_write_b128 v221, v[156:159] offset:1152
	ds_write_b128 v221, v[160:163] offset:2304
	ds_write_b128 v221, v[164:167] offset:3456
	ds_write_b128 v221, v[168:171] offset:4608
	ds_write_b128 v221, v[172:175] offset:5760
	ds_write_b128 v221, v[176:179] offset:6912
	ds_write_b128 v221, v[180:183] offset:8064
	s_waitcnt lgkmcnt(0)
; DI f32x16 mfma32(bf16x8 a, bf16x8 b, f32x16 c) { return __builtin_amdgcn_mfma_f32_32x32x16_bf16(a, b, c, 0, 0, 0); }
; DI float ex2(float x) { return __builtin_amdgcn_exp2f(x); }
; template <int EPI, int K, int LNI>
; DI void gemm_tail_unit(const Params& p, const bf16_t* __restrict__ A, const bf16_t* __restrict__ Bt, const int un, float* s_aux) {
;     ...
;         acc[0][0] = mfma32(a0, b0, acc[0][0]); acc[0][1] = mfma32(a0, b1, acc[0][1]);
;         acc[1][0] = mfma32(a1, b0, acc[1][0]); acc[1][1] = mfma32(a1, b1, acc[1][1]);
;     }
;     float* red = (float*)dsm;
; #pragma unroll
;     for (int i = 0; i < 2; ++i)
; #pragma unroll
;         for (int j = 0; j < 2; ++j)
; #pragma unroll
;             for (int reg = 0; reg < 16; ++reg) red[((w * 4 + i * 2 + j) * 16 + reg) * 64 + lane] = acc[i][j][reg];
;     ...
;             const int lrow0 = i * 32 + 8 * g + 4 * h;
;             f32x2 rs[4]; float lng = 1.f, lnb = 0.f;
;             if (EPI == EPI_E5) {
;                 lng = log2f(1.f - ex2(-5.f - (float)((col0 >> 8) & 3)));
;                 const int idx_ = (((ROW0 + lrow0) % LT) + 48) & 63;
; #pragma unroll
;                 for (int e = 0; e < 4; ++e) rs[e] = (f32x2){ex2(lng * (float)(idx_ + e + 1)), 0.0625f * ex2(lng * (float)(63 - idx_ - e))};
;             }
;             if (EPI == EPI_RESID && LNI >= 0) {
;                 const f32x2* st_ = (const f32x2*)((unsigned char*)p.out + OFFO_STATS) + ROW0 + lrow0;
; #pragma unroll
;                 for (int e = 0; e < 4; ++e) rs[e] = st_[e];
;                 lng = p.ln_g[(LNI < 0 ? 0 : LNI) * 1024 + col0 + j * 32 + r]; lnb = p.ln_b[(LNI < 0 ? 0 : LNI) * 1024 + col0 + j * 32 + r];
	ds_read_b128 v[152:155], v222
	ds_read_b128 v[156:159], v222 offset:32
	ds_read_b128 v[160:163], v222 offset:64
	ds_read_b128 v[164:167], v222 offset:96
	ds_read_b128 v[168:171], v222 offset:4608
	ds_read_b128 v[172:175], v222 offset:4640
	ds_read_b128 v[176:179], v222 offset:4672
	ds_read_b128 v[180:183], v222 offset:4704
	s_waitcnt vmcnt(0) lgkmcnt(0)
	ds_write_b128 v221, v[184:187]
	ds_write_b128 v221, v[188:191] offset:1152
	ds_write_b128 v221, v[192:195] offset:2304
	ds_write_b128 v221, v[196:199] offset:3456
	ds_write_b128 v221, v[200:203] offset:4608
	ds_write_b128 v221, v[204:207] offset:5760
	ds_write_b128 v221, v[212:215] offset:6912
	ds_write_b128 v221, v[216:219] offset:8064
	s_waitcnt lgkmcnt(0)
	ds_read_b128 v[184:187], v222
	ds_read_b128 v[188:191], v222 offset:32
	ds_read_b128 v[192:195], v222 offset:64
	ds_read_b128 v[196:199], v222 offset:96
	ds_read_b128 v[200:203], v222 offset:4608
	ds_read_b128 v[204:207], v222 offset:4640
	ds_read_b128 v[212:215], v222 offset:4672
	ds_read_b128 v[216:219], v222 offset:4704
	s_waitcnt lgkmcnt(0)
	v_mfma_f32_32x32x16_bf16 v[0:15], v[152:155], v[184:187], v[0:15]
	v_mfma_f32_32x32x16_bf16 v[16:31], v[152:155], v[200:203], v[16:31]
	v_mfma_f32_32x32x16_bf16 v[32:47], v[168:171], v[184:187], v[32:47]
	v_mfma_f32_32x32x16_bf16 v[48:63], v[168:171], v[200:203], v[48:63]
	v_mfma_f32_32x32x16_bf16 v[0:15], v[156:159], v[188:191], v[0:15]
	v_mfma_f32_32x32x16_bf16 v[16:31], v[156:159], v[204:207], v[16:31]
	v_mfma_f32_32x32x16_bf16 v[32:47], v[172:175], v[188:191], v[32:47]
	v_mfma_f32_32x32x16_bf16 v[48:63], v[172:175], v[204:207], v[48:63]
	v_mfma_f32_32x32x16_bf16 v[0:15], v[160:163], v[192:195], v[0:15]
	v_mfma_f32_32x32x16_bf16 v[16:31], v[160:163], v[212:215], v[16:31]
	v_mfma_f32_32x32x16_bf16 v[32:47], v[176:179], v[192:195], v[32:47]
	v_mfma_f32_32x32x16_bf16 v[48:63], v[176:179], v[212:215], v[48:63]
	v_mfma_f32_32x32x16_bf16 v[0:15], v[164:167], v[196:199], v[0:15]
	v_mfma_f32_32x32x16_bf16 v[16:31], v[164:167], v[216:219], v[16:31]
	v_mfma_f32_32x32x16_bf16 v[32:47], v[180:183], v[196:199], v[32:47]
	v_mfma_f32_32x32x16_bf16 v[48:63], v[180:183], v[216:219], v[48:63]
	s_nop 7
	v_and_b32_e32 v64, 63, v71
	v_lshl_add_u32 v64, v64, 2, 0
	v_lshl_add_u32 v66, v72, 14, v64
	s_nop 2
	ds_write2st64_b32 v66, v0, v1 offset1:1
	ds_write2st64_b32 v66, v2, v3 offset0:2 offset1:3
	ds_write2st64_b32 v66, v4, v5 offset0:4 offset1:5
	ds_write2st64_b32 v66, v6, v7 offset0:6 offset1:7
	ds_write2st64_b32 v66, v8, v9 offset0:8 offset1:9
	ds_write2st64_b32 v66, v10, v11 offset0:10 offset1:11
	ds_write2st64_b32 v66, v12, v13 offset0:12 offset1:13
	ds_write2st64_b32 v66, v14, v15 offset0:14 offset1:15
	ds_write2st64_b32 v66, v16, v17 offset0:16 offset1:17
	ds_write2st64_b32 v66, v18, v19 offset0:18 offset1:19
	ds_write2st64_b32 v66, v20, v21 offset0:20 offset1:21
	ds_write2st64_b32 v66, v22, v23 offset0:22 offset1:23
	ds_write2st64_b32 v66, v24, v25 offset0:24 offset1:25
	ds_write2st64_b32 v66, v26, v27 offset0:26 offset1:27
	ds_write2st64_b32 v66, v28, v29 offset0:28 offset1:29
	ds_write2st64_b32 v66, v30, v31 offset0:30 offset1:31
	ds_write2st64_b32 v66, v32, v33 offset0:32 offset1:33
	ds_write2st64_b32 v66, v34, v35 offset0:34 offset1:35
	ds_write2st64_b32 v66, v36, v37 offset0:36 offset1:37
	ds_write2st64_b32 v66, v38, v39 offset0:38 offset1:39
	ds_write2st64_b32 v66, v40, v41 offset0:40 offset1:41
	ds_write2st64_b32 v66, v42, v43 offset0:42 offset1:43
	ds_write2st64_b32 v66, v44, v45 offset0:44 offset1:45
	ds_write2st64_b32 v66, v46, v47 offset0:46 offset1:47
	ds_write2st64_b32 v66, v48, v49 offset0:48 offset1:49
	ds_write2st64_b32 v66, v50, v51 offset0:50 offset1:51
	ds_write2st64_b32 v66, v52, v53 offset0:52 offset1:53
	ds_write2st64_b32 v66, v54, v55 offset0:54 offset1:55
	ds_write2st64_b32 v66, v56, v57 offset0:56 offset1:57
	ds_write2st64_b32 v66, v58, v59 offset0:58 offset1:59
	ds_write2st64_b32 v66, v60, v61 offset0:60 offset1:61
	ds_write2st64_b32 v66, v62, v63 offset0:62 offset1:63
	v_ashrrev_i32_e32 v0, 7, v71
	v_lshlrev_b32_e32 v1, 1, v72
	v_and_b32_e32 v34, 2, v1
	v_lshlrev_b32_e32 v35, 12, v0
	v_ashrrev_i32_e32 v1, 3, v71
	v_lshlrev_b32_e32 v0, 5, v0
	s_lshl_b32 s6, s15, 6
	v_and_b32_e32 v1, 0xffffffe0, v1
	v_lshrrev_b32_e32 v2, 3, v71
	v_and_b32_e32 v0, 32, v0
	v_and_or_b32 v36, v2, 4, v1
	v_or3_b32 v0, s6, v0, v70
	v_ashrrev_i32_e32 v1, 31, v0
	v_lshl_or_b32 v24, v34, 3, v36
	v_lshlrev_b64 v[4:5], 2, v[0:1]
	v_lshl_or_b32 v37, v34, 10, v35
	v_ashrrev_i32_e32 v25, 31, v24
	v_lshl_add_u64 v[0:1], s[62:63], 0, v[4:5]
	v_lshl_add_u64 v[2:3], s[64:65], 0, v[4:5]
	v_add_u32_e32 v32, v64, v37
	v_lshl_add_u64 v[4:5], s[16:17], 0, v[4:5]
	v_lshl_add_u64 v[10:11], v[24:25], 3, s[4:5]
	v_lshlrev_b64 v[24:25], 12, v[24:25]
	s_waitcnt lgkmcnt(0)
	s_barrier
; DI float ex2(float x) { return __builtin_amdgcn_exp2f(x); }
;     ...
;         float* d = (float*)(p.ws + OFF_H) + (size_t)row0 * 1024 + col;
; #pragma unroll
;         for (int e = 0; e < 4; ++e) {
;             float hprev = d[(size_t)e * 1024];
;             if (LNI >= 0) hprev = (hprev - rs[e][0]) * rs[e][1] * gg + bb;
;             d[(size_t)e * 1024] = ALPHA * hprev + v[e];
; template <int EPI, int K, int LNI>
; DI void gemm_tail_unit(const Params& p, const bf16_t* __restrict__ A, const bf16_t* __restrict__ Bt, const int un, float* s_aux) {
;     ...
;     {
;         const int tile = w >> 1, i = tile >> 1, j = tile & 1;
; #pragma unroll
;         for (int gg = 0; gg < 2; ++gg) {
;             const int g = 2 * (w & 1) + gg;
;             float v[4];
; #pragma unroll
;             for (int e = 0; e < 4; ++e) {
;                 float sacc = 0.f;
; #pragma unroll
;                 for (int wv = 0; wv < 8; ++wv) sacc += red[((wv * 4 + tile) * 16 + 4 * g + e) * 64 + lane];
;                 v[e] = sacc;
;             }
;             const int lrow0 = i * 32 + 8 * g + 4 * h;
;             f32x2 rs[4]; float lng = 1.f, lnb = 0.f;
;             if (EPI == EPI_E5) {
;                 lng = log2f(1.f - ex2(-5.f - (float)((col0 >> 8) & 3)));
;                 const int idx_ = (((ROW0 + lrow0) % LT) + 48) & 63;
; #pragma unroll
;                 for (int e = 0; e < 4; ++e) rs[e] = (f32x2){ex2(lng * (float)(idx_ + e + 1)), 0.0625f * ex2(lng * (float)(63 - idx_ - e))};
;             }
;             if (EPI == EPI_RESID && LNI >= 0) {
;                 const f32x2* st_ = (const f32x2*)((unsigned char*)p.out + OFFO_STATS) + ROW0 + lrow0;
; #pragma unroll
;                 for (int e = 0; e < 4; ++e) rs[e] = st_[e];
;                 lng = p.ln_g[(LNI < 0 ? 0 : LNI) * 1024 + col0 + j * 32 + r]; lnb = p.ln_b[(LNI < 0 ? 0 : LNI) * 1024 + col0 + j * 32 + r];
;             }
;             epi_store<EPI, LNI>(p, ROW0 + lrow0, col0 + j * 32 + r, lrow0, v, s_aux, rs, lng, lnb);
	ds_read2st64_b32 v[14:15], v32 offset1:1
	ds_read2st64_b32 v[16:17], v32 offset0:64 offset1:65
	v_lshl_add_u64 v[24:25], v[4:5], 0, v[24:25]
	v_add_co_u32_e32 v26, vcc, s13, v24
	ds_read2st64_b32 v[18:19], v32 offset0:66 offset1:67
	ds_read2st64_b32 v[20:21], v32 offset0:2 offset1:3
	v_addc_co_u32_e32 v27, vcc, 0, v25, vcc
	ds_read2st64_b32 v[22:23], v32 offset0:128 offset1:129
	v_add_co_u32_e32 v24, vcc, s14, v24
	s_waitcnt lgkmcnt(4)
	v_add_f32_e32 v6, 0, v14
	v_addc_co_u32_e32 v25, vcc, 0, v25, vcc
	s_waitcnt lgkmcnt(3)
	v_add_f32_e32 v14, v6, v16
	global_load_dwordx4 v[6:9], v[10:11], off offset:16
	s_nop 0
	global_load_dwordx4 v[10:13], v[10:11], off
	s_nop 0
	global_load_dword v16, v[0:1], off
	global_load_dword v38, v[2:3], off
	global_load_dword v39, v[26:27], off offset:-4096
	ds_read2st64_b32 v[28:29], v32 offset0:192 offset1:193
	ds_read2st64_b32 v[30:31], v32 offset0:194 offset1:195
	ds_read2st64_b32 v[32:33], v32 offset0:130 offset1:131
	global_load_dword v40, v[24:25], off offset:-4096
	global_load_dword v43, v[24:25], off
	s_waitcnt lgkmcnt(3)
	v_add_f32_e32 v14, v14, v22
	global_load_dword v22, v[26:27], off
	v_add_f32_e32 v20, 0, v20
	s_waitcnt lgkmcnt(2)
	v_add_f32_e32 v14, v14, v28
	v_add_u32_e32 v28, 0x10000, v64
	v_add_u32_e32 v42, 0x14000, v64
	v_add_u32_e32 v45, 0x18000, v64
	v_add_u32_e32 v47, 0x1c000, v64
	v_or_b32_e32 v49, 0x100, v37
	v_add_f32_e32 v15, 0, v15
	v_add_f32_e32 v18, v20, v18
	v_add_u32_e32 v41, v28, v37
	v_add_u32_e32 v44, v42, v37
	v_add_u32_e32 v46, v45, v37
	v_add_u32_e32 v48, v47, v37
	v_add_u32_e32 v50, v28, v49
	v_add_u32_e32 v51, v42, v49
	v_add_u32_e32 v52, v45, v49
	v_add_u32_e32 v49, v47, v49
	v_add_f32_e32 v15, v15, v17
	s_waitcnt lgkmcnt(0)
	v_add_f32_e32 v18, v18, v32
	ds_read_b32 v41, v41
	ds_read_b32 v44, v44
	ds_read_b32 v46, v46
	ds_read_b32 v48, v48
	ds_read_b32 v50, v50
	ds_read_b32 v51, v51
	ds_read_b32 v52, v52
	ds_read_b32 v49, v49
	v_add_f32_e32 v15, v15, v23
	v_or_b32_e32 v17, 0x200, v37
	v_add_f32_e32 v18, v18, v30
	v_or_b32_e32 v30, 0x300, v37
	s_waitcnt lgkmcnt(7)
	v_add_f32_e32 v14, v14, v41
	v_add_f32_e32 v15, v15, v29
	v_add_u32_e32 v20, v28, v17
	v_add_u32_e32 v23, v42, v17
	v_add_u32_e32 v29, v45, v17
	v_add_u32_e32 v17, v47, v17
	v_add_u32_e32 v32, v28, v30
	v_add_u32_e32 v37, v42, v30
	v_add_u32_e32 v41, v45, v30
	v_add_u32_e32 v30, v47, v30
	ds_read_b32 v20, v20
	ds_read_b32 v23, v23
	ds_read_b32 v29, v29
	ds_read_b32 v17, v17
	ds_read_b32 v32, v32
	ds_read_b32 v37, v37
	ds_read_b32 v41, v41
	ds_read_b32 v30, v30
	s_waitcnt lgkmcnt(7)
	v_add_f32_e32 v18, v18, v20
	s_waitcnt lgkmcnt(6)
	v_add_f32_e32 v18, v18, v23
	s_waitcnt lgkmcnt(5)
	v_add_f32_e32 v18, v18, v29
	v_add_f32_e32 v14, v14, v44
	s_waitcnt lgkmcnt(4)
	v_add_f32_e32 v17, v18, v17
	v_add_f32_e32 v18, 0, v21
	v_add_f32_e32 v14, v14, v46
	v_add_f32_e32 v18, v18, v19
	v_add_f32_e32 v14, v14, v48
	v_add_f32_e32 v15, v15, v50
	v_add_f32_e32 v18, v18, v33
	v_add_f32_e32 v15, v15, v51
	v_add_f32_e32 v18, v18, v31
	v_add_f32_e32 v15, v15, v52
	s_waitcnt lgkmcnt(3)
	v_add_f32_e32 v18, v18, v32
	v_add_f32_e32 v15, v15, v49
	s_waitcnt lgkmcnt(2)
	v_add_f32_e32 v18, v18, v37
	s_waitcnt lgkmcnt(1)
	v_add_f32_e32 v18, v18, v41
	s_waitcnt lgkmcnt(0)
	v_add_f32_e32 v18, v18, v30
	s_add_i32 s15, s15, s58
	s_add_i32 s3, s3, s8
	s_cmp_lt_i32 s15, 16
	s_waitcnt vmcnt(3)
	v_sub_f32_e32 v10, v39, v10
	v_mul_f32_e32 v10, v11, v10
	s_waitcnt vmcnt(2)
	v_sub_f32_e32 v6, v40, v6
	v_mul_f32_e32 v6, v7, v6
	v_fma_f32 v10, v16, v10, v38
	v_fma_f32 v6, v16, v6, v38
	v_fmac_f32_e32 v14, 0x3fb504f3, v10
	s_waitcnt vmcnt(0)
; DI float ex2(float x) { return __builtin_amdgcn_exp2f(x); }
;     ...
;         float* d = (float*)(p.ws + OFF_H) + (size_t)row0 * 1024 + col;
; #pragma unroll
;         for (int e = 0; e < 4; ++e) {
;             float hprev = d[(size_t)e * 1024];
;             if (LNI >= 0) hprev = (hprev - rs[e][0]) * rs[e][1] * gg + bb;
;             d[(size_t)e * 1024] = ALPHA * hprev + v[e];
; template <int EPI, int K, int LNI>
; DI void gemm_tail_unit(const Params& p, const bf16_t* __restrict__ A, const bf16_t* __restrict__ Bt, const int un, float* s_aux) {
;     ...
;     {
;         const int tile = w >> 1, i = tile >> 1, j = tile & 1;
; #pragma unroll
;         for (int gg = 0; gg < 2; ++gg) {
;             const int g = 2 * (w & 1) + gg;
;             float v[4];
; #pragma unroll
;             for (int e = 0; e < 4; ++e) {
;                 float sacc = 0.f;
; #pragma unroll
;                 for (int wv = 0; wv < 8; ++wv) sacc += red[((wv * 4 + tile) * 16 + 4 * g + e) * 64 + lane];
;                 v[e] = sacc;
;             }
;             const int lrow0 = i * 32 + 8 * g + 4 * h;
;             f32x2 rs[4]; float lng = 1.f, lnb = 0.f;
;             if (EPI == EPI_E5) {
;                 lng = log2f(1.f - ex2(-5.f - (float)((col0 >> 8) & 3)));
;                 const int idx_ = (((ROW0 + lrow0) % LT) + 48) & 63;
; #pragma unroll
;                 for (int e = 0; e < 4; ++e) rs[e] = (f32x2){ex2(lng * (float)(idx_ + e + 1)), 0.0625f * ex2(lng * (float)(63 - idx_ - e))};
;             }
;             if (EPI == EPI_RESID && LNI >= 0) {
;                 const f32x2* st_ = (const f32x2*)((unsigned char*)p.out + OFFO_STATS) + ROW0 + lrow0;
; #pragma unroll
;                 for (int e = 0; e < 4; ++e) rs[e] = st_[e];
;                 lng = p.ln_g[(LNI < 0 ? 0 : LNI) * 1024 + col0 + j * 32 + r]; lnb = p.ln_b[(LNI < 0 ? 0 : LNI) * 1024 + col0 + j * 32 + r];
;             }
;             epi_store<EPI, LNI>(p, ROW0 + lrow0, col0 + j * 32 + r, lrow0, v, s_aux, rs, lng, lnb);
	v_sub_f32_e32 v10, v22, v12
	v_fmac_f32_e32 v17, 0x3fb504f3, v6
	v_sub_f32_e32 v6, v43, v8
	v_mul_f32_e32 v10, v13, v10
	v_mul_f32_e32 v6, v9, v6
	v_fma_f32 v10, v16, v10, v38
	v_fmac_f32_e32 v38, v16, v6
	v_or_b32_e32 v6, 1, v34
	v_fmac_f32_e32 v15, 0x3fb504f3, v10
	v_lshl_or_b32 v29, v6, 10, v35
	v_lshl_or_b32 v22, v6, 3, v36
	global_store_dword v[26:27], v14, off offset:-4096
	global_store_dword v[26:27], v15, off
	v_add_u32_e32 v26, v64, v29
	v_ashrrev_i32_e32 v23, 31, v22
	v_fmac_f32_e32 v18, 0x3fb504f3, v38
	ds_read2st64_b32 v[14:15], v26 offset1:1
	v_lshl_add_u64 v[10:11], v[22:23], 3, s[4:5]
	v_lshlrev_b64 v[22:23], 12, v[22:23]
	global_store_dword v[24:25], v17, off offset:-4096
	global_store_dword v[24:25], v18, off
	v_lshl_add_u64 v[4:5], v[4:5], 0, v[22:23]
	ds_read2st64_b32 v[16:17], v26 offset0:64 offset1:65
	ds_read2st64_b32 v[18:19], v26 offset0:66 offset1:67
	ds_read2st64_b32 v[20:21], v26 offset0:2 offset1:3
	global_load_dwordx4 v[6:9], v[10:11], off offset:16
	s_nop 0
	global_load_dwordx4 v[10:13], v[10:11], off
	v_add_co_u32_e32 v22, vcc, s13, v4
	s_waitcnt lgkmcnt(3)
	v_add_f32_e32 v14, 0, v14
	v_addc_co_u32_e32 v23, vcc, 0, v5, vcc
	global_load_dword v30, v[22:23], off offset:-4096
	global_load_dword v31, v[0:1], off
	global_load_dword v32, v[2:3], off
	s_waitcnt lgkmcnt(2)
	v_add_f32_e32 v14, v14, v16
	global_load_dword v16, v[22:23], off
	ds_read2st64_b32 v[0:1], v26 offset0:128 offset1:129
	v_add_co_u32_e32 v2, vcc, s14, v4
	v_or_b32_e32 v37, 0x100, v29
	s_nop 0
	v_addc_co_u32_e32 v3, vcc, 0, v5, vcc
	global_load_dword v33, v[2:3], off offset:-4096
	ds_read2st64_b32 v[4:5], v26 offset0:192 offset1:193
	ds_read2st64_b32 v[24:25], v26 offset0:194 offset1:195
	ds_read2st64_b32 v[26:27], v26 offset0:130 offset1:131
	s_waitcnt lgkmcnt(3)
	v_add_f32_e32 v0, v14, v0
	global_load_dword v14, v[2:3], off
	s_waitcnt lgkmcnt(2)
	v_add_f32_e32 v0, v0, v4
	v_add_u32_e32 v4, v28, v29
	v_add_u32_e32 v34, v42, v29
	v_add_u32_e32 v35, v45, v29
	v_add_u32_e32 v36, v47, v29
	v_add_u32_e32 v38, v28, v37
	v_add_u32_e32 v39, v42, v37
	v_add_u32_e32 v40, v45, v37
	v_add_u32_e32 v37, v47, v37
	ds_read_b32 v4, v4
	ds_read_b32 v34, v34
	ds_read_b32 v35, v35
	ds_read_b32 v36, v36
	ds_read_b32 v38, v38
	ds_read_b32 v39, v39
	ds_read_b32 v40, v40
	ds_read_b32 v37, v37
	s_waitcnt lgkmcnt(7)
	v_add_f32_e32 v0, v0, v4
	v_add_f32_e32 v4, 0, v15
	v_add_f32_e32 v4, v4, v17
	v_add_f32_e32 v1, v4, v1
	v_add_f32_e32 v1, v1, v5
	v_add_f32_e32 v5, 0, v20
	v_add_f32_e32 v5, v5, v18
	s_waitcnt lgkmcnt(6)
	v_add_f32_e32 v0, v0, v34
	v_or_b32_e32 v4, 0x200, v29
	v_add_f32_e32 v5, v5, v26
	v_or_b32_e32 v20, 0x300, v29
	s_waitcnt lgkmcnt(5)
	v_add_f32_e32 v0, v0, v35
	v_add_f32_e32 v5, v5, v24
	v_add_u32_e32 v15, v28, v4
	v_add_u32_e32 v17, v42, v4
	v_add_u32_e32 v18, v45, v4
	v_add_u32_e32 v4, v47, v4
	v_add_u32_e32 v24, v28, v20
	v_add_u32_e32 v26, v42, v20
	v_add_u32_e32 v28, v45, v20
	v_add_u32_e32 v20, v47, v20
	s_waitcnt lgkmcnt(4)
	v_add_f32_e32 v0, v0, v36
	ds_read_b32 v15, v15
	ds_read_b32 v17, v17
	ds_read_b32 v18, v18
	ds_read_b32 v4, v4
	ds_read_b32 v24, v24
	ds_read_b32 v26, v26
	ds_read_b32 v28, v28
	ds_read_b32 v20, v20
	s_waitcnt lgkmcnt(7)
	v_add_f32_e32 v5, v5, v15
	v_add_f32_e32 v1, v1, v38
	s_waitcnt lgkmcnt(6)
	v_add_f32_e32 v5, v5, v17
	v_add_f32_e32 v1, v1, v39
	s_waitcnt lgkmcnt(5)
	v_add_f32_e32 v5, v5, v18
	v_add_f32_e32 v1, v1, v40
	s_waitcnt lgkmcnt(4)
	v_add_f32_e32 v4, v5, v4
	v_add_f32_e32 v5, 0, v21
	v_add_f32_e32 v1, v1, v37
	v_add_f32_e32 v5, v5, v19
	v_add_f32_e32 v5, v5, v27
	v_add_f32_e32 v5, v5, v25
	s_waitcnt lgkmcnt(3)
	v_add_f32_e32 v5, v5, v24
	s_waitcnt lgkmcnt(2)
	v_add_f32_e32 v5, v5, v26
	s_waitcnt lgkmcnt(1)
	v_add_f32_e32 v5, v5, v28
	s_waitcnt lgkmcnt(0)
	v_add_f32_e32 v5, v5, v20
	s_waitcnt vmcnt(5)
	v_sub_f32_e32 v10, v30, v10
	v_mul_f32_e32 v10, v11, v10
	s_waitcnt vmcnt(3)
	v_fma_f32 v10, v31, v10, v32
	v_fmac_f32_e32 v0, 0x3fb504f3, v10
	global_store_dword v[22:23], v0, off offset:-4096
	s_waitcnt vmcnt(3)
	v_sub_f32_e32 v0, v16, v12
	v_mul_f32_e32 v0, v13, v0
	v_fma_f32 v0, v31, v0, v32
	v_fmac_f32_e32 v1, 0x3fb504f3, v0
	global_store_dword v[22:23], v1, off
	s_waitcnt vmcnt(3)
	v_sub_f32_e32 v0, v33, v6
	v_mul_f32_e32 v0, v7, v0
	v_fma_f32 v0, v31, v0, v32
	v_fmac_f32_e32 v4, 0x3fb504f3, v0
	s_waitcnt vmcnt(2)
	v_sub_f32_e32 v0, v14, v8
	v_mul_f32_e32 v0, v9, v0
	v_fmac_f32_e32 v32, v31, v0
	v_fmac_f32_e32 v5, 0x3fb504f3, v32
	global_store_dword v[2:3], v4, off offset:-4096
	global_store_dword v[2:3], v5, off
	s_barrier
	s_cbranch_scc1 .LBB0_1013

; DI f32x16 mfma32(bf16x8 a, bf16x8 b, f32x16 c) { return __builtin_amdgcn_mfma_f32_32x32x16_bf16(a, b, c, 0, 0, 0); }
; template <int EPI, int K, int LNI>
; DI void gemm_tail_unit(const Params& p, const bf16_t* __restrict__ A, const bf16_t* __restrict__ Bt, const int un, float* s_aux) {
;     ...
;     const bf16_t* ap = A + (size_t)(ROW0 + r) * K + w * KS + h * 8;
;     const bf16_t* bp = Bt + (size_t)(col0 + r) * K + w * KS + h * 8;
; #pragma unroll 8
;     for (int s = 0; s < KS / 16; ++s) {
;         const bf16x8 a0 = *(const bf16x8*)(ap + s * 16), a1 = *(const bf16x8*)(ap + (size_t)32 * K + s * 16);
;         const bf16x8 b0 = *(const bf16x8*)(bp + s * 16), b1 = *(const bf16x8*)(bp + (size_t)32 * K + s * 16);
;         acc[0][0] = mfma32(a0, b0, acc[0][0]); acc[0][1] = mfma32(a0, b1, acc[0][1]);
;         acc[1][0] = mfma32(a1, b0, acc[1][0]); acc[1][1] = mfma32(a1, b1, acc[1][1]);
;     }
.LBB0_1726:
	v_lshl_add_u64 v[74:75], v[68:69], 0, s[8:9]
	v_add_co_u32_e32 v102, vcc, s11, v74
	v_lshl_add_u64 v[76:77], v[66:67], 0, s[8:9]
	s_nop 0
	v_addc_co_u32_e32 v103, vcc, 0, v75, vcc
	v_add_co_u32_e32 v104, vcc, s12, v74
	s_add_u32 s8, s8, 0x100
	s_nop 0
	v_addc_co_u32_e32 v105, vcc, 0, v75, vcc
	v_add_co_u32_e32 v106, vcc, s13, v76
	s_addc_u32 s9, s9, 0
	s_nop 0
	v_addc_co_u32_e32 v107, vcc, 0, v77, vcc
	v_add_co_u32_e32 v108, vcc, s14, v76
	s_cmpk_lg_i32 s8, 0x200
	s_nop 0
	v_addc_co_u32_e32 v109, vcc, 0, v77, vcc
	s_nop 1
	v_readfirstlane_b32 s88, v102
	v_readfirstlane_b32 s89, v103
	v_readfirstlane_b32 s90, v106
	v_readfirstlane_b32 s91, v107
	v_and_b32_e32 v220, 63, v71
	v_lshrrev_b32_e32 v221, 3, v220
	v_and_b32_e32 v222, 7, v220
	v_lshlrev_b32_e32 v223, 12, v221
	v_lshl_add_u32 v223, v222, 4, v223
	v_lshlrev_b32_e32 v224, 14, v72
	v_mul_u32_u24_e32 v221, 0x90, v221
	v_lshl_add_u32 v221, v222, 4, v221
	v_add_u32_e32 v221, v221, v224
	v_lshrrev_b32_e32 v222, 5, v220
	v_mul_u32_u24_e32 v225, 0x90, v70
	v_lshl_add_u32 v222, v222, 4, v225
	v_add_u32_e32 v222, v222, v224
	global_load_dwordx4 v[76:79], v223, s[88:89]
	s_add_u32 s92, s88, 0x8000
	s_addc_u32 s93, s89, 0
	s_nop 0
	global_load_dwordx4 v[80:83], v223, s[92:93]
	s_add_u32 s94, s88, 0x10000
	s_addc_u32 s95, s89, 0
	s_nop 0
	global_load_dwordx4 v[84:87], v223, s[94:95]
	s_add_u32 s92, s88, 0x18000
	s_addc_u32 s93, s89, 0
	s_nop 0
	global_load_dwordx4 v[88:91], v223, s[92:93]
	s_add_u32 s94, s88, 0x20000
	s_addc_u32 s95, s89, 0
	s_nop 0
	global_load_dwordx4 v[92:95], v223, s[94:95]
	s_add_u32 s92, s88, 0x28000
	s_addc_u32 s93, s89, 0
	s_nop 0
	global_load_dwordx4 v[96:99], v223, s[92:93]
	s_add_u32 s94, s88, 0x30000
	s_addc_u32 s95, s89, 0
	s_nop 0
	global_load_dwordx4 v[112:115], v223, s[94:95]
	s_add_u32 s92, s88, 0x38000
	s_addc_u32 s93, s89, 0
	s_nop 0
	global_load_dwordx4 v[116:119], v223, s[92:93]
	global_load_dwordx4 v[120:123], v223, s[90:91]
	s_add_u32 s94, s90, 0x8000
	s_addc_u32 s95, s91, 0
	s_nop 0
	global_load_dwordx4 v[124:127], v223, s[94:95]
	s_add_u32 s92, s90, 0x10000
	s_addc_u32 s93, s91, 0
	s_nop 0
	global_load_dwordx4 v[128:131], v223, s[92:93]
	s_add_u32 s94, s90, 0x18000
	s_addc_u32 s95, s91, 0
	s_nop 0
	global_load_dwordx4 v[132:135], v223, s[94:95]
	s_add_u32 s92, s90, 0x20000
	s_addc_u32 s93, s91, 0
	s_nop 0
	global_load_dwordx4 v[136:139], v223, s[92:93]
	s_add_u32 s94, s90, 0x28000
	s_addc_u32 s95, s91, 0
	s_nop 0
	global_load_dwordx4 v[140:143], v223, s[94:95]
	s_add_u32 s92, s90, 0x30000
	s_addc_u32 s93, s91, 0
	s_nop 0
	global_load_dwordx4 v[144:147], v223, s[92:93]
	s_add_u32 s94, s90, 0x38000
	s_addc_u32 s95, s91, 0
	s_nop 0
	global_load_dwordx4 v[148:151], v223, s[94:95]
	global_load_dwordx4 v[152:155], v223, s[88:89] offset:128
	s_add_u32 s92, s88, 0x8000
	s_addc_u32 s93, s89, 0
	s_nop 0
	global_load_dwordx4 v[156:159], v223, s[92:93] offset:128
	s_add_u32 s94, s88, 0x10000
	s_addc_u32 s95, s89, 0
	s_nop 0
	global_load_dwordx4 v[160:163], v223, s[94:95] offset:128
	s_add_u32 s92, s88, 0x18000
	s_addc_u32 s93, s89, 0
	s_nop 0
	global_load_dwordx4 v[164:167], v223, s[92:93] offset:128
	s_add_u32 s94, s88, 0x20000
	s_addc_u32 s95, s89, 0
	s_nop 0
	global_load_dwordx4 v[168:171], v223, s[94:95] offset:128
	s_add_u32 s92, s88, 0x28000
	s_addc_u32 s93, s89, 0
	s_nop 0
	global_load_dwordx4 v[172:175], v223, s[92:93] offset:128
	s_add_u32 s94, s88, 0x30000
	s_addc_u32 s95, s89, 0
	s_nop 0
	global_load_dwordx4 v[176:179], v223, s[94:95] offset:128
	s_add_u32 s92, s88, 0x38000
	s_addc_u32 s93, s89, 0
	s_nop 0
	global_load_dwordx4 v[180:183], v223, s[92:93] offset:128
	global_load_dwordx4 v[184:187], v223, s[90:91] offset:128
	s_add_u32 s94, s90, 0x8000
	s_addc_u32 s95, s91, 0
	s_nop 0
	global_load_dwordx4 v[188:191], v223, s[94:95] offset:128
	s_add_u32 s92, s90, 0x10000
	s_addc_u32 s93, s91, 0
	s_nop 0
	global_load_dwordx4 v[192:195], v223, s[92:93] offset:128
	s_add_u32 s94, s90, 0x18000
	s_addc_u32 s95, s91, 0
	s_nop 0
	global_load_dwordx4 v[196:199], v223, s[94:95] offset:128
	s_add_u32 s92, s90, 0x20000
	s_addc_u32 s93, s91, 0
	s_nop 0
	global_load_dwordx4 v[200:203], v223, s[92:93] offset:128
	s_add_u32 s94, s90, 0x28000
	s_addc_u32 s95, s91, 0
	s_nop 0
	global_load_dwordx4 v[204:207], v223, s[94:95] offset:128
	s_add_u32 s92, s90, 0x30000
	s_addc_u32 s93, s91, 0
	s_nop 0
	global_load_dwordx4 v[212:215], v223, s[92:93] offset:128
	s_add_u32 s94, s90, 0x38000
	s_addc_u32 s95, s91, 0
	s_nop 0
	global_load_dwordx4 v[216:219], v223, s[94:95] offset:128
	s_waitcnt vmcnt(24) lgkmcnt(0)
	ds_write_b128 v221, v[76:79]
	ds_write_b128 v221, v[80:83] offset:1152
	ds_write_b128 v221, v[84:87] offset:2304
	ds_write_b128 v221, v[88:91] offset:3456
	ds_write_b128 v221, v[92:95] offset:4608
	ds_write_b128 v221, v[96:99] offset:5760
	ds_write_b128 v221, v[112:115] offset:6912
	ds_write_b128 v221, v[116:119] offset:8064
	s_waitcnt lgkmcnt(0)
	ds_read_b128 v[76:79], v222
	ds_read_b128 v[80:83], v222 offset:32
	ds_read_b128 v[84:87], v222 offset:64
	ds_read_b128 v[88:91], v222 offset:96
	ds_read_b128 v[92:95], v222 offset:4608
	ds_read_b128 v[96:99], v222 offset:4640
	ds_read_b128 v[112:115], v222 offset:4672
	ds_read_b128 v[116:119], v222 offset:4704
	s_waitcnt vmcnt(16) lgkmcnt(0)
	ds_write_b128 v221, v[120:123]
	ds_write_b128 v221, v[124:127] offset:1152
	ds_write_b128 v221, v[128:131] offset:2304
	ds_write_b128 v221, v[132:135] offset:3456
	ds_write_b128 v221, v[136:139] offset:4608
	ds_write_b128 v221, v[140:143] offset:5760
	ds_write_b128 v221, v[144:147] offset:6912
	ds_write_b128 v221, v[148:151] offset:8064
	s_waitcnt lgkmcnt(0)
; DI f32x16 mfma32(bf16x8 a, bf16x8 b, f32x16 c) { return __builtin_amdgcn_mfma_f32_32x32x16_bf16(a, b, c, 0, 0, 0); }
; template <int EPI, int K, int LNI>
; DI void gemm_tail_unit(const Params& p, const bf16_t* __restrict__ A, const bf16_t* __restrict__ Bt, const int un, float* s_aux) {
;     ...
;     const bf16_t* ap = A + (size_t)(ROW0 + r) * K + w * KS + h * 8;
;     const bf16_t* bp = Bt + (size_t)(col0 + r) * K + w * KS + h * 8;
; #pragma unroll 8
;     for (int s = 0; s < KS / 16; ++s) {
;         const bf16x8 a0 = *(const bf16x8*)(ap + s * 16), a1 = *(const bf16x8*)(ap + (size_t)32 * K + s * 16);
;         const bf16x8 b0 = *(const bf16x8*)(bp + s * 16), b1 = *(const bf16x8*)(bp + (size_t)32 * K + s * 16);
;         acc[0][0] = mfma32(a0, b0, acc[0][0]); acc[0][1] = mfma32(a0, b1, acc[0][1]);
;         acc[1][0] = mfma32(a1, b0, acc[1][0]); acc[1][1] = mfma32(a1, b1, acc[1][1]);
;     }
	ds_read_b128 v[120:123], v222
	ds_read_b128 v[124:127], v222 offset:32
	ds_read_b128 v[128:131], v222 offset:64
	ds_read_b128 v[132:135], v222 offset:96
	ds_read_b128 v[136:139], v222 offset:4608
	ds_read_b128 v[140:143], v222 offset:4640
	ds_read_b128 v[144:147], v222 offset:4672
	ds_read_b128 v[148:151], v222 offset:4704
	s_waitcnt lgkmcnt(0)
	v_mfma_f32_32x32x16_bf16 v[0:15], v[76:79], v[120:123], v[0:15]
	v_mfma_f32_32x32x16_bf16 v[16:31], v[76:79], v[136:139], v[16:31]
	v_mfma_f32_32x32x16_bf16 v[32:47], v[92:95], v[120:123], v[32:47]
	v_mfma_f32_32x32x16_bf16 v[48:63], v[92:95], v[136:139], v[48:63]
	v_mfma_f32_32x32x16_bf16 v[0:15], v[80:83], v[124:127], v[0:15]
	v_mfma_f32_32x32x16_bf16 v[16:31], v[80:83], v[140:143], v[16:31]
	v_mfma_f32_32x32x16_bf16 v[32:47], v[96:99], v[124:127], v[32:47]
	v_mfma_f32_32x32x16_bf16 v[48:63], v[96:99], v[140:143], v[48:63]
	v_mfma_f32_32x32x16_bf16 v[0:15], v[84:87], v[128:131], v[0:15]
	v_mfma_f32_32x32x16_bf16 v[16:31], v[84:87], v[144:147], v[16:31]
	v_mfma_f32_32x32x16_bf16 v[32:47], v[112:115], v[128:131], v[32:47]
	v_mfma_f32_32x32x16_bf16 v[48:63], v[112:115], v[144:147], v[48:63]
	v_mfma_f32_32x32x16_bf16 v[0:15], v[88:91], v[132:135], v[0:15]
	v_mfma_f32_32x32x16_bf16 v[16:31], v[88:91], v[148:151], v[16:31]
	v_mfma_f32_32x32x16_bf16 v[32:47], v[116:119], v[132:135], v[32:47]
	v_mfma_f32_32x32x16_bf16 v[48:63], v[116:119], v[148:151], v[48:63]
	global_load_dwordx4 v[76:79], v223, s[88:89] offset:256
	s_add_u32 s92, s88, 0x8000
	s_addc_u32 s93, s89, 0
	s_nop 0
	global_load_dwordx4 v[80:83], v223, s[92:93] offset:256
	s_add_u32 s94, s88, 0x10000
	s_addc_u32 s95, s89, 0
	s_nop 0
	global_load_dwordx4 v[84:87], v223, s[94:95] offset:256
	s_add_u32 s92, s88, 0x18000
	s_addc_u32 s93, s89, 0
	s_nop 0
	global_load_dwordx4 v[88:91], v223, s[92:93] offset:256
	s_add_u32 s94, s88, 0x20000
	s_addc_u32 s95, s89, 0
	s_nop 0
	global_load_dwordx4 v[92:95], v223, s[94:95] offset:256
	s_add_u32 s92, s88, 0x28000
	s_addc_u32 s93, s89, 0
	s_nop 0
	global_load_dwordx4 v[96:99], v223, s[92:93] offset:256
	s_add_u32 s94, s88, 0x30000
	s_addc_u32 s95, s89, 0
	s_nop 0
	global_load_dwordx4 v[112:115], v223, s[94:95] offset:256
	s_add_u32 s92, s88, 0x38000
	s_addc_u32 s93, s89, 0
	s_nop 0
	global_load_dwordx4 v[116:119], v223, s[92:93] offset:256
	global_load_dwordx4 v[120:123], v223, s[90:91] offset:256
	s_add_u32 s94, s90, 0x8000
	s_addc_u32 s95, s91, 0
	s_nop 0
	global_load_dwordx4 v[124:127], v223, s[94:95] offset:256
	s_add_u32 s92, s90, 0x10000
	s_addc_u32 s93, s91, 0
	s_nop 0
	global_load_dwordx4 v[128:131], v223, s[92:93] offset:256
	s_add_u32 s94, s90, 0x18000
	s_addc_u32 s95, s91, 0
	s_nop 0
	global_load_dwordx4 v[132:135], v223, s[94:95] offset:256
	s_add_u32 s92, s90, 0x20000
	s_addc_u32 s93, s91, 0
	s_nop 0
	global_load_dwordx4 v[136:139], v223, s[92:93] offset:256
	s_add_u32 s94, s90, 0x28000
	s_addc_u32 s95, s91, 0
	s_nop 0
	global_load_dwordx4 v[140:143], v223, s[94:95] offset:256
	s_add_u32 s92, s90, 0x30000
	s_addc_u32 s93, s91, 0
	s_nop 0
	global_load_dwordx4 v[144:147], v223, s[92:93] offset:256
	s_add_u32 s94, s90, 0x38000
	s_addc_u32 s95, s91, 0
	s_nop 0
	global_load_dwordx4 v[148:151], v223, s[94:95] offset:256
	s_waitcnt vmcnt(24) lgkmcnt(0)
	ds_write_b128 v221, v[152:155]
	ds_write_b128 v221, v[156:159] offset:1152
	ds_write_b128 v221, v[160:163] offset:2304
	ds_write_b128 v221, v[164:167] offset:3456
	ds_write_b128 v221, v[168:171] offset:4608
	ds_write_b128 v221, v[172:175] offset:5760
	ds_write_b128 v221, v[176:179] offset:6912
	ds_write_b128 v221, v[180:183] offset:8064
	s_waitcnt lgkmcnt(0)
	ds_read_b128 v[152:155], v222
	ds_read_b128 v[156:159], v222 offset:32
	ds_read_b128 v[160:163], v222 offset:64
	ds_read_b128 v[164:167], v222 offset:96
	ds_read_b128 v[168:171], v222 offset:4608
	ds_read_b128 v[172:175], v222 offset:4640
	ds_read_b128 v[176:179], v222 offset:4672
	ds_read_b128 v[180:183], v222 offset:4704
	s_waitcnt vmcnt(16) lgkmcnt(0)
	ds_write_b128 v221, v[184:187]
	ds_write_b128 v221, v[188:191] offset:1152
	ds_write_b128 v221, v[192:195] offset:2304
	ds_write_b128 v221, v[196:199] offset:3456
	ds_write_b128 v221, v[200:203] offset:4608
	ds_write_b128 v221, v[204:207] offset:5760
	ds_write_b128 v221, v[212:215] offset:6912
	ds_write_b128 v221, v[216:219] offset:8064
	s_waitcnt lgkmcnt(0)
	ds_read_b128 v[184:187], v222
	ds_read_b128 v[188:191], v222 offset:32
	ds_read_b128 v[192:195], v222 offset:64
	ds_read_b128 v[196:199], v222 offset:96
	ds_read_b128 v[200:203], v222 offset:4608
	ds_read_b128 v[204:207], v222 offset:4640
	ds_read_b128 v[212:215], v222 offset:4672
	ds_read_b128 v[216:219], v222 offset:4704
	s_waitcnt lgkmcnt(0)
; DI f32x16 mfma32(bf16x8 a, bf16x8 b, f32x16 c) { return __builtin_amdgcn_mfma_f32_32x32x16_bf16(a, b, c, 0, 0, 0); }
; template <int EPI, int K, int LNI>
; DI void gemm_tail_unit(const Params& p, const bf16_t* __restrict__ A, const bf16_t* __restrict__ Bt, const int un, float* s_aux) {
;     ...
;     const bf16_t* ap = A + (size_t)(ROW0 + r) * K + w * KS + h * 8;
;     const bf16_t* bp = Bt + (size_t)(col0 + r) * K + w * KS + h * 8;
; #pragma unroll 8
;     for (int s = 0; s < KS / 16; ++s) {
;         const bf16x8 a0 = *(const bf16x8*)(ap + s * 16), a1 = *(const bf16x8*)(ap + (size_t)32 * K + s * 16);
;         const bf16x8 b0 = *(const bf16x8*)(bp + s * 16), b1 = *(const bf16x8*)(bp + (size_t)32 * K + s * 16);
;         acc[0][0] = mfma32(a0, b0, acc[0][0]); acc[0][1] = mfma32(a0, b1, acc[0][1]);
;         acc[1][0] = mfma32(a1, b0, acc[1][0]); acc[1][1] = mfma32(a1, b1, acc[1][1]);
;     }
	v_mfma_f32_32x32x16_bf16 v[0:15], v[152:155], v[184:187], v[0:15]
	v_mfma_f32_32x32x16_bf16 v[16:31], v[152:155], v[200:203], v[16:31]
	v_mfma_f32_32x32x16_bf16 v[32:47], v[168:171], v[184:187], v[32:47]
	v_mfma_f32_32x32x16_bf16 v[48:63], v[168:171], v[200:203], v[48:63]
	v_mfma_f32_32x32x16_bf16 v[0:15], v[156:159], v[188:191], v[0:15]
	v_mfma_f32_32x32x16_bf16 v[16:31], v[156:159], v[204:207], v[16:31]
	v_mfma_f32_32x32x16_bf16 v[32:47], v[172:175], v[188:191], v[32:47]
	v_mfma_f32_32x32x16_bf16 v[48:63], v[172:175], v[204:207], v[48:63]
	v_mfma_f32_32x32x16_bf16 v[0:15], v[160:163], v[192:195], v[0:15]
	v_mfma_f32_32x32x16_bf16 v[16:31], v[160:163], v[212:215], v[16:31]
	v_mfma_f32_32x32x16_bf16 v[32:47], v[176:179], v[192:195], v[32:47]
	v_mfma_f32_32x32x16_bf16 v[48:63], v[176:179], v[212:215], v[48:63]
	v_mfma_f32_32x32x16_bf16 v[0:15], v[164:167], v[196:199], v[0:15]
	v_mfma_f32_32x32x16_bf16 v[16:31], v[164:167], v[216:219], v[16:31]
	v_mfma_f32_32x32x16_bf16 v[32:47], v[180:183], v[196:199], v[32:47]
	v_mfma_f32_32x32x16_bf16 v[48:63], v[180:183], v[216:219], v[48:63]
	global_load_dwordx4 v[152:155], v223, s[88:89] offset:384
	s_add_u32 s92, s88, 0x8000
	s_addc_u32 s93, s89, 0
	s_nop 0
	global_load_dwordx4 v[156:159], v223, s[92:93] offset:384
	s_add_u32 s94, s88, 0x10000
	s_addc_u32 s95, s89, 0
	s_nop 0
	global_load_dwordx4 v[160:163], v223, s[94:95] offset:384
	s_add_u32 s92, s88, 0x18000
	s_addc_u32 s93, s89, 0
	s_nop 0
	global_load_dwordx4 v[164:167], v223, s[92:93] offset:384
	s_add_u32 s94, s88, 0x20000
	s_addc_u32 s95, s89, 0
	s_nop 0
	global_load_dwordx4 v[168:171], v223, s[94:95] offset:384
	s_add_u32 s92, s88, 0x28000
	s_addc_u32 s93, s89, 0
	s_nop 0
	global_load_dwordx4 v[172:175], v223, s[92:93] offset:384
	s_add_u32 s94, s88, 0x30000
	s_addc_u32 s95, s89, 0
	s_nop 0
	global_load_dwordx4 v[176:179], v223, s[94:95] offset:384
	s_add_u32 s92, s88, 0x38000
	s_addc_u32 s93, s89, 0
	s_nop 0
	global_load_dwordx4 v[180:183], v223, s[92:93] offset:384
	global_load_dwordx4 v[184:187], v223, s[90:91] offset:384
	s_add_u32 s94, s90, 0x8000
	s_addc_u32 s95, s91, 0
	s_nop 0
	global_load_dwordx4 v[188:191], v223, s[94:95] offset:384
	s_add_u32 s92, s90, 0x10000
	s_addc_u32 s93, s91, 0
	s_nop 0
	global_load_dwordx4 v[192:195], v223, s[92:93] offset:384
	s_add_u32 s94, s90, 0x18000
	s_addc_u32 s95, s91, 0
	s_nop 0
	global_load_dwordx4 v[196:199], v223, s[94:95] offset:384
	s_add_u32 s92, s90, 0x20000
	s_addc_u32 s93, s91, 0
	s_nop 0
	global_load_dwordx4 v[200:203], v223, s[92:93] offset:384
	s_add_u32 s94, s90, 0x28000
	s_addc_u32 s95, s91, 0
	s_nop 0
	global_load_dwordx4 v[204:207], v223, s[94:95] offset:384
	s_add_u32 s92, s90, 0x30000
	s_addc_u32 s93, s91, 0
	s_nop 0
	global_load_dwordx4 v[212:215], v223, s[92:93] offset:384
	s_add_u32 s94, s90, 0x38000
	s_addc_u32 s95, s91, 0
	s_nop 0
	global_load_dwordx4 v[216:219], v223, s[94:95] offset:384
	s_waitcnt vmcnt(24) lgkmcnt(0)
	ds_write_b128 v221, v[76:79]
	ds_write_b128 v221, v[80:83] offset:1152
	ds_write_b128 v221, v[84:87] offset:2304
	ds_write_b128 v221, v[88:91] offset:3456
	ds_write_b128 v221, v[92:95] offset:4608
	ds_write_b128 v221, v[96:99] offset:5760
	ds_write_b128 v221, v[112:115] offset:6912
	ds_write_b128 v221, v[116:119] offset:8064
	s_waitcnt lgkmcnt(0)
	ds_read_b128 v[76:79], v222
	ds_read_b128 v[80:83], v222 offset:32
	ds_read_b128 v[84:87], v222 offset:64
	ds_read_b128 v[88:91], v222 offset:96
	ds_read_b128 v[92:95], v222 offset:4608
	ds_read_b128 v[96:99], v222 offset:4640
	ds_read_b128 v[112:115], v222 offset:4672
	ds_read_b128 v[116:119], v222 offset:4704
	s_waitcnt vmcnt(16) lgkmcnt(0)
	ds_write_b128 v221, v[120:123]
	ds_write_b128 v221, v[124:127] offset:1152
	ds_write_b128 v221, v[128:131] offset:2304
	ds_write_b128 v221, v[132:135] offset:3456
	ds_write_b128 v221, v[136:139] offset:4608
	ds_write_b128 v221, v[140:143] offset:5760
	ds_write_b128 v221, v[144:147] offset:6912
	ds_write_b128 v221, v[148:151] offset:8064
	s_waitcnt lgkmcnt(0)
	ds_read_b128 v[120:123], v222
	ds_read_b128 v[124:127], v222 offset:32
	ds_read_b128 v[128:131], v222 offset:64
	ds_read_b128 v[132:135], v222 offset:96
	ds_read_b128 v[136:139], v222 offset:4608
	ds_read_b128 v[140:143], v222 offset:4640
	ds_read_b128 v[144:147], v222 offset:4672
	ds_read_b128 v[148:151], v222 offset:4704
	s_waitcnt lgkmcnt(0)
	v_mfma_f32_32x32x16_bf16 v[0:15], v[76:79], v[120:123], v[0:15]
	v_mfma_f32_32x32x16_bf16 v[16:31], v[76:79], v[136:139], v[16:31]
	v_mfma_f32_32x32x16_bf16 v[32:47], v[92:95], v[120:123], v[32:47]
	v_mfma_f32_32x32x16_bf16 v[48:63], v[92:95], v[136:139], v[48:63]
	v_mfma_f32_32x32x16_bf16 v[0:15], v[80:83], v[124:127], v[0:15]
	v_mfma_f32_32x32x16_bf16 v[16:31], v[80:83], v[140:143], v[16:31]
	v_mfma_f32_32x32x16_bf16 v[32:47], v[96:99], v[124:127], v[32:47]
	v_mfma_f32_32x32x16_bf16 v[48:63], v[96:99], v[140:143], v[48:63]
	v_mfma_f32_32x32x16_bf16 v[0:15], v[84:87], v[128:131], v[0:15]
	v_mfma_f32_32x32x16_bf16 v[16:31], v[84:87], v[144:147], v[16:31]
	v_mfma_f32_32x32x16_bf16 v[32:47], v[112:115], v[128:131], v[32:47]
	v_mfma_f32_32x32x16_bf16 v[48:63], v[112:115], v[144:147], v[48:63]
	v_mfma_f32_32x32x16_bf16 v[0:15], v[88:91], v[132:135], v[0:15]
	v_mfma_f32_32x32x16_bf16 v[16:31], v[88:91], v[148:151], v[16:31]
	v_mfma_f32_32x32x16_bf16 v[32:47], v[116:119], v[132:135], v[32:47]
	v_mfma_f32_32x32x16_bf16 v[48:63], v[116:119], v[148:151], v[48:63]
	s_waitcnt vmcnt(8) lgkmcnt(0)
	ds_write_b128 v221, v[152:155]
	ds_write_b128 v221, v[156:159] offset:1152
	ds_write_b128 v221, v[160:163] offset:2304
	ds_write_b128 v221, v[164:167] offset:3456
	ds_write_b128 v221, v[168:171] offset:4608
	ds_write_b128 v221, v[172:175] offset:5760
	ds_write_b128 v221, v[176:179] offset:6912
	ds_write_b128 v221, v[180:183] offset:8064
	s_waitcnt lgkmcnt(0)
; DI f32x16 mfma32(bf16x8 a, bf16x8 b, f32x16 c) { return __builtin_amdgcn_mfma_f32_32x32x16_bf16(a, b, c, 0, 0, 0); }
; template <int EPI, int K, int LNI>
; DI void gemm_tail_unit(const Params& p, const bf16_t* __restrict__ A, const bf16_t* __restrict__ Bt, const int un, float* s_aux) {
;     ...
; #pragma unroll 8
;     for (int s = 0; s < KS / 16; ++s) {
;         const bf16x8 a0 = *(const bf16x8*)(ap + s * 16), a1 = *(const bf16x8*)(ap + (size_t)32 * K + s * 16);
;         const bf16x8 b0 = *(const bf16x8*)(bp + s * 16), b1 = *(const bf16x8*)(bp + (size_t)32 * K + s * 16);
;         acc[0][0] = mfma32(a0, b0, acc[0][0]); acc[0][1] = mfma32(a0, b1, acc[0][1]);
;         acc[1][0] = mfma32(a1, b0, acc[1][0]); acc[1][1] = mfma32(a1, b1, acc[1][1]);
;     }
;     float* red = (float*)dsm;
; #pragma unroll
;     for (int i = 0; i < 2; ++i)
; #pragma unroll
;         for (int j = 0; j < 2; ++j)
; #pragma unroll
;             for (int reg = 0; reg < 16; ++reg) red[((w * 4 + i * 2 + j) * 16 + reg) * 64 + lane] = acc[i][j][reg];
;     __syncthreads();
	ds_read_b128 v[152:155], v222
	ds_read_b128 v[156:159], v222 offset:32
	ds_read_b128 v[160:163], v222 offset:64
	ds_read_b128 v[164:167], v222 offset:96
	ds_read_b128 v[168:171], v222 offset:4608
	ds_read_b128 v[172:175], v222 offset:4640
	ds_read_b128 v[176:179], v222 offset:4672
	ds_read_b128 v[180:183], v222 offset:4704
	s_waitcnt vmcnt(0) lgkmcnt(0)
	ds_write_b128 v221, v[184:187]
	ds_write_b128 v221, v[188:191] offset:1152
	ds_write_b128 v221, v[192:195] offset:2304
	ds_write_b128 v221, v[196:199] offset:3456
	ds_write_b128 v221, v[200:203] offset:4608
	ds_write_b128 v221, v[204:207] offset:5760
	ds_write_b128 v221, v[212:215] offset:6912
	ds_write_b128 v221, v[216:219] offset:8064
	s_waitcnt lgkmcnt(0)
	ds_read_b128 v[184:187], v222
	ds_read_b128 v[188:191], v222 offset:32
	ds_read_b128 v[192:195], v222 offset:64
	ds_read_b128 v[196:199], v222 offset:96
	ds_read_b128 v[200:203], v222 offset:4608
	ds_read_b128 v[204:207], v222 offset:4640
	ds_read_b128 v[212:215], v222 offset:4672
	ds_read_b128 v[216:219], v222 offset:4704
	s_waitcnt lgkmcnt(0)
	v_mfma_f32_32x32x16_bf16 v[0:15], v[152:155], v[184:187], v[0:15]
	v_mfma_f32_32x32x16_bf16 v[16:31], v[152:155], v[200:203], v[16:31]
	v_mfma_f32_32x32x16_bf16 v[32:47], v[168:171], v[184:187], v[32:47]
	v_mfma_f32_32x32x16_bf16 v[48:63], v[168:171], v[200:203], v[48:63]
	v_mfma_f32_32x32x16_bf16 v[0:15], v[156:159], v[188:191], v[0:15]
	v_mfma_f32_32x32x16_bf16 v[16:31], v[156:159], v[204:207], v[16:31]
	v_mfma_f32_32x32x16_bf16 v[32:47], v[172:175], v[188:191], v[32:47]
	v_mfma_f32_32x32x16_bf16 v[48:63], v[172:175], v[204:207], v[48:63]
	v_mfma_f32_32x32x16_bf16 v[0:15], v[160:163], v[192:195], v[0:15]
	v_mfma_f32_32x32x16_bf16 v[16:31], v[160:163], v[212:215], v[16:31]
	v_mfma_f32_32x32x16_bf16 v[32:47], v[176:179], v[192:195], v[32:47]
	v_mfma_f32_32x32x16_bf16 v[48:63], v[176:179], v[212:215], v[48:63]
	v_mfma_f32_32x32x16_bf16 v[0:15], v[164:167], v[196:199], v[0:15]
	v_mfma_f32_32x32x16_bf16 v[16:31], v[164:167], v[216:219], v[16:31]
	v_mfma_f32_32x32x16_bf16 v[32:47], v[180:183], v[196:199], v[32:47]
	v_mfma_f32_32x32x16_bf16 v[48:63], v[180:183], v[216:219], v[48:63]
	s_nop 7
	v_and_b32_e32 v64, 63, v71
	v_lshl_add_u32 v64, v64, 2, 0
	v_lshl_add_u32 v66, v72, 14, v64
	s_nop 2
	ds_write2st64_b32 v66, v0, v1 offset1:1
	ds_write2st64_b32 v66, v2, v3 offset0:2 offset1:3
	ds_write2st64_b32 v66, v4, v5 offset0:4 offset1:5
	ds_write2st64_b32 v66, v6, v7 offset0:6 offset1:7
	ds_write2st64_b32 v66, v8, v9 offset0:8 offset1:9
	ds_write2st64_b32 v66, v10, v11 offset0:10 offset1:11
	ds_write2st64_b32 v66, v12, v13 offset0:12 offset1:13
	ds_write2st64_b32 v66, v14, v15 offset0:14 offset1:15
	ds_write2st64_b32 v66, v16, v17 offset0:16 offset1:17
	ds_write2st64_b32 v66, v18, v19 offset0:18 offset1:19
	ds_write2st64_b32 v66, v20, v21 offset0:20 offset1:21
	ds_write2st64_b32 v66, v22, v23 offset0:22 offset1:23
	ds_write2st64_b32 v66, v24, v25 offset0:24 offset1:25
	ds_write2st64_b32 v66, v26, v27 offset0:26 offset1:27
	ds_write2st64_b32 v66, v28, v29 offset0:28 offset1:29
	ds_write2st64_b32 v66, v30, v31 offset0:30 offset1:31
	ds_write2st64_b32 v66, v32, v33 offset0:32 offset1:33
	ds_write2st64_b32 v66, v34, v35 offset0:34 offset1:35
	ds_write2st64_b32 v66, v36, v37 offset0:36 offset1:37
	ds_write2st64_b32 v66, v38, v39 offset0:38 offset1:39
	ds_write2st64_b32 v66, v40, v41 offset0:40 offset1:41
	ds_write2st64_b32 v66, v42, v43 offset0:42 offset1:43
	ds_write2st64_b32 v66, v44, v45 offset0:44 offset1:45
	ds_write2st64_b32 v66, v46, v47 offset0:46 offset1:47
	ds_write2st64_b32 v66, v48, v49 offset0:48 offset1:49
	ds_write2st64_b32 v66, v50, v51 offset0:50 offset1:51
	ds_write2st64_b32 v66, v52, v53 offset0:52 offset1:53
	ds_write2st64_b32 v66, v54, v55 offset0:54 offset1:55
	ds_write2st64_b32 v66, v56, v57 offset0:56 offset1:57
	ds_write2st64_b32 v66, v58, v59 offset0:58 offset1:59
	ds_write2st64_b32 v66, v60, v61 offset0:60 offset1:61
	ds_write2st64_b32 v66, v62, v63 offset0:62 offset1:63
	v_ashrrev_i32_e32 v0, 7, v71
	v_lshlrev_b32_e32 v1, 1, v72
	v_and_b32_e32 v34, 2, v1
	v_lshlrev_b32_e32 v35, 12, v0
	v_ashrrev_i32_e32 v1, 3, v71
	v_lshl_or_b32 v37, v34, 10, v35
	s_lshl_b32 s8, s21, 6
	v_and_b32_e32 v1, 0xffffffe0, v1
	v_lshrrev_b32_e32 v2, 3, v71
	v_lshlrev_b32_e32 v0, 5, v0
	v_add_u32_e32 v32, v64, v37
	s_waitcnt lgkmcnt(0)
	s_barrier
; DI float ex2(float x) { return __builtin_amdgcn_exp2f(x); }
;     ...
;         float* d = (float*)(p.ws + OFF_H) + (size_t)row0 * 1024 + col;
; #pragma unroll
;         for (int e = 0; e < 4; ++e) {
;             float hprev = d[(size_t)e * 1024];
;             if (LNI >= 0) hprev = (hprev - rs[e][0]) * rs[e][1] * gg + bb;
;             d[(size_t)e * 1024] = ALPHA * hprev + v[e];
; template <int EPI, int K, int LNI>
; DI void gemm_tail_unit(const Params& p, const bf16_t* __restrict__ A, const bf16_t* __restrict__ Bt, const int un, float* s_aux) {
;     ...
;     {
;         const int tile = w >> 1, i = tile >> 1, j = tile & 1;
; #pragma unroll
;         for (int gg = 0; gg < 2; ++gg) {
;             const int g = 2 * (w & 1) + gg;
;             float v[4];
; #pragma unroll
;             for (int e = 0; e < 4; ++e) {
;                 float sacc = 0.f;
; #pragma unroll
;                 for (int wv = 0; wv < 8; ++wv) sacc += red[((wv * 4 + tile) * 16 + 4 * g + e) * 64 + lane];
;                 v[e] = sacc;
;             }
;             const int lrow0 = i * 32 + 8 * g + 4 * h;
;             f32x2 rs[4]; float lng = 1.f, lnb = 0.f;
;             if (EPI == EPI_E5) {
;                 lng = log2f(1.f - ex2(-5.f - (float)((col0 >> 8) & 3)));
;                 const int idx_ = (((ROW0 + lrow0) % LT) + 48) & 63;
; #pragma unroll
;                 for (int e = 0; e < 4; ++e) rs[e] = (f32x2){ex2(lng * (float)(idx_ + e + 1)), 0.0625f * ex2(lng * (float)(63 - idx_ - e))};
;             }
;             if (EPI == EPI_RESID && LNI >= 0) {
;                 const f32x2* st_ = (const f32x2*)((unsigned char*)p.out + OFFO_STATS) + ROW0 + lrow0;
; #pragma unroll
;                 for (int e = 0; e < 4; ++e) rs[e] = st_[e];
;                 lng = p.ln_g[(LNI < 0 ? 0 : LNI) * 1024 + col0 + j * 32 + r]; lnb = p.ln_b[(LNI < 0 ? 0 : LNI) * 1024 + col0 + j * 32 + r];
;             }
;             epi_store<EPI, LNI>(p, ROW0 + lrow0, col0 + j * 32 + r, lrow0, v, s_aux, rs, lng, lnb);
	v_and_or_b32 v36, v2, 4, v1
	s_add_i32 s9, s8, 0x400
	v_and_b32_e32 v4, 32, v0
	ds_read2st64_b32 v[14:15], v32 offset1:1
	ds_read2st64_b32 v[16:17], v32 offset0:64 offset1:65
	v_or3_b32 v0, v4, s9, v70
	v_or3_b32 v4, v70, s8, v4
	v_lshl_or_b32 v24, v34, 3, v36
	v_ashrrev_i32_e32 v5, 31, v4
	v_ashrrev_i32_e32 v25, 31, v24
	v_ashrrev_i32_e32 v1, 31, v0
	v_lshl_add_u64 v[4:5], v[4:5], 2, s[16:17]
	v_lshl_add_u64 v[26:27], v[24:25], 3, s[6:7]
	v_lshlrev_b64 v[24:25], 12, v[24:25]
	v_lshlrev_b64 v[2:3], 2, v[0:1]
	s_waitcnt lgkmcnt(1)
	v_add_f32_e32 v6, 0, v14
	v_lshl_add_u64 v[24:25], v[4:5], 0, v[24:25]
	v_lshl_add_u64 v[0:1], s[62:63], 0, v[2:3]
	v_lshl_add_u64 v[2:3], s[64:65], 0, v[2:3]
	ds_read2st64_b32 v[18:19], v32 offset0:66 offset1:67
	ds_read2st64_b32 v[20:21], v32 offset0:2 offset1:3
	s_waitcnt lgkmcnt(2)
	v_add_f32_e32 v14, v6, v16
	ds_read2st64_b32 v[22:23], v32 offset0:128 offset1:129
	global_load_dwordx4 v[6:9], v[26:27], off offset:16
	global_load_dwordx4 v[10:13], v[26:27], off
	global_load_dword v16, v[0:1], off
	global_load_dword v38, v[2:3], off
	v_add_co_u32_e32 v26, vcc, s15, v24
	s_waitcnt lgkmcnt(1)
	v_add_f32_e32 v20, 0, v20
	v_addc_co_u32_e32 v27, vcc, 0, v25, vcc
	v_add_co_u32_e32 v24, vcc, s20, v24
	global_load_dword v39, v[26:27], off offset:-4096
	s_nop 0
	v_addc_co_u32_e32 v25, vcc, 0, v25, vcc
	ds_read2st64_b32 v[28:29], v32 offset0:192 offset1:193
	ds_read2st64_b32 v[30:31], v32 offset0:194 offset1:195
	ds_read2st64_b32 v[32:33], v32 offset0:130 offset1:131
	global_load_dword v40, v[24:25], off offset:-4096
	global_load_dword v43, v[24:25], off
	s_waitcnt lgkmcnt(3)
	v_add_f32_e32 v14, v14, v22
	global_load_dword v22, v[26:27], off
	s_waitcnt lgkmcnt(2)
	v_add_f32_e32 v14, v14, v28
	v_add_u32_e32 v28, 0x10000, v64
	v_add_u32_e32 v42, 0x14000, v64
	v_add_u32_e32 v45, 0x18000, v64
	v_add_u32_e32 v47, 0x1c000, v64
	v_or_b32_e32 v49, 0x100, v37
	v_add_f32_e32 v15, 0, v15
	v_add_f32_e32 v18, v20, v18
	v_add_u32_e32 v41, v28, v37
	v_add_u32_e32 v44, v42, v37
	v_add_u32_e32 v46, v45, v37
	v_add_u32_e32 v48, v47, v37
	v_add_u32_e32 v50, v28, v49
	v_add_u32_e32 v51, v42, v49
	v_add_u32_e32 v52, v45, v49
	v_add_u32_e32 v49, v47, v49
	v_add_f32_e32 v15, v15, v17
	s_waitcnt lgkmcnt(0)
	v_add_f32_e32 v18, v18, v32
	ds_read_b32 v41, v41
	ds_read_b32 v44, v44
	ds_read_b32 v46, v46
	ds_read_b32 v48, v48
	ds_read_b32 v50, v50
	ds_read_b32 v51, v51
	ds_read_b32 v52, v52
	ds_read_b32 v49, v49
	v_add_f32_e32 v15, v15, v23
	v_or_b32_e32 v17, 0x200, v37
	v_add_f32_e32 v18, v18, v30
	v_or_b32_e32 v30, 0x300, v37
	s_waitcnt lgkmcnt(7)
	v_add_f32_e32 v14, v14, v41
	v_add_f32_e32 v15, v15, v29
	v_add_u32_e32 v20, v28, v17
	v_add_u32_e32 v23, v42, v17
	v_add_u32_e32 v29, v45, v17
	v_add_u32_e32 v17, v47, v17
	v_add_u32_e32 v32, v28, v30
	v_add_u32_e32 v37, v42, v30
	v_add_u32_e32 v41, v45, v30
	v_add_u32_e32 v30, v47, v30
	ds_read_b32 v20, v20
	ds_read_b32 v23, v23
	ds_read_b32 v29, v29
	ds_read_b32 v17, v17
	ds_read_b32 v32, v32
	ds_read_b32 v37, v37
	ds_read_b32 v41, v41
	ds_read_b32 v30, v30
	s_waitcnt lgkmcnt(7)
	v_add_f32_e32 v18, v18, v20
	s_waitcnt lgkmcnt(6)
	v_add_f32_e32 v18, v18, v23
	s_waitcnt lgkmcnt(5)
	v_add_f32_e32 v18, v18, v29
	s_waitcnt lgkmcnt(4)
	v_add_f32_e32 v17, v18, v17
	v_add_f32_e32 v18, 0, v21
	v_add_f32_e32 v14, v14, v44
	v_add_f32_e32 v18, v18, v19
	v_add_f32_e32 v14, v14, v46
	v_add_f32_e32 v18, v18, v33
	v_add_f32_e32 v14, v14, v48
	v_add_f32_e32 v15, v15, v50
	v_add_f32_e32 v18, v18, v31
	v_add_f32_e32 v15, v15, v51
	s_waitcnt lgkmcnt(3)
	v_add_f32_e32 v18, v18, v32
	v_add_f32_e32 v15, v15, v52
	s_waitcnt lgkmcnt(2)
	v_add_f32_e32 v18, v18, v37
	v_add_f32_e32 v15, v15, v49
	s_waitcnt lgkmcnt(1)
	v_add_f32_e32 v18, v18, v41
	s_waitcnt lgkmcnt(0)
	v_add_f32_e32 v18, v18, v30
	s_add_i32 s21, s21, s58
	s_add_i32 s3, s3, s10
	s_cmp_lt_i32 s21, 16
	s_waitcnt vmcnt(3)
	v_sub_f32_e32 v10, v39, v10
	v_mul_f32_e32 v10, v11, v10
	v_fma_f32 v10, v16, v10, v38
	v_fmac_f32_e32 v14, 0x3fb504f3, v10
	s_waitcnt vmcnt(2)
	v_sub_f32_e32 v6, v40, v6
	v_mul_f32_e32 v6, v7, v6
	v_fma_f32 v6, v16, v6, v38
	s_waitcnt vmcnt(0)
; DI float ex2(float x) { return __builtin_amdgcn_exp2f(x); }
;     ...
;         float* d = (float*)(p.ws + OFF_H) + (size_t)row0 * 1024 + col;
; #pragma unroll
;         for (int e = 0; e < 4; ++e) {
;             float hprev = d[(size_t)e * 1024];
;             if (LNI >= 0) hprev = (hprev - rs[e][0]) * rs[e][1] * gg + bb;
;             d[(size_t)e * 1024] = ALPHA * hprev + v[e];
; template <int EPI, int K, int LNI>
; DI void gemm_tail_unit(const Params& p, const bf16_t* __restrict__ A, const bf16_t* __restrict__ Bt, const int un, float* s_aux) {
;     ...
;         const int tile = w >> 1, i = tile >> 1, j = tile & 1;
; #pragma unroll
;         for (int gg = 0; gg < 2; ++gg) {
;             const int g = 2 * (w & 1) + gg;
;             float v[4];
; #pragma unroll
;             for (int e = 0; e < 4; ++e) {
;                 float sacc = 0.f;
; #pragma unroll
;                 for (int wv = 0; wv < 8; ++wv) sacc += red[((wv * 4 + tile) * 16 + 4 * g + e) * 64 + lane];
;                 v[e] = sacc;
;             }
;             const int lrow0 = i * 32 + 8 * g + 4 * h;
;             f32x2 rs[4]; float lng = 1.f, lnb = 0.f;
;             if (EPI == EPI_E5) {
;                 lng = log2f(1.f - ex2(-5.f - (float)((col0 >> 8) & 3)));
;                 const int idx_ = (((ROW0 + lrow0) % LT) + 48) & 63;
; #pragma unroll
;                 for (int e = 0; e < 4; ++e) rs[e] = (f32x2){ex2(lng * (float)(idx_ + e + 1)), 0.0625f * ex2(lng * (float)(63 - idx_ - e))};
;             }
;             if (EPI == EPI_RESID && LNI >= 0) {
;                 const f32x2* st_ = (const f32x2*)((unsigned char*)p.out + OFFO_STATS) + ROW0 + lrow0;
; #pragma unroll
;                 for (int e = 0; e < 4; ++e) rs[e] = st_[e];
;                 lng = p.ln_g[(LNI < 0 ? 0 : LNI) * 1024 + col0 + j * 32 + r]; lnb = p.ln_b[(LNI < 0 ? 0 : LNI) * 1024 + col0 + j * 32 + r];
;             }
;             epi_store<EPI, LNI>(p, ROW0 + lrow0, col0 + j * 32 + r, lrow0, v, s_aux, rs, lng, lnb);
;         }
;     }
;     __syncthreads();
	v_sub_f32_e32 v10, v22, v12
	v_fmac_f32_e32 v17, 0x3fb504f3, v6
	v_sub_f32_e32 v6, v43, v8
	v_mul_f32_e32 v10, v13, v10
	v_mul_f32_e32 v6, v9, v6
	v_fma_f32 v10, v16, v10, v38
	v_fmac_f32_e32 v38, v16, v6
	v_or_b32_e32 v6, 1, v34
	v_fmac_f32_e32 v15, 0x3fb504f3, v10
	v_lshl_or_b32 v29, v6, 10, v35
	v_lshl_or_b32 v22, v6, 3, v36
	global_store_dword v[26:27], v14, off offset:-4096
	global_store_dword v[26:27], v15, off
	v_fmac_f32_e32 v18, 0x3fb504f3, v38
	v_add_u32_e32 v26, v64, v29
	v_ashrrev_i32_e32 v23, 31, v22
	global_store_dword v[24:25], v17, off offset:-4096
	ds_read2st64_b32 v[14:15], v26 offset1:1
	global_store_dword v[24:25], v18, off
	v_lshl_add_u64 v[24:25], v[22:23], 3, s[6:7]
	v_lshlrev_b64 v[22:23], 12, v[22:23]
	v_lshl_add_u64 v[4:5], v[4:5], 0, v[22:23]
	ds_read2st64_b32 v[16:17], v26 offset0:64 offset1:65
	ds_read2st64_b32 v[18:19], v26 offset0:66 offset1:67
	ds_read2st64_b32 v[20:21], v26 offset0:2 offset1:3
	global_load_dwordx4 v[6:9], v[24:25], off offset:16
	global_load_dwordx4 v[10:13], v[24:25], off
	v_add_co_u32_e32 v22, vcc, s15, v4
	s_waitcnt lgkmcnt(3)
	v_add_f32_e32 v14, 0, v14
	v_addc_co_u32_e32 v23, vcc, 0, v5, vcc
	global_load_dword v30, v[22:23], off offset:-4096
	global_load_dword v31, v[0:1], off
	global_load_dword v32, v[2:3], off
	s_waitcnt lgkmcnt(2)
	v_add_f32_e32 v14, v14, v16
	global_load_dword v16, v[22:23], off
	ds_read2st64_b32 v[0:1], v26 offset0:128 offset1:129
	v_add_co_u32_e32 v2, vcc, s20, v4
	v_or_b32_e32 v37, 0x100, v29
	s_nop 0
	v_addc_co_u32_e32 v3, vcc, 0, v5, vcc
	global_load_dword v33, v[2:3], off offset:-4096
	ds_read2st64_b32 v[4:5], v26 offset0:192 offset1:193
	ds_read2st64_b32 v[24:25], v26 offset0:194 offset1:195
	ds_read2st64_b32 v[26:27], v26 offset0:130 offset1:131
	s_waitcnt lgkmcnt(3)
	v_add_f32_e32 v0, v14, v0
	global_load_dword v14, v[2:3], off
	s_waitcnt lgkmcnt(2)
	v_add_f32_e32 v0, v0, v4
	v_add_u32_e32 v4, v28, v29
	v_add_u32_e32 v34, v42, v29
	v_add_u32_e32 v35, v45, v29
	v_add_u32_e32 v36, v47, v29
	v_add_u32_e32 v38, v28, v37
	v_add_u32_e32 v39, v42, v37
	v_add_u32_e32 v40, v45, v37
	v_add_u32_e32 v37, v47, v37
	ds_read_b32 v4, v4
	ds_read_b32 v34, v34
	ds_read_b32 v35, v35
	ds_read_b32 v36, v36
	ds_read_b32 v38, v38
	ds_read_b32 v39, v39
	ds_read_b32 v40, v40
	ds_read_b32 v37, v37
	s_waitcnt lgkmcnt(7)
	v_add_f32_e32 v0, v0, v4
	v_add_f32_e32 v4, 0, v15
	v_add_f32_e32 v4, v4, v17
	v_add_f32_e32 v1, v4, v1
	v_add_f32_e32 v1, v1, v5
	v_add_f32_e32 v5, 0, v20
	v_add_f32_e32 v5, v5, v18
	s_waitcnt lgkmcnt(6)
	v_add_f32_e32 v0, v0, v34
	v_or_b32_e32 v4, 0x200, v29
	v_add_f32_e32 v5, v5, v26
	v_or_b32_e32 v20, 0x300, v29
	s_waitcnt lgkmcnt(5)
	v_add_f32_e32 v0, v0, v35
	v_add_f32_e32 v5, v5, v24
	v_add_u32_e32 v15, v28, v4
	v_add_u32_e32 v17, v42, v4
	v_add_u32_e32 v18, v45, v4
	v_add_u32_e32 v4, v47, v4
	v_add_u32_e32 v24, v28, v20
	v_add_u32_e32 v26, v42, v20
	v_add_u32_e32 v28, v45, v20
	v_add_u32_e32 v20, v47, v20
	s_waitcnt lgkmcnt(4)
	v_add_f32_e32 v0, v0, v36
	ds_read_b32 v15, v15
	ds_read_b32 v17, v17
	ds_read_b32 v18, v18
	ds_read_b32 v4, v4
	ds_read_b32 v24, v24
	ds_read_b32 v26, v26
	ds_read_b32 v28, v28
	ds_read_b32 v20, v20
	s_waitcnt lgkmcnt(7)
	v_add_f32_e32 v5, v5, v15
	v_add_f32_e32 v1, v1, v38
	s_waitcnt lgkmcnt(6)
	v_add_f32_e32 v5, v5, v17
	v_add_f32_e32 v1, v1, v39
	s_waitcnt lgkmcnt(5)
	v_add_f32_e32 v5, v5, v18
	v_add_f32_e32 v1, v1, v40
	s_waitcnt lgkmcnt(4)
	v_add_f32_e32 v4, v5, v4
	v_add_f32_e32 v5, 0, v21
	v_add_f32_e32 v1, v1, v37
	v_add_f32_e32 v5, v5, v19
	v_add_f32_e32 v5, v5, v27
	v_add_f32_e32 v5, v5, v25
	s_waitcnt lgkmcnt(3)
	v_add_f32_e32 v5, v5, v24
	s_waitcnt lgkmcnt(2)
	v_add_f32_e32 v5, v5, v26
	s_waitcnt lgkmcnt(1)
	v_add_f32_e32 v5, v5, v28
	s_waitcnt lgkmcnt(0)
	v_add_f32_e32 v5, v5, v20
	s_waitcnt vmcnt(5)
	v_sub_f32_e32 v10, v30, v10
	v_mul_f32_e32 v10, v11, v10
	s_waitcnt vmcnt(3)
	v_fma_f32 v10, v31, v10, v32
	v_fmac_f32_e32 v0, 0x3fb504f3, v10
	global_store_dword v[22:23], v0, off offset:-4096
	s_waitcnt vmcnt(3)
	v_sub_f32_e32 v0, v16, v12
	v_mul_f32_e32 v0, v13, v0
	v_fma_f32 v0, v31, v0, v32
	v_fmac_f32_e32 v1, 0x3fb504f3, v0
	global_store_dword v[22:23], v1, off
	s_waitcnt vmcnt(3)
	v_sub_f32_e32 v0, v33, v6
	v_mul_f32_e32 v0, v7, v0
	v_fma_f32 v0, v31, v0, v32
	v_fmac_f32_e32 v4, 0x3fb504f3, v0
	s_waitcnt vmcnt(2)
	v_sub_f32_e32 v0, v14, v8
	v_mul_f32_e32 v0, v9, v0
	v_fmac_f32_e32 v32, v31, v0
	v_fmac_f32_e32 v5, 0x3fb504f3, v32
	global_store_dword v[2:3], v4, off offset:-4096
	global_store_dword v[2:3], v5, off
	s_barrier
	s_cbranch_scc1 .LBB0_1725

; #define STAGE(P, g) do { const char* g_ = (const char*)(g); \
;         __builtin_amdgcn_global_load_lds((const unsigned*)(g_ + so0), (lds_u32*)((lds_u8*)(P) + sb0), 16, 0, 0); \
;         __builtin_amdgcn_global_load_lds((const unsigned*)(g_ + so1), (lds_u32*)((lds_u8*)(P) + sb0 + 8192), 16, 0, 0); } while (0)
; #define LDA(dst, b, h) for (int m = 0; m < 4; ++m) for (int k = 0; k < 2; ++k) \
;         dst[m][k] = *reinterpret_cast<const bf16x8*>((char*)SA(b, h) + lds_byte(wr * 64 + m * 16 + fr, k * 32 + fq * 8))
; #define LDB(dst, b, h) for (int n = 0; n < 2; ++n) for (int k = 0; k < 2; ++k) \
;         dst[n][k] = *reinterpret_cast<const bf16x8*>((char*)SB(b, h) + lds_byte(wc * 32 + n * 16 + fr, k * 32 + fq * 8))
; #define MMA(ai, bj, At_, Bt_) do { __builtin_amdgcn_s_setprio(1); \
;         for (int m = 0; m < 4; ++m) for (int n = 0; n < 2; ++n) for (int k = 0; k < 2; ++k) \
;             acc[ai][bj][m][n] = __builtin_amdgcn_mfma_f32_16x16x32_bf16(At_[m][k], Bt_[n][k], acc[ai][bj][m][n], 0, 0, 0); \
;         __builtin_amdgcn_s_setprio(0); } while (0)
; #define WAIT_V(n) asm volatile("s_waitcnt vmcnt(" #n ")" ::: "memory")
; #define WAIT_L(n) asm volatile("s_waitcnt lgkmcnt(" #n ")" ::: "memory")
; #define BAR __builtin_amdgcn_s_barrier()
; #define SCHED __builtin_amdgcn_sched_barrier(0)
; template <int EPI, int K, int LNI = -1>
; DI void ph_gemm(const Params& p, const bf16_t* __restrict__ A, const bf16_t* __restrict__ Bt, int N, float* s_aux) {
;     ...
;         for (int t = 0; t < nt; t += 2) {
;             const bool last = (t == nt - 2);
;             const bf16_t* a1 = cA + (size_t)(t + 1) * kstep;
;             const bf16_t* a2 = last ? nA : cA + (size_t)(t + 2) * kstep; const bf16_t* b2 = last ? nB : cB + (size_t)(t + 2) * kstep;
;             const bf16_t* a3 = a2 + kstep; const bf16_t* b3 = b2 + kstep;
;             LDB(B0, 0, 0); LDB(B1, 0, 1); SCHED; LDA(At, 0, 0); STAGE(SA(1, 1), a1 + hstep);
;             WAIT_V(8); WAIT_L(0); BAR; MMA(0, 0, At, B0); MMA(0, 1, At, B1); BAR; SCHED;
;             LDA(At, 0, 1); STAGE(SB(0, 0), b2); STAGE(SB(0, 1), b2 + hstep); STAGE(SA(0, 0), a2);
;             WAIT_V(8); WAIT_L(0); BAR; MMA(1, 0, At, B0); MMA(1, 1, At, B1); BAR; SCHED;
.LBB0_1853:
	ds_read_b128 v[166:169], v156
	ds_read_b128 v[170:173], v156 offset:1024
	ds_read_b128 v[174:177], v156 offset:2048
	ds_read_b128 v[178:181], v156 offset:3072
	ds_read_b128 v[182:185], v157
	ds_read_b128 v[186:189], v157 offset:1024
	ds_read_b128 v[190:193], v157 offset:2048
	ds_read_b128 v[194:197], v157 offset:3072
	s_add_u32 s46, s60, s44
	s_addc_u32 s47, s61, s45
	s_add_u32 s46, s46, 0xb840100
	s_addc_u32 s47, s47, 0
	s_add_u32 s69, s66, s44
	s_addc_u32 s70, s67, s45
	s_cmpk_eq_i32 s44, 0x700
	s_cselect_b32 s49, s52, s47
	s_cselect_b32 s48, s21, s46
	s_cselect_b32 s47, s53, s70
	s_cselect_b32 s46, s23, s69
	v_readfirstlane_b32 s69, v162
	v_lshl_add_u64 v[232:233], v[136:137], 0, s[44:45]
	s_mov_b32 m0, s69
	v_readfirstlane_b32 s69, v163
	ds_read_b128 v[198:201], v158
	ds_read_b128 v[202:205], v158 offset:1024
	ds_read_b128 v[206:209], v159
	ds_read_b128 v[212:215], v159 offset:1024
	ds_read_b128 v[216:219], v160
	ds_read_b128 v[220:223], v160 offset:1024
	ds_read_b128 v[224:227], v161
	ds_read_b128 v[228:231], v161 offset:1024
	global_load_lds_dwordx4 v[232:233], off
	v_lshl_add_u64 v[232:233], v[138:139], 0, s[44:45]
	s_mov_b32 m0, s69
	s_nop 0
	global_load_lds_dwordx4 v[232:233], off
	s_waitcnt vmcnt(8)
	s_waitcnt lgkmcnt(0)
	s_barrier
	s_setprio 1
	s_waitcnt lgkmcnt(0)
	v_mfma_f32_16x16x32_bf16 v[124:127], v[198:201], v[166:169], v[124:127]
	v_mfma_f32_16x16x32_bf16 v[120:123], v[198:201], v[174:177], v[120:123]
	v_mfma_f32_16x16x32_bf16 v[108:111], v[206:209], v[166:169], v[108:111]
	v_mfma_f32_16x16x32_bf16 v[104:107], v[206:209], v[174:177], v[104:107]
	v_mfma_f32_16x16x32_bf16 v[92:95], v[216:219], v[166:169], v[92:95]
	v_mfma_f32_16x16x32_bf16 v[88:91], v[216:219], v[174:177], v[88:91]
	v_mfma_f32_16x16x32_bf16 v[76:79], v[224:227], v[166:169], v[76:79]
	v_mfma_f32_16x16x32_bf16 v[72:75], v[224:227], v[174:177], v[72:75]
	v_mfma_f32_16x16x32_bf16 v[124:127], v[202:205], v[170:173], v[124:127]
	v_mfma_f32_16x16x32_bf16 v[120:123], v[202:205], v[178:181], v[120:123]
	v_mfma_f32_16x16x32_bf16 v[108:111], v[212:215], v[170:173], v[108:111]
	v_mfma_f32_16x16x32_bf16 v[104:107], v[212:215], v[178:181], v[104:107]
	v_mfma_f32_16x16x32_bf16 v[92:95], v[220:223], v[170:173], v[92:95]
	v_mfma_f32_16x16x32_bf16 v[88:91], v[220:223], v[178:181], v[88:91]
	v_mfma_f32_16x16x32_bf16 v[76:79], v[228:231], v[170:173], v[76:79]
	v_mfma_f32_16x16x32_bf16 v[72:75], v[228:231], v[178:181], v[72:75]
	s_setprio 0
	s_setprio 1
	v_mfma_f32_16x16x32_bf16 v[116:119], v[198:201], v[182:185], v[116:119]
	v_mfma_f32_16x16x32_bf16 v[112:115], v[198:201], v[190:193], v[112:115]
	v_mfma_f32_16x16x32_bf16 v[100:103], v[206:209], v[182:185], v[100:103]
	v_mfma_f32_16x16x32_bf16 v[96:99], v[206:209], v[190:193], v[96:99]
	v_mfma_f32_16x16x32_bf16 v[84:87], v[216:219], v[182:185], v[84:87]
	v_mfma_f32_16x16x32_bf16 v[80:83], v[216:219], v[190:193], v[80:83]
	v_mfma_f32_16x16x32_bf16 v[68:71], v[224:227], v[182:185], v[68:71]
	v_mfma_f32_16x16x32_bf16 v[64:67], v[224:227], v[190:193], v[64:67]
	v_mfma_f32_16x16x32_bf16 v[116:119], v[202:205], v[186:189], v[116:119]
	v_mfma_f32_16x16x32_bf16 v[112:115], v[202:205], v[194:197], v[112:115]
	v_mfma_f32_16x16x32_bf16 v[100:103], v[212:215], v[186:189], v[100:103]
	v_mfma_f32_16x16x32_bf16 v[96:99], v[212:215], v[194:197], v[96:99]
	v_mfma_f32_16x16x32_bf16 v[84:87], v[220:223], v[186:189], v[84:87]
	v_mfma_f32_16x16x32_bf16 v[80:83], v[220:223], v[194:197], v[80:83]
	v_mfma_f32_16x16x32_bf16 v[68:71], v[228:231], v[186:189], v[68:71]
	v_mfma_f32_16x16x32_bf16 v[64:67], v[228:231], v[194:197], v[64:67]
	s_setprio 0
	s_barrier
	v_readfirstlane_b32 s69, v140
	v_lshl_add_u64 v[232:233], s[46:47], 0, v[128:129]
	s_mov_b32 m0, s69
	v_readfirstlane_b32 s69, v141
	s_add_u32 s70, s46, 0x40000
	ds_read_b128 v[198:201], v158 offset:16384
	ds_read_b128 v[202:205], v158 offset:17408
	ds_read_b128 v[206:209], v159 offset:16384
	ds_read_b128 v[212:215], v159 offset:17408
	ds_read_b128 v[216:219], v160 offset:16384
	ds_read_b128 v[220:223], v160 offset:17408
	ds_read_b128 v[224:227], v161 offset:16384
	ds_read_b128 v[228:231], v161 offset:17408
	global_load_lds_dwordx4 v[232:233], off
	v_lshl_add_u64 v[234:235], s[46:47], 0, v[130:131]
	s_mov_b32 m0, s69
	s_addc_u32 s71, s47, 0
	v_readfirstlane_b32 s69, v142
	global_load_lds_dwordx4 v[234:235], off
	v_lshl_add_u64 v[236:237], s[70:71], 0, v[128:129]
	s_mov_b32 m0, s69
	v_readfirstlane_b32 s69, v143
	global_load_lds_dwordx4 v[236:237], off
	v_lshl_add_u64 v[236:237], s[70:71], 0, v[130:131]
	s_mov_b32 m0, s69
	v_readfirstlane_b32 s69, v144
	global_load_lds_dwordx4 v[236:237], off
	v_lshl_add_u64 v[236:237], s[48:49], 0, v[128:129]
	s_mov_b32 m0, s69
	v_readfirstlane_b32 s69, v145
	global_load_lds_dwordx4 v[236:237], off
	v_lshl_add_u64 v[238:239], s[48:49], 0, v[130:131]
	s_mov_b32 m0, s69
	s_nop 0
	global_load_lds_dwordx4 v[238:239], off
	s_waitcnt vmcnt(8)
	s_waitcnt lgkmcnt(0)
	s_barrier
; #define STAGE(P, g) do { const char* g_ = (const char*)(g); \
;         __builtin_amdgcn_global_load_lds((const unsigned*)(g_ + so0), (lds_u32*)((lds_u8*)(P) + sb0), 16, 0, 0); \
;         __builtin_amdgcn_global_load_lds((const unsigned*)(g_ + so1), (lds_u32*)((lds_u8*)(P) + sb0 + 8192), 16, 0, 0); } while (0)
; #define LDA(dst, b, h) for (int m = 0; m < 4; ++m) for (int k = 0; k < 2; ++k) \
;         dst[m][k] = *reinterpret_cast<const bf16x8*>((char*)SA(b, h) + lds_byte(wr * 64 + m * 16 + fr, k * 32 + fq * 8))
; #define LDB(dst, b, h) for (int n = 0; n < 2; ++n) for (int k = 0; k < 2; ++k) \
;         dst[n][k] = *reinterpret_cast<const bf16x8*>((char*)SB(b, h) + lds_byte(wc * 32 + n * 16 + fr, k * 32 + fq * 8))
; #define MMA(ai, bj, At_, Bt_) do { __builtin_amdgcn_s_setprio(1); \
;         for (int m = 0; m < 4; ++m) for (int n = 0; n < 2; ++n) for (int k = 0; k < 2; ++k) \
;             acc[ai][bj][m][n] = __builtin_amdgcn_mfma_f32_16x16x32_bf16(At_[m][k], Bt_[n][k], acc[ai][bj][m][n], 0, 0, 0); \
;         __builtin_amdgcn_s_setprio(0); } while (0)
; #define WAIT_V(n) asm volatile("s_waitcnt vmcnt(" #n ")" ::: "memory")
; #define WAIT_L(n) asm volatile("s_waitcnt lgkmcnt(" #n ")" ::: "memory")
; #define BAR __builtin_amdgcn_s_barrier()
; #define SCHED __builtin_amdgcn_sched_barrier(0)
; template <int EPI, int K, int LNI = -1>
; DI void ph_gemm(const Params& p, const bf16_t* __restrict__ A, const bf16_t* __restrict__ Bt, int N, float* s_aux) {
;     ...
;             WAIT_V(8); WAIT_L(0); BAR; MMA(0, 0, At, B0); MMA(0, 1, At, B1); BAR; SCHED;
;             LDA(At, 0, 1); STAGE(SB(0, 0), b2); STAGE(SB(0, 1), b2 + hstep); STAGE(SA(0, 0), a2);
;             WAIT_V(8); WAIT_L(0); BAR; MMA(1, 0, At, B0); MMA(1, 1, At, B1); BAR; SCHED;
;             LDB(B0, 1, 0); LDB(B1, 1, 1); SCHED; LDA(At, 1, 0); STAGE(SA(0, 1), a2 + hstep);
;             WAIT_V(8); WAIT_L(0); BAR; MMA(0, 0, At, B0); MMA(0, 1, At, B1); BAR; SCHED;
	s_setprio 1
	s_waitcnt lgkmcnt(0)
	v_mfma_f32_16x16x32_bf16 v[60:63], v[198:201], v[166:169], v[60:63]
	v_mfma_f32_16x16x32_bf16 v[56:59], v[198:201], v[174:177], v[56:59]
	v_mfma_f32_16x16x32_bf16 v[44:47], v[206:209], v[166:169], v[44:47]
	v_mfma_f32_16x16x32_bf16 v[40:43], v[206:209], v[174:177], v[40:43]
	v_mfma_f32_16x16x32_bf16 v[28:31], v[216:219], v[166:169], v[28:31]
	v_mfma_f32_16x16x32_bf16 v[24:27], v[216:219], v[174:177], v[24:27]
	v_mfma_f32_16x16x32_bf16 v[12:15], v[224:227], v[166:169], v[12:15]
	v_mfma_f32_16x16x32_bf16 v[8:11], v[224:227], v[174:177], v[8:11]
	v_mfma_f32_16x16x32_bf16 v[60:63], v[202:205], v[170:173], v[60:63]
	v_mfma_f32_16x16x32_bf16 v[56:59], v[202:205], v[178:181], v[56:59]
	v_mfma_f32_16x16x32_bf16 v[44:47], v[212:215], v[170:173], v[44:47]
	v_mfma_f32_16x16x32_bf16 v[40:43], v[212:215], v[178:181], v[40:43]
	v_mfma_f32_16x16x32_bf16 v[28:31], v[220:223], v[170:173], v[28:31]
	v_mfma_f32_16x16x32_bf16 v[24:27], v[220:223], v[178:181], v[24:27]
	v_mfma_f32_16x16x32_bf16 v[12:15], v[228:231], v[170:173], v[12:15]
	v_mfma_f32_16x16x32_bf16 v[8:11], v[228:231], v[178:181], v[8:11]
	s_setprio 0
	s_setprio 1
	v_mfma_f32_16x16x32_bf16 v[52:55], v[198:201], v[182:185], v[52:55]
	v_mfma_f32_16x16x32_bf16 v[48:51], v[198:201], v[190:193], v[48:51]
	v_mfma_f32_16x16x32_bf16 v[36:39], v[206:209], v[182:185], v[36:39]
	v_mfma_f32_16x16x32_bf16 v[32:35], v[206:209], v[190:193], v[32:35]
	v_mfma_f32_16x16x32_bf16 v[20:23], v[216:219], v[182:185], v[20:23]
	v_mfma_f32_16x16x32_bf16 v[16:19], v[216:219], v[190:193], v[16:19]
	v_mfma_f32_16x16x32_bf16 v[4:7], v[224:227], v[182:185], v[4:7]
	v_mfma_f32_16x16x32_bf16 v[0:3], v[224:227], v[190:193], v[0:3]
	v_mfma_f32_16x16x32_bf16 v[52:55], v[202:205], v[186:189], v[52:55]
	v_mfma_f32_16x16x32_bf16 v[48:51], v[202:205], v[194:197], v[48:51]
	v_mfma_f32_16x16x32_bf16 v[36:39], v[212:215], v[186:189], v[36:39]
	v_mfma_f32_16x16x32_bf16 v[32:35], v[212:215], v[194:197], v[32:35]
	v_mfma_f32_16x16x32_bf16 v[20:23], v[220:223], v[186:189], v[20:23]
	v_mfma_f32_16x16x32_bf16 v[16:19], v[220:223], v[194:197], v[16:19]
	v_mfma_f32_16x16x32_bf16 v[4:7], v[228:231], v[186:189], v[4:7]
	v_mfma_f32_16x16x32_bf16 v[0:3], v[228:231], v[194:197], v[0:3]
	s_setprio 0
	s_barrier
	ds_read_b128 v[166:169], v164
	ds_read_b128 v[170:173], v164 offset:1024
	ds_read_b128 v[174:177], v164 offset:2048
	ds_read_b128 v[178:181], v164 offset:3072
	ds_read_b128 v[182:185], v165
	ds_read_b128 v[186:189], v165 offset:1024
	ds_read_b128 v[190:193], v165 offset:2048
	ds_read_b128 v[194:197], v165 offset:3072
	s_add_u32 s48, s48, 0x40000
	s_addc_u32 s49, s49, 0
	v_readfirstlane_b32 s69, v146
	v_lshl_add_u64 v[240:241], s[48:49], 0, v[128:129]
	s_mov_b32 m0, s69
	ds_read_b128 v[198:201], v158 offset:32768
	ds_read_b128 v[202:205], v158 offset:33792
	ds_read_b128 v[206:209], v159 offset:32768
	ds_read_b128 v[212:215], v159 offset:33792
	ds_read_b128 v[216:219], v160 offset:32768
	ds_read_b128 v[220:223], v160 offset:33792
	ds_read_b128 v[224:227], v161 offset:32768
	ds_read_b128 v[228:231], v161 offset:33792
	global_load_lds_dwordx4 v[240:241], off
	v_lshl_add_u64 v[240:241], s[48:49], 0, v[130:131]
	v_readfirstlane_b32 s48, v147
	s_mov_b32 m0, s48
	s_nop 0
	global_load_lds_dwordx4 v[240:241], off
	s_waitcnt vmcnt(8)
	s_waitcnt lgkmcnt(0)
	s_barrier
	s_setprio 1
	s_waitcnt lgkmcnt(0)
	v_mfma_f32_16x16x32_bf16 v[124:127], v[198:201], v[166:169], v[124:127]
	v_mfma_f32_16x16x32_bf16 v[120:123], v[198:201], v[174:177], v[120:123]
	v_mfma_f32_16x16x32_bf16 v[108:111], v[206:209], v[166:169], v[108:111]
	v_mfma_f32_16x16x32_bf16 v[104:107], v[206:209], v[174:177], v[104:107]
	v_mfma_f32_16x16x32_bf16 v[92:95], v[216:219], v[166:169], v[92:95]
	v_mfma_f32_16x16x32_bf16 v[88:91], v[216:219], v[174:177], v[88:91]
	v_mfma_f32_16x16x32_bf16 v[76:79], v[224:227], v[166:169], v[76:79]
	v_mfma_f32_16x16x32_bf16 v[72:75], v[224:227], v[174:177], v[72:75]
	v_mfma_f32_16x16x32_bf16 v[124:127], v[202:205], v[170:173], v[124:127]
	v_mfma_f32_16x16x32_bf16 v[120:123], v[202:205], v[178:181], v[120:123]
	v_mfma_f32_16x16x32_bf16 v[108:111], v[212:215], v[170:173], v[108:111]
	v_mfma_f32_16x16x32_bf16 v[104:107], v[212:215], v[178:181], v[104:107]
	v_mfma_f32_16x16x32_bf16 v[92:95], v[220:223], v[170:173], v[92:95]
	v_mfma_f32_16x16x32_bf16 v[88:91], v[220:223], v[178:181], v[88:91]
	v_mfma_f32_16x16x32_bf16 v[76:79], v[228:231], v[170:173], v[76:79]
	v_mfma_f32_16x16x32_bf16 v[72:75], v[228:231], v[178:181], v[72:75]
	s_setprio 0
	s_setprio 1
	v_mfma_f32_16x16x32_bf16 v[116:119], v[198:201], v[182:185], v[116:119]
	v_mfma_f32_16x16x32_bf16 v[112:115], v[198:201], v[190:193], v[112:115]
	v_mfma_f32_16x16x32_bf16 v[100:103], v[206:209], v[182:185], v[100:103]
	v_mfma_f32_16x16x32_bf16 v[96:99], v[206:209], v[190:193], v[96:99]
	v_mfma_f32_16x16x32_bf16 v[84:87], v[216:219], v[182:185], v[84:87]
	v_mfma_f32_16x16x32_bf16 v[80:83], v[216:219], v[190:193], v[80:83]
	v_mfma_f32_16x16x32_bf16 v[68:71], v[224:227], v[182:185], v[68:71]
	v_mfma_f32_16x16x32_bf16 v[64:67], v[224:227], v[190:193], v[64:67]
	v_mfma_f32_16x16x32_bf16 v[116:119], v[202:205], v[186:189], v[116:119]
	v_mfma_f32_16x16x32_bf16 v[112:115], v[202:205], v[194:197], v[112:115]
	v_mfma_f32_16x16x32_bf16 v[100:103], v[212:215], v[186:189], v[100:103]
	v_mfma_f32_16x16x32_bf16 v[96:99], v[212:215], v[194:197], v[96:99]
	v_mfma_f32_16x16x32_bf16 v[84:87], v[220:223], v[186:189], v[84:87]
	v_mfma_f32_16x16x32_bf16 v[80:83], v[220:223], v[194:197], v[80:83]
	v_mfma_f32_16x16x32_bf16 v[68:71], v[228:231], v[186:189], v[68:71]
	v_mfma_f32_16x16x32_bf16 v[64:67], v[228:231], v[194:197], v[64:67]
	s_setprio 0
	s_barrier
; DI bf16_t f2bf(float x) { return (bf16_t)(cvt_pk(x, 0.f) & 0xffffu); }
; #define STAGE(P, g) do { const char* g_ = (const char*)(g); \
;         __builtin_amdgcn_global_load_lds((const unsigned*)(g_ + so0), (lds_u32*)((lds_u8*)(P) + sb0), 16, 0, 0); \
;         __builtin_amdgcn_global_load_lds((const unsigned*)(g_ + so1), (lds_u32*)((lds_u8*)(P) + sb0 + 8192), 16, 0, 0); } while (0)
; #define LDA(dst, b, h) for (int m = 0; m < 4; ++m) for (int k = 0; k < 2; ++k) \
;         dst[m][k] = *reinterpret_cast<const bf16x8*>((char*)SA(b, h) + lds_byte(wr * 64 + m * 16 + fr, k * 32 + fq * 8))
; #define LDB(dst, b, h) for (int n = 0; n < 2; ++n) for (int k = 0; k < 2; ++k) \
;         dst[n][k] = *reinterpret_cast<const bf16x8*>((char*)SB(b, h) + lds_byte(wc * 32 + n * 16 + fr, k * 32 + fq * 8))
; #define MMA(ai, bj, At_, Bt_) do { __builtin_amdgcn_s_setprio(1); \
;         for (int m = 0; m < 4; ++m) for (int n = 0; n < 2; ++n) for (int k = 0; k < 2; ++k) \
;             acc[ai][bj][m][n] = __builtin_amdgcn_mfma_f32_16x16x32_bf16(At_[m][k], Bt_[n][k], acc[ai][bj][m][n], 0, 0, 0); \
;         __builtin_amdgcn_s_setprio(0); } while (0)
; #define WAIT_V(n) asm volatile("s_waitcnt vmcnt(" #n ")" ::: "memory")
; #define WAIT_L(n) asm volatile("s_waitcnt lgkmcnt(" #n ")" ::: "memory")
; #define BAR __builtin_amdgcn_s_barrier()
; #define SCHED __builtin_amdgcn_sched_barrier(0)
;     ...
;         bf16_t* d = (bf16_t*)(p.ws + OFF_U) + (size_t)row0 * 4096 + col;
; #pragma unroll
;         for (int e = 0; e < 4; ++e) { const float t = fmaxf(v[e], 0.f); d[(size_t)e * 4096] = f2bf(t * t); }
; template <int EPI, int K, int LNI = -1>
; DI void ph_gemm(const Params& p, const bf16_t* __restrict__ A, const bf16_t* __restrict__ Bt, int N, float* s_aux) {
;     ...
;             LDA(At, 0, 1); STAGE(SB(0, 0), b2); STAGE(SB(0, 1), b2 + hstep); STAGE(SA(0, 0), a2);
;             WAIT_V(8); WAIT_L(0); BAR; MMA(1, 0, At, B0); MMA(1, 1, At, B1); BAR; SCHED;
;             LDB(B0, 1, 0); LDB(B1, 1, 1); SCHED; LDA(At, 1, 0); STAGE(SA(0, 1), a2 + hstep);
;             WAIT_V(8); WAIT_L(0); BAR; MMA(0, 0, At, B0); MMA(0, 1, At, B1); BAR; SCHED;
;             LDA(At, 1, 1); STAGE(SB(1, 0), b3); STAGE(SB(1, 1), b3 + hstep); STAGE(SA(1, 0), a3);
;             WAIT_V(8); WAIT_L(0); BAR; MMA(1, 0, At, B0); MMA(1, 1, At, B1); BAR; SCHED;
;         }
;         if (wr == 0) BAR;
	v_readfirstlane_b32 s48, v148
	v_lshl_add_u64 v[232:233], v[232:233], 0, s[12:13]
	s_mov_b32 m0, s48
	v_readfirstlane_b32 s48, v149
	s_add_u32 s46, s46, 0x40080
	ds_read_b128 v[198:201], v158 offset:49152
	ds_read_b128 v[202:205], v158 offset:50176
	ds_read_b128 v[206:209], v159 offset:49152
	ds_read_b128 v[212:215], v159 offset:50176
	ds_read_b128 v[216:219], v160 offset:49152
	ds_read_b128 v[220:223], v160 offset:50176
	ds_read_b128 v[224:227], v161 offset:49152
	ds_read_b128 v[228:231], v161 offset:50176
	global_load_lds_dwordx4 v[232:233], off
	v_lshl_add_u64 v[232:233], v[234:235], 0, s[12:13]
	s_mov_b32 m0, s48
	s_addc_u32 s47, s47, 0
	v_readfirstlane_b32 s48, v152
	global_load_lds_dwordx4 v[232:233], off
	v_lshl_add_u64 v[232:233], s[46:47], 0, v[128:129]
	s_mov_b32 m0, s48
	s_nop 0
	global_load_lds_dwordx4 v[232:233], off
	v_lshl_add_u64 v[232:233], s[46:47], 0, v[130:131]
	v_readfirstlane_b32 s46, v153
	s_mov_b32 m0, s46
	v_readfirstlane_b32 s46, v150
	global_load_lds_dwordx4 v[232:233], off
	v_lshl_add_u64 v[232:233], v[236:237], 0, s[12:13]
	s_mov_b32 m0, s46
	v_readfirstlane_b32 s46, v151
	global_load_lds_dwordx4 v[232:233], off
	v_lshl_add_u64 v[232:233], v[238:239], 0, s[12:13]
	s_mov_b32 m0, s46
	s_nop 0
	global_load_lds_dwordx4 v[232:233], off
	s_waitcnt vmcnt(8)
	s_waitcnt lgkmcnt(0)
	s_barrier
	s_setprio 1
	s_waitcnt lgkmcnt(0)
	v_mfma_f32_16x16x32_bf16 v[60:63], v[198:201], v[166:169], v[60:63]
	v_mfma_f32_16x16x32_bf16 v[56:59], v[198:201], v[174:177], v[56:59]
	v_mfma_f32_16x16x32_bf16 v[44:47], v[206:209], v[166:169], v[44:47]
	v_mfma_f32_16x16x32_bf16 v[40:43], v[206:209], v[174:177], v[40:43]
	v_mfma_f32_16x16x32_bf16 v[28:31], v[216:219], v[166:169], v[28:31]
	v_mfma_f32_16x16x32_bf16 v[24:27], v[216:219], v[174:177], v[24:27]
	v_mfma_f32_16x16x32_bf16 v[12:15], v[224:227], v[166:169], v[12:15]
	v_mfma_f32_16x16x32_bf16 v[8:11], v[224:227], v[174:177], v[8:11]
	v_mfma_f32_16x16x32_bf16 v[60:63], v[202:205], v[170:173], v[60:63]
	v_mfma_f32_16x16x32_bf16 v[56:59], v[202:205], v[178:181], v[56:59]
	v_mfma_f32_16x16x32_bf16 v[44:47], v[212:215], v[170:173], v[44:47]
	v_mfma_f32_16x16x32_bf16 v[40:43], v[212:215], v[178:181], v[40:43]
	v_mfma_f32_16x16x32_bf16 v[28:31], v[220:223], v[170:173], v[28:31]
	v_mfma_f32_16x16x32_bf16 v[24:27], v[220:223], v[178:181], v[24:27]
	v_mfma_f32_16x16x32_bf16 v[12:15], v[228:231], v[170:173], v[12:15]
	v_mfma_f32_16x16x32_bf16 v[8:11], v[228:231], v[178:181], v[8:11]
	s_setprio 0
	s_setprio 1
	v_mfma_f32_16x16x32_bf16 v[52:55], v[198:201], v[182:185], v[52:55]
	v_mfma_f32_16x16x32_bf16 v[48:51], v[198:201], v[190:193], v[48:51]
	v_mfma_f32_16x16x32_bf16 v[36:39], v[206:209], v[182:185], v[36:39]
	v_mfma_f32_16x16x32_bf16 v[32:35], v[206:209], v[190:193], v[32:35]
	v_mfma_f32_16x16x32_bf16 v[20:23], v[216:219], v[182:185], v[20:23]
	v_mfma_f32_16x16x32_bf16 v[16:19], v[216:219], v[190:193], v[16:19]
	v_mfma_f32_16x16x32_bf16 v[4:7], v[224:227], v[182:185], v[4:7]
	v_mfma_f32_16x16x32_bf16 v[0:3], v[224:227], v[190:193], v[0:3]
	v_mfma_f32_16x16x32_bf16 v[52:55], v[202:205], v[186:189], v[52:55]
	v_mfma_f32_16x16x32_bf16 v[48:51], v[202:205], v[194:197], v[48:51]
	v_mfma_f32_16x16x32_bf16 v[36:39], v[212:215], v[186:189], v[36:39]
	v_mfma_f32_16x16x32_bf16 v[32:35], v[212:215], v[194:197], v[32:35]
	v_mfma_f32_16x16x32_bf16 v[20:23], v[220:223], v[186:189], v[20:23]
	v_mfma_f32_16x16x32_bf16 v[16:19], v[220:223], v[194:197], v[16:19]
	v_mfma_f32_16x16x32_bf16 v[4:7], v[228:231], v[186:189], v[4:7]
	v_mfma_f32_16x16x32_bf16 v[0:3], v[228:231], v[194:197], v[0:3]
	s_setprio 0
	s_barrier
	s_add_i32 s68, s68, 2
	s_add_u32 s44, s44, 0x100
	s_addc_u32 s45, s45, 0
	s_cmp_gt_u32 s68, 13
	s_cbranch_scc0 .LBB0_1853
	s_and_saveexec_b64 s[44:45], s[8:9]
	s_cbranch_execz .LBB0_1856
	s_barrier
.LBB0_1856:
	s_or_b64 exec, exec, s[44:45]
	s_lshl_b32 s21, s42, 8
	v_mov_b32_e32 v137, 0
	v_lshl_or_b32 v138, s28, 8, v155
	v_add3_u32 v136, v154, s21, v137
	v_add_u32_e32 v138, v138, v137
	v_ashrrev_i32_e32 v137, 31, v136
	v_max_f32_e32 v124, v124, v124
	v_lshlrev_b64 v[166:167], 13, v[136:137]
	v_ashrrev_i32_e32 v139, 31, v138
	v_max_f32_e32 v124, 0, v124
	v_max_f32_e32 v112, v112, v112
	v_lshl_add_u64 v[166:167], s[36:37], 0, v[166:167]
	v_lshlrev_b64 v[138:139], 1, v[138:139]
	v_mul_f32_e32 v124, v124, v124
	v_max_f32_e32 v112, 0, v112
	v_lshl_add_u64 v[166:167], v[166:167], 0, v[138:139]
	v_cvt_pk_bf16_f32 v124, v124, s0
	v_mul_f32_e32 v112, v112, v112
	global_store_short v[166:167], v124, off
	v_max_f32_e32 v124, v125, v125
	v_cvt_pk_bf16_f32 v112, v112, s0
	v_max_f32_e32 v124, 0, v124
	global_store_short v[166:167], v112, off offset:288
	v_max_f32_e32 v112, v113, v113
	v_mul_f32_e32 v124, v124, v124
	v_max_f32_e32 v112, 0, v112
	v_cvt_pk_bf16_f32 v137, v124, s0
	v_add_co_u32_e32 v124, vcc, s3, v166
	v_mul_f32_e32 v112, v112, v112
	s_nop 0
	v_addc_co_u32_e32 v125, vcc, 0, v167, vcc
	v_max_f32_e32 v126, v126, v126
	v_cvt_pk_bf16_f32 v112, v112, s0
	v_max_f32_e32 v126, 0, v126
	global_store_short v[124:125], v112, off offset:288
	v_max_f32_e32 v112, v114, v114
	v_mul_f32_e32 v126, v126, v126
	v_add_co_u32_e32 v168, vcc, s29, v166
	v_max_f32_e32 v112, 0, v112
	v_cvt_pk_bf16_f32 v126, v126, s0
	v_addc_co_u32_e32 v169, vcc, 0, v167, vcc
	v_mul_f32_e32 v112, v112, v112
	global_store_short v[168:169], v126, off
	v_max_f32_e32 v126, v127, v127
	v_cvt_pk_bf16_f32 v112, v112, s0
	v_max_f32_e32 v126, 0, v126
	global_store_short v[168:169], v112, off offset:288
	v_max_f32_e32 v112, v115, v115
	v_mul_f32_e32 v126, v126, v126
	v_max_f32_e32 v112, 0, v112
	global_store_short v[124:125], v137, off
; DI bf16_t f2bf(float x) { return (bf16_t)(cvt_pk(x, 0.f) & 0xffffu); }
; DI float ex2(float x) { return __builtin_amdgcn_exp2f(x); }
;     ...
;         bf16_t* d = (bf16_t*)(p.ws + OFF_U) + (size_t)row0 * 4096 + col;
; #pragma unroll
;         for (int e = 0; e < 4; ++e) { const float t = fmaxf(v[e], 0.f); d[(size_t)e * 4096] = f2bf(t * t); }
; template <int EPI, int K, int LNI = -1>
; DI void ph_gemm(const Params& p, const bf16_t* __restrict__ A, const bf16_t* __restrict__ Bt, int N, float* s_aux) {
;     ...
;             for (int ai = 0; ai < 2; ++ai)
; #pragma unroll
;                 for (int m = 0; m < 4; ++m) {
;                     const int lrow0 = ai * 128 + wr * 64 + m * 16 + fq * 4, row0 = brow + lrow0 + oz;
;                     f32x2 rs[4];
;                     if (EPI == EPI_RESID && LNI >= 0) {
;                         const f32x2* st_ = (const f32x2*)((unsigned char*)p.out + OFFO_STATS) + row0;
; #pragma unroll
;                         for (int e = 0; e < 4; ++e) rs[e] = st_[e];
;                     }
;                     if (EPI == EPI_E5) {
;                         const int idx_ = ((row0 % LT) + 48) & 63; const float lgh = lg_[0][0];
; #pragma unroll
;                         for (int e = 0; e < 4; ++e) rs[e] = (f32x2){ex2(lgh * (float)(idx_ + e + 1)), 0.0625f * ex2(lgh * (float)(63 - idx_ - e))};
;                     }
; #pragma unroll
;                     for (int bj = 0; bj < 2; ++bj)
; #pragma unroll
;                         for (int n = 0; n < 2; ++n) {
;                             float v[4];
; #pragma unroll
;                             for (int e = 0; e < 4; ++e) v[e] = acc[ai][bj][m][n][e];
;                             epi_store<EPI, LNI>(p, row0, bcol + bj * 128 + wc * 32 + n * 16 + fr + oz, lrow0, v, sa, rs, lg_[bj][n], lb_[bj][n]);
	v_cvt_pk_bf16_f32 v137, v126, s0
	v_add_co_u32_e32 v126, vcc, s35, v166
	v_mul_f32_e32 v112, v112, v112
	s_nop 0
	v_addc_co_u32_e32 v127, vcc, 0, v167, vcc
	v_cvt_pk_bf16_f32 v112, v112, s0
	v_max_f32_e32 v116, v116, v116
	global_store_short v[126:127], v112, off offset:288
	v_add_u32_e32 v112, 16, v136
	v_max_f32_e32 v116, 0, v116
	v_ashrrev_i32_e32 v113, 31, v112
	v_max_f32_e32 v108, v108, v108
	v_mul_f32_e32 v116, v116, v116
	v_lshlrev_b64 v[112:113], 13, v[112:113]
	v_max_f32_e32 v108, 0, v108
	v_max_f32_e32 v96, v96, v96
	v_cvt_pk_bf16_f32 v116, v116, s0
	v_lshl_add_u64 v[112:113], s[36:37], 0, v[112:113]
	v_mul_f32_e32 v108, v108, v108
	v_max_f32_e32 v96, 0, v96
	global_store_short v[166:167], v116, off offset:256
	v_max_f32_e32 v116, v117, v117
	v_lshl_add_u64 v[112:113], v[112:113], 0, v[138:139]
	v_cvt_pk_bf16_f32 v108, v108, s0
	v_mul_f32_e32 v96, v96, v96
	v_max_f32_e32 v116, 0, v116
	global_store_short v[112:113], v108, off
	v_max_f32_e32 v108, v109, v109
	v_cvt_pk_bf16_f32 v96, v96, s0
	v_mul_f32_e32 v116, v116, v116
	v_max_f32_e32 v108, 0, v108
	global_store_short v[112:113], v96, off offset:288
	v_max_f32_e32 v96, v97, v97
	v_cvt_pk_bf16_f32 v116, v116, s0
	v_mul_f32_e32 v108, v108, v108
	v_max_f32_e32 v96, 0, v96
	global_store_short v[124:125], v116, off offset:256
	v_max_f32_e32 v116, v118, v118
	v_cvt_pk_bf16_f32 v114, v108, s0
	v_add_co_u32_e32 v108, vcc, s3, v112
	v_mul_f32_e32 v96, v96, v96
	v_max_f32_e32 v116, 0, v116
	v_addc_co_u32_e32 v109, vcc, 0, v113, vcc
	v_max_f32_e32 v110, v110, v110
	v_cvt_pk_bf16_f32 v96, v96, s0
	v_mul_f32_e32 v116, v116, v116
	v_max_f32_e32 v110, 0, v110
	global_store_short v[108:109], v96, off offset:288
	v_max_f32_e32 v96, v98, v98
	v_cvt_pk_bf16_f32 v116, v116, s0
	global_store_short v[108:109], v114, off
	v_mul_f32_e32 v110, v110, v110
	v_add_co_u32_e32 v114, vcc, s29, v112
	v_max_f32_e32 v96, 0, v96
	global_store_short v[168:169], v116, off offset:256
	v_max_f32_e32 v116, v119, v119
	v_cvt_pk_bf16_f32 v110, v110, s0
	v_addc_co_u32_e32 v115, vcc, 0, v113, vcc
	v_mul_f32_e32 v96, v96, v96
	v_max_f32_e32 v116, 0, v116
	global_store_short v[114:115], v110, off
	v_max_f32_e32 v110, v111, v111
	v_cvt_pk_bf16_f32 v96, v96, s0
	v_mul_f32_e32 v116, v116, v116
	v_max_f32_e32 v110, 0, v110
	global_store_short v[114:115], v96, off offset:288
	v_max_f32_e32 v96, v99, v99
	v_cvt_pk_bf16_f32 v116, v116, s0
	v_mul_f32_e32 v110, v110, v110
	v_max_f32_e32 v96, 0, v96
	global_store_short v[126:127], v116, off offset:256
	v_cvt_pk_bf16_f32 v116, v110, s0
	v_add_co_u32_e32 v110, vcc, s35, v112
	v_mul_f32_e32 v96, v96, v96
	s_nop 0
	v_addc_co_u32_e32 v111, vcc, 0, v113, vcc
	v_cvt_pk_bf16_f32 v96, v96, s0
	v_max_f32_e32 v100, v100, v100
	global_store_short v[110:111], v96, off offset:288
	v_add_u32_e32 v96, 32, v136
	v_max_f32_e32 v100, 0, v100
	v_ashrrev_i32_e32 v97, 31, v96
	v_max_f32_e32 v92, v92, v92
	v_mul_f32_e32 v100, v100, v100
	v_lshlrev_b64 v[96:97], 13, v[96:97]
	v_max_f32_e32 v92, 0, v92
	v_max_f32_e32 v80, v80, v80
	v_cvt_pk_bf16_f32 v100, v100, s0
	v_lshl_add_u64 v[96:97], s[36:37], 0, v[96:97]
	v_mul_f32_e32 v92, v92, v92
	v_max_f32_e32 v80, 0, v80
	global_store_short v[112:113], v100, off offset:256
	v_max_f32_e32 v100, v101, v101
	v_lshl_add_u64 v[96:97], v[96:97], 0, v[138:139]
	v_cvt_pk_bf16_f32 v92, v92, s0
	v_mul_f32_e32 v80, v80, v80
	v_max_f32_e32 v100, 0, v100
	global_store_short v[96:97], v92, off
	v_max_f32_e32 v92, v93, v93
	v_cvt_pk_bf16_f32 v80, v80, s0
	v_mul_f32_e32 v100, v100, v100
	v_max_f32_e32 v92, 0, v92
	global_store_short v[96:97], v80, off offset:288
	v_max_f32_e32 v80, v81, v81
	v_cvt_pk_bf16_f32 v100, v100, s0
	v_mul_f32_e32 v92, v92, v92
	v_max_f32_e32 v80, 0, v80
	global_store_short v[108:109], v100, off offset:256
	v_max_f32_e32 v100, v102, v102
	v_cvt_pk_bf16_f32 v98, v92, s0
	v_add_co_u32_e32 v92, vcc, s3, v96
	v_mul_f32_e32 v80, v80, v80
	v_max_f32_e32 v100, 0, v100
	v_addc_co_u32_e32 v93, vcc, 0, v97, vcc
	v_max_f32_e32 v94, v94, v94
	v_cvt_pk_bf16_f32 v80, v80, s0
	v_mul_f32_e32 v100, v100, v100
	v_max_f32_e32 v94, 0, v94
	global_store_short v[92:93], v80, off offset:288
	v_max_f32_e32 v80, v82, v82
	v_cvt_pk_bf16_f32 v100, v100, s0
	global_store_short v[92:93], v98, off
	v_mul_f32_e32 v94, v94, v94
	v_add_co_u32_e32 v98, vcc, s29, v96
	v_max_f32_e32 v80, 0, v80
	global_store_short v[114:115], v100, off offset:256
	v_max_f32_e32 v100, v103, v103
	v_cvt_pk_bf16_f32 v94, v94, s0
	v_addc_co_u32_e32 v99, vcc, 0, v97, vcc
	v_mul_f32_e32 v80, v80, v80
	v_max_f32_e32 v100, 0, v100
	global_store_short v[98:99], v94, off
	v_max_f32_e32 v94, v95, v95
	v_cvt_pk_bf16_f32 v80, v80, s0
	v_mul_f32_e32 v100, v100, v100
	v_max_f32_e32 v94, 0, v94
	global_store_short v[98:99], v80, off offset:288
	v_max_f32_e32 v80, v83, v83
	v_cvt_pk_bf16_f32 v100, v100, s0
	v_mul_f32_e32 v94, v94, v94
	v_max_f32_e32 v80, 0, v80
	global_store_short v[110:111], v100, off offset:256
	v_cvt_pk_bf16_f32 v100, v94, s0
	v_add_co_u32_e32 v94, vcc, s35, v96
	v_mul_f32_e32 v80, v80, v80
	s_nop 0
	v_addc_co_u32_e32 v95, vcc, 0, v97, vcc
	v_cvt_pk_bf16_f32 v80, v80, s0
	v_max_f32_e32 v84, v84, v84
	global_store_short v[94:95], v80, off offset:288
	v_add_u32_e32 v80, 48, v136
	v_max_f32_e32 v84, 0, v84
	v_ashrrev_i32_e32 v81, 31, v80
	v_max_f32_e32 v76, v76, v76
	v_mul_f32_e32 v84, v84, v84
	v_lshlrev_b64 v[80:81], 13, v[80:81]
	v_max_f32_e32 v76, 0, v76
	v_max_f32_e32 v64, v64, v64
	v_cvt_pk_bf16_f32 v84, v84, s0
	v_lshl_add_u64 v[80:81], s[36:37], 0, v[80:81]
	v_mul_f32_e32 v76, v76, v76
	v_max_f32_e32 v64, 0, v64
	global_store_short v[96:97], v84, off offset:256
	v_max_f32_e32 v84, v85, v85
; DI bf16_t f2bf(float x) { return (bf16_t)(cvt_pk(x, 0.f) & 0xffffu); }
; DI float ex2(float x) { return __builtin_amdgcn_exp2f(x); }
;     ...
;         bf16_t* d = (bf16_t*)(p.ws + OFF_U) + (size_t)row0 * 4096 + col;
; #pragma unroll
;         for (int e = 0; e < 4; ++e) { const float t = fmaxf(v[e], 0.f); d[(size_t)e * 4096] = f2bf(t * t); }
; template <int EPI, int K, int LNI = -1>
; DI void ph_gemm(const Params& p, const bf16_t* __restrict__ A, const bf16_t* __restrict__ Bt, int N, float* s_aux) {
;     ...
;             for (int ai = 0; ai < 2; ++ai)
; #pragma unroll
;                 for (int m = 0; m < 4; ++m) {
;                     const int lrow0 = ai * 128 + wr * 64 + m * 16 + fq * 4, row0 = brow + lrow0 + oz;
;                     f32x2 rs[4];
;                     if (EPI == EPI_RESID && LNI >= 0) {
;                         const f32x2* st_ = (const f32x2*)((unsigned char*)p.out + OFFO_STATS) + row0;
; #pragma unroll
;                         for (int e = 0; e < 4; ++e) rs[e] = st_[e];
;                     }
;                     if (EPI == EPI_E5) {
;                         const int idx_ = ((row0 % LT) + 48) & 63; const float lgh = lg_[0][0];
; #pragma unroll
;                         for (int e = 0; e < 4; ++e) rs[e] = (f32x2){ex2(lgh * (float)(idx_ + e + 1)), 0.0625f * ex2(lgh * (float)(63 - idx_ - e))};
;                     }
; #pragma unroll
;                     for (int bj = 0; bj < 2; ++bj)
; #pragma unroll
;                         for (int n = 0; n < 2; ++n) {
;                             float v[4];
; #pragma unroll
;                             for (int e = 0; e < 4; ++e) v[e] = acc[ai][bj][m][n][e];
;                             epi_store<EPI, LNI>(p, row0, bcol + bj * 128 + wc * 32 + n * 16 + fr + oz, lrow0, v, sa, rs, lg_[bj][n], lb_[bj][n]);
	v_lshl_add_u64 v[80:81], v[80:81], 0, v[138:139]
	v_cvt_pk_bf16_f32 v76, v76, s0
	v_mul_f32_e32 v64, v64, v64
	v_max_f32_e32 v84, 0, v84
	global_store_short v[80:81], v76, off
	v_max_f32_e32 v76, v77, v77
	v_cvt_pk_bf16_f32 v64, v64, s0
	v_mul_f32_e32 v84, v84, v84
	v_max_f32_e32 v76, 0, v76
	global_store_short v[80:81], v64, off offset:288
	v_max_f32_e32 v64, v65, v65
	v_cvt_pk_bf16_f32 v84, v84, s0
	v_mul_f32_e32 v76, v76, v76
	v_max_f32_e32 v64, 0, v64
	global_store_short v[92:93], v84, off offset:256
	v_max_f32_e32 v84, v86, v86
	v_cvt_pk_bf16_f32 v82, v76, s0
	v_add_co_u32_e32 v76, vcc, s3, v80
	v_mul_f32_e32 v64, v64, v64
	v_max_f32_e32 v84, 0, v84
	v_addc_co_u32_e32 v77, vcc, 0, v81, vcc
	v_max_f32_e32 v78, v78, v78
	v_cvt_pk_bf16_f32 v64, v64, s0
	v_mul_f32_e32 v84, v84, v84
	v_max_f32_e32 v78, 0, v78
	global_store_short v[76:77], v64, off offset:288
	v_max_f32_e32 v64, v66, v66
	v_cvt_pk_bf16_f32 v84, v84, s0
	global_store_short v[76:77], v82, off
	v_mul_f32_e32 v78, v78, v78
	v_add_co_u32_e32 v82, vcc, s29, v80
	v_max_f32_e32 v64, 0, v64
	global_store_short v[98:99], v84, off offset:256
	v_max_f32_e32 v84, v87, v87
	v_cvt_pk_bf16_f32 v78, v78, s0
	v_addc_co_u32_e32 v83, vcc, 0, v81, vcc
	v_mul_f32_e32 v64, v64, v64
	v_max_f32_e32 v84, 0, v84
	global_store_short v[82:83], v78, off
	v_max_f32_e32 v78, v79, v79
	v_cvt_pk_bf16_f32 v64, v64, s0
	v_mul_f32_e32 v84, v84, v84
	v_max_f32_e32 v78, 0, v78
	global_store_short v[82:83], v64, off offset:288
	v_max_f32_e32 v64, v67, v67
	v_cvt_pk_bf16_f32 v84, v84, s0
	v_mul_f32_e32 v78, v78, v78
	v_max_f32_e32 v64, 0, v64
	global_store_short v[94:95], v84, off offset:256
	v_cvt_pk_bf16_f32 v84, v78, s0
	v_add_co_u32_e32 v78, vcc, s35, v80
	v_mul_f32_e32 v64, v64, v64
	s_nop 0
	v_addc_co_u32_e32 v79, vcc, 0, v81, vcc
	v_cvt_pk_bf16_f32 v64, v64, s0
	v_max_f32_e32 v68, v68, v68
	global_store_short v[78:79], v64, off offset:288
	v_add_u32_e32 v64, 0x80, v136
	v_max_f32_e32 v68, 0, v68
	v_ashrrev_i32_e32 v65, 31, v64
	v_max_f32_e32 v60, v60, v60
	v_mul_f32_e32 v68, v68, v68
	v_lshlrev_b64 v[64:65], 13, v[64:65]
	v_max_f32_e32 v60, 0, v60
	v_max_f32_e32 v48, v48, v48
	v_cvt_pk_bf16_f32 v68, v68, s0
	v_lshl_add_u64 v[64:65], s[36:37], 0, v[64:65]
	v_mul_f32_e32 v60, v60, v60
	v_max_f32_e32 v48, 0, v48
	global_store_short v[80:81], v68, off offset:256
	v_max_f32_e32 v68, v69, v69
	v_lshl_add_u64 v[64:65], v[64:65], 0, v[138:139]
	v_cvt_pk_bf16_f32 v60, v60, s0
	v_mul_f32_e32 v48, v48, v48
	v_max_f32_e32 v68, 0, v68
	global_store_short v[64:65], v60, off
	v_max_f32_e32 v60, v61, v61
	v_cvt_pk_bf16_f32 v48, v48, s0
	v_mul_f32_e32 v68, v68, v68
	v_max_f32_e32 v60, 0, v60
	global_store_short v[64:65], v48, off offset:288
	v_max_f32_e32 v48, v49, v49
	v_cvt_pk_bf16_f32 v68, v68, s0
	v_mul_f32_e32 v60, v60, v60
	v_max_f32_e32 v48, 0, v48
	global_store_short v[76:77], v68, off offset:256
	v_max_f32_e32 v68, v70, v70
	v_cvt_pk_bf16_f32 v66, v60, s0
	v_add_co_u32_e32 v60, vcc, s3, v64
	v_mul_f32_e32 v48, v48, v48
	v_max_f32_e32 v68, 0, v68
	v_addc_co_u32_e32 v61, vcc, 0, v65, vcc
	v_max_f32_e32 v62, v62, v62
	v_cvt_pk_bf16_f32 v48, v48, s0
	v_mul_f32_e32 v68, v68, v68
	v_max_f32_e32 v62, 0, v62
	global_store_short v[60:61], v48, off offset:288
	v_max_f32_e32 v48, v50, v50
	v_cvt_pk_bf16_f32 v68, v68, s0
	global_store_short v[60:61], v66, off
	v_mul_f32_e32 v62, v62, v62
	v_add_co_u32_e32 v66, vcc, s29, v64
	v_max_f32_e32 v48, 0, v48
	global_store_short v[82:83], v68, off offset:256
	v_max_f32_e32 v68, v71, v71
	v_cvt_pk_bf16_f32 v62, v62, s0
	v_addc_co_u32_e32 v67, vcc, 0, v65, vcc
	v_mul_f32_e32 v48, v48, v48
	v_max_f32_e32 v68, 0, v68
	global_store_short v[66:67], v62, off
	v_max_f32_e32 v62, v63, v63
	v_cvt_pk_bf16_f32 v48, v48, s0
	v_mul_f32_e32 v68, v68, v68
	v_max_f32_e32 v62, 0, v62
	global_store_short v[66:67], v48, off offset:288
	v_max_f32_e32 v48, v51, v51
	v_cvt_pk_bf16_f32 v68, v68, s0
	v_mul_f32_e32 v62, v62, v62
	v_max_f32_e32 v48, 0, v48
	global_store_short v[78:79], v68, off offset:256
	v_cvt_pk_bf16_f32 v68, v62, s0
	v_add_co_u32_e32 v62, vcc, s35, v64
	v_mul_f32_e32 v48, v48, v48
	s_nop 0
	v_addc_co_u32_e32 v63, vcc, 0, v65, vcc
	v_cvt_pk_bf16_f32 v48, v48, s0
	v_max_f32_e32 v52, v52, v52
	global_store_short v[62:63], v48, off offset:288
	v_add_u32_e32 v48, 0x90, v136
	v_max_f32_e32 v52, 0, v52
	v_ashrrev_i32_e32 v49, 31, v48
	v_max_f32_e32 v44, v44, v44
	v_mul_f32_e32 v52, v52, v52
	v_lshlrev_b64 v[48:49], 13, v[48:49]
	v_max_f32_e32 v44, 0, v44
	v_max_f32_e32 v32, v32, v32
	v_cvt_pk_bf16_f32 v52, v52, s0
	v_lshl_add_u64 v[48:49], s[36:37], 0, v[48:49]
	v_mul_f32_e32 v44, v44, v44
	v_max_f32_e32 v32, 0, v32
	global_store_short v[64:65], v52, off offset:256
	v_max_f32_e32 v52, v53, v53
	v_lshl_add_u64 v[48:49], v[48:49], 0, v[138:139]
	v_cvt_pk_bf16_f32 v44, v44, s0
	v_mul_f32_e32 v32, v32, v32
	v_max_f32_e32 v52, 0, v52
	global_store_short v[48:49], v44, off
	v_max_f32_e32 v44, v45, v45
	v_cvt_pk_bf16_f32 v32, v32, s0
	v_mul_f32_e32 v52, v52, v52
	v_max_f32_e32 v44, 0, v44
	global_store_short v[48:49], v32, off offset:288
	v_max_f32_e32 v32, v33, v33
	v_cvt_pk_bf16_f32 v52, v52, s0
	v_mul_f32_e32 v44, v44, v44
	v_max_f32_e32 v32, 0, v32
	global_store_short v[60:61], v52, off offset:256
	v_max_f32_e32 v52, v54, v54
	v_cvt_pk_bf16_f32 v50, v44, s0
	v_add_co_u32_e32 v44, vcc, s3, v48
	v_mul_f32_e32 v32, v32, v32
	v_max_f32_e32 v52, 0, v52
	v_addc_co_u32_e32 v45, vcc, 0, v49, vcc
	v_max_f32_e32 v46, v46, v46
	v_cvt_pk_bf16_f32 v32, v32, s0
	v_mul_f32_e32 v52, v52, v52
	v_max_f32_e32 v46, 0, v46
	global_store_short v[44:45], v32, off offset:288
	v_max_f32_e32 v32, v34, v34
; DI bf16_t f2bf(float x) { return (bf16_t)(cvt_pk(x, 0.f) & 0xffffu); }
; DI float ex2(float x) { return __builtin_amdgcn_exp2f(x); }
;     ...
;         bf16_t* d = (bf16_t*)(p.ws + OFF_U) + (size_t)row0 * 4096 + col;
; #pragma unroll
;         for (int e = 0; e < 4; ++e) { const float t = fmaxf(v[e], 0.f); d[(size_t)e * 4096] = f2bf(t * t); }
; template <int EPI, int K, int LNI = -1>
; DI void ph_gemm(const Params& p, const bf16_t* __restrict__ A, const bf16_t* __restrict__ Bt, int N, float* s_aux) {
;     ...
;             for (int ai = 0; ai < 2; ++ai)
; #pragma unroll
;                 for (int m = 0; m < 4; ++m) {
;                     const int lrow0 = ai * 128 + wr * 64 + m * 16 + fq * 4, row0 = brow + lrow0 + oz;
;                     f32x2 rs[4];
;                     if (EPI == EPI_RESID && LNI >= 0) {
;                         const f32x2* st_ = (const f32x2*)((unsigned char*)p.out + OFFO_STATS) + row0;
; #pragma unroll
;                         for (int e = 0; e < 4; ++e) rs[e] = st_[e];
;                     }
;                     if (EPI == EPI_E5) {
;                         const int idx_ = ((row0 % LT) + 48) & 63; const float lgh = lg_[0][0];
; #pragma unroll
;                         for (int e = 0; e < 4; ++e) rs[e] = (f32x2){ex2(lgh * (float)(idx_ + e + 1)), 0.0625f * ex2(lgh * (float)(63 - idx_ - e))};
;                     }
; #pragma unroll
;                     for (int bj = 0; bj < 2; ++bj)
; #pragma unroll
;                         for (int n = 0; n < 2; ++n) {
;                             float v[4];
; #pragma unroll
;                             for (int e = 0; e < 4; ++e) v[e] = acc[ai][bj][m][n][e];
;                             epi_store<EPI, LNI>(p, row0, bcol + bj * 128 + wc * 32 + n * 16 + fr + oz, lrow0, v, sa, rs, lg_[bj][n], lb_[bj][n]);
	v_cvt_pk_bf16_f32 v52, v52, s0
	global_store_short v[44:45], v50, off
	v_mul_f32_e32 v46, v46, v46
	v_add_co_u32_e32 v50, vcc, s29, v48
	v_max_f32_e32 v32, 0, v32
	global_store_short v[66:67], v52, off offset:256
	v_max_f32_e32 v52, v55, v55
	v_cvt_pk_bf16_f32 v46, v46, s0
	v_addc_co_u32_e32 v51, vcc, 0, v49, vcc
	v_mul_f32_e32 v32, v32, v32
	v_max_f32_e32 v52, 0, v52
	global_store_short v[50:51], v46, off
	v_max_f32_e32 v46, v47, v47
	v_cvt_pk_bf16_f32 v32, v32, s0
	v_mul_f32_e32 v52, v52, v52
	v_max_f32_e32 v46, 0, v46
	global_store_short v[50:51], v32, off offset:288
	v_max_f32_e32 v32, v35, v35
	v_cvt_pk_bf16_f32 v52, v52, s0
	v_mul_f32_e32 v46, v46, v46
	v_max_f32_e32 v32, 0, v32
	global_store_short v[62:63], v52, off offset:256
	v_cvt_pk_bf16_f32 v52, v46, s0
	v_add_co_u32_e32 v46, vcc, s35, v48
	v_mul_f32_e32 v32, v32, v32
	s_nop 0
	v_addc_co_u32_e32 v47, vcc, 0, v49, vcc
	v_cvt_pk_bf16_f32 v32, v32, s0
	v_max_f32_e32 v36, v36, v36
	global_store_short v[46:47], v32, off offset:288
	v_add_u32_e32 v32, 0xa0, v136
	v_max_f32_e32 v36, 0, v36
	v_ashrrev_i32_e32 v33, 31, v32
	v_max_f32_e32 v28, v28, v28
	v_mul_f32_e32 v36, v36, v36
	v_lshlrev_b64 v[32:33], 13, v[32:33]
	v_max_f32_e32 v28, 0, v28
	v_max_f32_e32 v16, v16, v16
	v_cvt_pk_bf16_f32 v36, v36, s0
	v_lshl_add_u64 v[32:33], s[36:37], 0, v[32:33]
	v_mul_f32_e32 v28, v28, v28
	v_max_f32_e32 v16, 0, v16
	global_store_short v[48:49], v36, off offset:256
	v_max_f32_e32 v36, v37, v37
	v_lshl_add_u64 v[32:33], v[32:33], 0, v[138:139]
	v_cvt_pk_bf16_f32 v28, v28, s0
	v_mul_f32_e32 v16, v16, v16
	v_max_f32_e32 v36, 0, v36
	global_store_short v[32:33], v28, off
	v_max_f32_e32 v28, v29, v29
	v_cvt_pk_bf16_f32 v16, v16, s0
	v_mul_f32_e32 v36, v36, v36
	v_max_f32_e32 v28, 0, v28
	global_store_short v[32:33], v16, off offset:288
	v_max_f32_e32 v16, v17, v17
	v_cvt_pk_bf16_f32 v36, v36, s0
	v_mul_f32_e32 v28, v28, v28
	v_max_f32_e32 v16, 0, v16
	global_store_short v[44:45], v36, off offset:256
	v_max_f32_e32 v36, v38, v38
	v_cvt_pk_bf16_f32 v34, v28, s0
	v_add_co_u32_e32 v28, vcc, s3, v32
	v_mul_f32_e32 v16, v16, v16
	v_max_f32_e32 v36, 0, v36
	v_addc_co_u32_e32 v29, vcc, 0, v33, vcc
	v_max_f32_e32 v30, v30, v30
	v_cvt_pk_bf16_f32 v16, v16, s0
	v_mul_f32_e32 v36, v36, v36
	v_max_f32_e32 v30, 0, v30
	global_store_short v[28:29], v16, off offset:288
	v_max_f32_e32 v16, v18, v18
	v_cvt_pk_bf16_f32 v36, v36, s0
	global_store_short v[28:29], v34, off
	v_mul_f32_e32 v30, v30, v30
	v_add_co_u32_e32 v34, vcc, s29, v32
	v_max_f32_e32 v16, 0, v16
	global_store_short v[50:51], v36, off offset:256
	v_max_f32_e32 v36, v39, v39
	v_cvt_pk_bf16_f32 v30, v30, s0
	v_addc_co_u32_e32 v35, vcc, 0, v33, vcc
	v_mul_f32_e32 v16, v16, v16
	v_max_f32_e32 v36, 0, v36
	global_store_short v[34:35], v30, off
	v_max_f32_e32 v30, v31, v31
	v_cvt_pk_bf16_f32 v16, v16, s0
	v_mul_f32_e32 v36, v36, v36
	v_max_f32_e32 v30, 0, v30
	global_store_short v[34:35], v16, off offset:288
	v_max_f32_e32 v16, v19, v19
	v_cvt_pk_bf16_f32 v36, v36, s0
	v_mul_f32_e32 v30, v30, v30
	v_max_f32_e32 v16, 0, v16
	global_store_short v[46:47], v36, off offset:256
	v_cvt_pk_bf16_f32 v36, v30, s0
	v_add_co_u32_e32 v30, vcc, s35, v32
	v_mul_f32_e32 v16, v16, v16
	s_nop 0
	v_addc_co_u32_e32 v31, vcc, 0, v33, vcc
	v_max_f32_e32 v20, v20, v20
	v_cvt_pk_bf16_f32 v16, v16, s0
	v_max_f32_e32 v20, 0, v20
	global_store_short v[30:31], v16, off offset:288
	v_add_u32_e32 v16, 0xb0, v136
	v_mul_f32_e32 v20, v20, v20
	v_ashrrev_i32_e32 v17, 31, v16
	v_max_f32_e32 v12, v12, v12
	v_max_f32_e32 v120, v120, v120
	v_max_f32_e32 v104, v104, v104
	v_max_f32_e32 v88, v88, v88
	v_max_f32_e32 v72, v72, v72
	v_max_f32_e32 v56, v56, v56
	v_max_f32_e32 v40, v40, v40
	v_max_f32_e32 v24, v24, v24
	v_cvt_pk_bf16_f32 v20, v20, s0
	v_lshlrev_b64 v[16:17], 13, v[16:17]
	v_max_f32_e32 v12, 0, v12
	v_max_f32_e32 v8, v8, v8
	v_max_f32_e32 v4, v4, v4
	v_max_f32_e32 v0, v0, v0
	v_max_f32_e32 v120, 0, v120
	v_max_f32_e32 v104, 0, v104
	v_max_f32_e32 v88, 0, v88
	v_max_f32_e32 v72, 0, v72
	v_max_f32_e32 v56, 0, v56
	v_max_f32_e32 v40, 0, v40
	v_max_f32_e32 v24, 0, v24
	global_store_short v[32:33], v20, off offset:256
	v_max_f32_e32 v20, v21, v21
	v_lshl_add_u64 v[16:17], s[36:37], 0, v[16:17]
	v_mul_f32_e32 v12, v12, v12
	v_max_f32_e32 v8, 0, v8
	v_max_f32_e32 v4, 0, v4
	v_max_f32_e32 v0, 0, v0
	v_mul_f32_e32 v120, v120, v120
	v_mul_f32_e32 v104, v104, v104
	v_mul_f32_e32 v88, v88, v88
	v_mul_f32_e32 v72, v72, v72
	v_mul_f32_e32 v56, v56, v56
	v_mul_f32_e32 v40, v40, v40
	v_mul_f32_e32 v24, v24, v24
	v_max_f32_e32 v20, 0, v20
	v_lshl_add_u64 v[16:17], v[16:17], 0, v[138:139]
	v_cvt_pk_bf16_f32 v12, v12, s0
	v_mul_f32_e32 v8, v8, v8
	v_mul_f32_e32 v4, v4, v4
	v_mul_f32_e32 v0, v0, v0
	v_cvt_pk_bf16_f32 v120, v120, s0
	v_cvt_pk_bf16_f32 v104, v104, s0
	v_cvt_pk_bf16_f32 v88, v88, s0
	v_cvt_pk_bf16_f32 v72, v72, s0
	v_cvt_pk_bf16_f32 v56, v56, s0
	v_cvt_pk_bf16_f32 v40, v40, s0
	v_cvt_pk_bf16_f32 v24, v24, s0
	v_mul_f32_e32 v20, v20, v20
	global_store_short v[16:17], v12, off
	v_max_f32_e32 v12, v13, v13
	v_cvt_pk_bf16_f32 v8, v8, s0
	v_cvt_pk_bf16_f32 v4, v4, s0
	v_cvt_pk_bf16_f32 v0, v0, s0
	global_store_short v[166:167], v120, off offset:32
	v_max_f32_e32 v120, v121, v121
	global_store_short v[112:113], v104, off offset:32
	v_max_f32_e32 v104, v105, v105
	global_store_short v[96:97], v88, off offset:32
	v_max_f32_e32 v88, v89, v89
	global_store_short v[80:81], v72, off offset:32
	v_max_f32_e32 v72, v73, v73
	global_store_short v[64:65], v56, off offset:32
	v_max_f32_e32 v56, v57, v57
	global_store_short v[48:49], v40, off offset:32
	v_max_f32_e32 v40, v41, v41
	global_store_short v[32:33], v24, off offset:32
; DI bf16_t f2bf(float x) { return (bf16_t)(cvt_pk(x, 0.f) & 0xffffu); }
; #define BAR __builtin_amdgcn_s_barrier()
;     ...
;         bf16_t* d = (bf16_t*)(p.ws + OFF_U) + (size_t)row0 * 4096 + col;
; #pragma unroll
;         for (int e = 0; e < 4; ++e) { const float t = fmaxf(v[e], 0.f); d[(size_t)e * 4096] = f2bf(t * t); }
; template <int EPI, int K, int LNI = -1>
; DI void ph_gemm(const Params& p, const bf16_t* __restrict__ A, const bf16_t* __restrict__ Bt, int N, float* s_aux) {
;     ...
; #pragma unroll
;                     for (int bj = 0; bj < 2; ++bj)
; #pragma unroll
;                         for (int n = 0; n < 2; ++n) {
;                             float v[4];
; #pragma unroll
;                             for (int e = 0; e < 4; ++e) v[e] = acc[ai][bj][m][n][e];
;                             epi_store<EPI, LNI>(p, row0, bcol + bj * 128 + wc * 32 + n * 16 + fr + oz, lrow0, v, sa, rs, lg_[bj][n], lb_[bj][n]);
;                         }
;                 }
;         }
;         if (!has_next) break;
; #pragma unroll
;         for (int a = 0; a < 2; ++a)
; #pragma unroll
;             for (int b = 0; b < 2; ++b)
; #pragma unroll
;                 for (int m = 0; m < 4; ++m)
; #pragma unroll
;                     for (int n = 0; n < 2; ++n) acc[a][b][m][n] = (f32x4){0.f, 0.f, 0.f, 0.f};
;         pm = npm; pn = npn; cA = nA; cB = nB; it = itn; ++cnt;
;         if (wr == 1) BAR;
;     }
	v_max_f32_e32 v24, v25, v25
	v_cvt_pk_bf16_f32 v20, v20, s0
	v_max_f32_e32 v12, 0, v12
	global_store_short v[16:17], v8, off offset:32
	v_max_f32_e32 v8, v9, v9
	global_store_short v[16:17], v4, off offset:256
	v_max_f32_e32 v4, v5, v5
	global_store_short v[16:17], v0, off offset:288
	v_max_f32_e32 v0, v1, v1
	v_max_f32_e32 v120, 0, v120
	v_max_f32_e32 v104, 0, v104
	v_max_f32_e32 v88, 0, v88
	v_max_f32_e32 v72, 0, v72
	v_max_f32_e32 v56, 0, v56
	v_max_f32_e32 v40, 0, v40
	v_max_f32_e32 v24, 0, v24
	global_store_short v[28:29], v20, off offset:256
	v_max_f32_e32 v20, v22, v22
	v_mul_f32_e32 v12, v12, v12
	v_max_f32_e32 v8, 0, v8
	v_max_f32_e32 v4, 0, v4
	v_max_f32_e32 v0, 0, v0
	v_mul_f32_e32 v120, v120, v120
	v_mul_f32_e32 v104, v104, v104
	v_mul_f32_e32 v88, v88, v88
	v_mul_f32_e32 v72, v72, v72
	v_mul_f32_e32 v56, v56, v56
	v_mul_f32_e32 v40, v40, v40
	v_mul_f32_e32 v24, v24, v24
	v_max_f32_e32 v20, 0, v20
	v_cvt_pk_bf16_f32 v18, v12, s0
	v_add_co_u32_e32 v12, vcc, s3, v16
	v_max_f32_e32 v14, v14, v14
	v_mul_f32_e32 v8, v8, v8
	v_mul_f32_e32 v4, v4, v4
	v_mul_f32_e32 v0, v0, v0
	v_cvt_pk_bf16_f32 v120, v120, s0
	v_cvt_pk_bf16_f32 v104, v104, s0
	v_cvt_pk_bf16_f32 v88, v88, s0
	v_cvt_pk_bf16_f32 v72, v72, s0
	v_cvt_pk_bf16_f32 v56, v56, s0
	v_cvt_pk_bf16_f32 v40, v40, s0
	v_cvt_pk_bf16_f32 v24, v24, s0
	v_mul_f32_e32 v20, v20, v20
	v_addc_co_u32_e32 v13, vcc, 0, v17, vcc
	v_max_f32_e32 v14, 0, v14
	v_cvt_pk_bf16_f32 v8, v8, s0
	v_cvt_pk_bf16_f32 v4, v4, s0
	v_cvt_pk_bf16_f32 v0, v0, s0
	global_store_short v[124:125], v120, off offset:32
	v_max_f32_e32 v120, v122, v122
	global_store_short v[108:109], v104, off offset:32
	v_max_f32_e32 v104, v106, v106
	global_store_short v[92:93], v88, off offset:32
	v_max_f32_e32 v88, v90, v90
	global_store_short v[76:77], v72, off offset:32
	v_max_f32_e32 v72, v74, v74
	global_store_short v[60:61], v56, off offset:32
	v_max_f32_e32 v56, v58, v58
	global_store_short v[44:45], v40, off offset:32
	v_max_f32_e32 v40, v42, v42
	global_store_short v[28:29], v24, off offset:32
	v_max_f32_e32 v24, v26, v26
	v_cvt_pk_bf16_f32 v20, v20, s0
	global_store_short v[12:13], v18, off
	v_mul_f32_e32 v14, v14, v14
	v_add_co_u32_e32 v18, vcc, s29, v16
	global_store_short v[12:13], v8, off offset:32
	v_max_f32_e32 v8, v10, v10
	global_store_short v[12:13], v4, off offset:256
	v_max_f32_e32 v4, v6, v6
	global_store_short v[12:13], v0, off offset:288
	v_max_f32_e32 v0, v2, v2
	v_max_f32_e32 v120, 0, v120
	v_max_f32_e32 v104, 0, v104
	v_max_f32_e32 v88, 0, v88
	v_max_f32_e32 v72, 0, v72
	v_max_f32_e32 v56, 0, v56
	v_max_f32_e32 v40, 0, v40
	v_max_f32_e32 v24, 0, v24
	global_store_short v[34:35], v20, off offset:256
	v_max_f32_e32 v20, v23, v23
	v_cvt_pk_bf16_f32 v14, v14, s0
	v_addc_co_u32_e32 v19, vcc, 0, v17, vcc
	v_max_f32_e32 v8, 0, v8
	v_max_f32_e32 v4, 0, v4
	v_max_f32_e32 v0, 0, v0
	v_mul_f32_e32 v120, v120, v120
	v_mul_f32_e32 v104, v104, v104
	v_mul_f32_e32 v88, v88, v88
	v_mul_f32_e32 v72, v72, v72
	v_mul_f32_e32 v56, v56, v56
	v_mul_f32_e32 v40, v40, v40
	v_mul_f32_e32 v24, v24, v24
	v_max_f32_e32 v20, 0, v20
	global_store_short v[18:19], v14, off
	v_max_f32_e32 v14, v15, v15
	v_mul_f32_e32 v8, v8, v8
	v_mul_f32_e32 v4, v4, v4
	v_mul_f32_e32 v0, v0, v0
	v_cvt_pk_bf16_f32 v120, v120, s0
	v_cvt_pk_bf16_f32 v104, v104, s0
	v_cvt_pk_bf16_f32 v88, v88, s0
	v_cvt_pk_bf16_f32 v72, v72, s0
	v_cvt_pk_bf16_f32 v56, v56, s0
	v_cvt_pk_bf16_f32 v40, v40, s0
	v_cvt_pk_bf16_f32 v24, v24, s0
	v_mul_f32_e32 v20, v20, v20
	v_max_f32_e32 v14, 0, v14
	v_cvt_pk_bf16_f32 v8, v8, s0
	v_cvt_pk_bf16_f32 v4, v4, s0
	v_cvt_pk_bf16_f32 v0, v0, s0
	global_store_short v[168:169], v120, off offset:32
	v_max_f32_e32 v120, v123, v123
	global_store_short v[114:115], v104, off offset:32
	v_max_f32_e32 v104, v107, v107
	global_store_short v[98:99], v88, off offset:32
	v_max_f32_e32 v88, v91, v91
	global_store_short v[82:83], v72, off offset:32
	v_max_f32_e32 v72, v75, v75
	global_store_short v[66:67], v56, off offset:32
	v_max_f32_e32 v56, v59, v59
	global_store_short v[50:51], v40, off offset:32
	v_max_f32_e32 v40, v43, v43
	global_store_short v[34:35], v24, off offset:32
	v_max_f32_e32 v24, v27, v27
	v_cvt_pk_bf16_f32 v20, v20, s0
	v_mul_f32_e32 v14, v14, v14
	global_store_short v[18:19], v8, off offset:32
	v_max_f32_e32 v8, v11, v11
	global_store_short v[18:19], v4, off offset:256
	v_max_f32_e32 v4, v7, v7
	global_store_short v[18:19], v0, off offset:288
	v_max_f32_e32 v0, v3, v3
	v_max_f32_e32 v120, 0, v120
	v_max_f32_e32 v104, 0, v104
	v_max_f32_e32 v88, 0, v88
	v_max_f32_e32 v72, 0, v72
	v_max_f32_e32 v56, 0, v56
	v_max_f32_e32 v40, 0, v40
	v_max_f32_e32 v24, 0, v24
	global_store_short v[30:31], v20, off offset:256
	v_cvt_pk_bf16_f32 v20, v14, s0
	v_add_co_u32_e32 v14, vcc, s35, v16
	v_max_f32_e32 v8, 0, v8
	v_max_f32_e32 v4, 0, v4
	v_max_f32_e32 v0, 0, v0
	v_mul_f32_e32 v120, v120, v120
	v_mul_f32_e32 v104, v104, v104
	v_mul_f32_e32 v88, v88, v88
	v_mul_f32_e32 v72, v72, v72
	v_mul_f32_e32 v56, v56, v56
	v_mul_f32_e32 v40, v40, v40
	v_mul_f32_e32 v24, v24, v24
	v_addc_co_u32_e32 v15, vcc, 0, v17, vcc
	v_mul_f32_e32 v8, v8, v8
	v_mul_f32_e32 v4, v4, v4
	v_mul_f32_e32 v0, v0, v0
	v_cvt_pk_bf16_f32 v120, v120, s0
	v_cvt_pk_bf16_f32 v104, v104, s0
	v_cvt_pk_bf16_f32 v88, v88, s0
	v_cvt_pk_bf16_f32 v72, v72, s0
	v_cvt_pk_bf16_f32 v56, v56, s0
	v_cvt_pk_bf16_f32 v40, v40, s0
	v_cvt_pk_bf16_f32 v24, v24, s0
	v_cvt_pk_bf16_f32 v8, v8, s0
	v_cvt_pk_bf16_f32 v4, v4, s0
	v_cvt_pk_bf16_f32 v0, v0, s0
	s_andn2_b64 vcc, exec, s[14:15]
	s_mov_b64 s[14:15], -1
	global_store_short v[126:127], v137, off
	global_store_short v[126:127], v120, off offset:32
	global_store_short v[110:111], v116, off
	global_store_short v[110:111], v104, off offset:32
	global_store_short v[94:95], v100, off
	global_store_short v[94:95], v88, off offset:32
	global_store_short v[78:79], v84, off
	global_store_short v[78:79], v72, off offset:32
	global_store_short v[62:63], v68, off
	global_store_short v[62:63], v56, off offset:32
	global_store_short v[46:47], v52, off
	global_store_short v[46:47], v40, off offset:32
	global_store_short v[30:31], v36, off
	global_store_short v[30:31], v24, off offset:32
	global_store_short v[14:15], v20, off
	global_store_short v[14:15], v8, off offset:32
	global_store_short v[14:15], v4, off offset:256
	global_store_short v[14:15], v0, off offset:288
	s_cbranch_vccnz .LBB0_1845
	s_and_saveexec_b64 s[14:15], s[6:7]
	s_xor_b64 s[14:15], exec, s[14:15]
	s_cbranch_execz .LBB0_1844
	s_barrier
	s_branch .LBB0_1844

; DI f32x16 mfma32(bf16x8 a, bf16x8 b, f32x16 c) { return __builtin_amdgcn_mfma_f32_32x32x16_bf16(a, b, c, 0, 0, 0); }
; template <int EPI, int K, int LNI>
; DI void gemm_tail_unit(const Params& p, const bf16_t* __restrict__ A, const bf16_t* __restrict__ Bt, const int un, float* s_aux) {
;     ...
;     const bf16_t* ap = A + (size_t)(ROW0 + r) * K + w * KS + h * 8;
;     const bf16_t* bp = Bt + (size_t)(col0 + r) * K + w * KS + h * 8;
; #pragma unroll 8
;     for (int s = 0; s < KS / 16; ++s) {
;         const bf16x8 a0 = *(const bf16x8*)(ap + s * 16), a1 = *(const bf16x8*)(ap + (size_t)32 * K + s * 16);
;         const bf16x8 b0 = *(const bf16x8*)(bp + s * 16), b1 = *(const bf16x8*)(bp + (size_t)32 * K + s * 16);
;         acc[0][0] = mfma32(a0, b0, acc[0][0]); acc[0][1] = mfma32(a0, b1, acc[0][1]);
;         acc[1][0] = mfma32(a1, b0, acc[1][0]); acc[1][1] = mfma32(a1, b1, acc[1][1]);
;     }
.LBB0_1939:
	v_lshl_add_u64 v[74:75], v[68:69], 0, s[4:5]
	v_add_co_u32_e32 v102, vcc, s7, v74
	v_lshl_add_u64 v[76:77], v[66:67], 0, s[4:5]
	s_nop 0
	v_addc_co_u32_e32 v103, vcc, 0, v75, vcc
	v_add_co_u32_e32 v104, vcc, s8, v74
	s_add_u32 s4, s4, 0x100
	s_nop 0
	v_addc_co_u32_e32 v105, vcc, 0, v75, vcc
	v_add_co_u32_e32 v106, vcc, s9, v76
	s_addc_u32 s5, s5, 0
	s_nop 0
	v_addc_co_u32_e32 v107, vcc, 0, v77, vcc
	v_add_co_u32_e32 v108, vcc, s10, v76
	s_cmpk_lg_i32 s4, 0x400
	s_nop 0
	v_addc_co_u32_e32 v109, vcc, 0, v77, vcc
	s_nop 1
	v_readfirstlane_b32 s88, v102
	v_readfirstlane_b32 s89, v103
	v_readfirstlane_b32 s90, v106
	v_readfirstlane_b32 s91, v107
	v_and_b32_e32 v220, 63, v71
	v_lshrrev_b32_e32 v221, 3, v220
	v_and_b32_e32 v222, 7, v220
	v_lshlrev_b32_e32 v223, 13, v221
	v_lshl_add_u32 v223, v222, 4, v223
	v_lshlrev_b32_e32 v224, 14, v72
	v_mul_u32_u24_e32 v221, 0x90, v221
	v_lshl_add_u32 v221, v222, 4, v221
	v_add_u32_e32 v221, v221, v224
	v_lshrrev_b32_e32 v222, 5, v220
	v_mul_u32_u24_e32 v225, 0x90, v70
	v_lshl_add_u32 v222, v222, 4, v225
	v_add_u32_e32 v222, v222, v224
	global_load_dwordx4 v[76:79], v223, s[88:89]
	s_add_u32 s92, s88, 0x10000
	s_addc_u32 s93, s89, 0
	s_nop 0
	global_load_dwordx4 v[80:83], v223, s[92:93]
	s_add_u32 s94, s88, 0x20000
	s_addc_u32 s95, s89, 0
	s_nop 0
	global_load_dwordx4 v[84:87], v223, s[94:95]
	s_add_u32 s92, s88, 0x30000
	s_addc_u32 s93, s89, 0
	s_nop 0
	global_load_dwordx4 v[88:91], v223, s[92:93]
	s_add_u32 s94, s88, 0x40000
	s_addc_u32 s95, s89, 0
	s_nop 0
	global_load_dwordx4 v[92:95], v223, s[94:95]
	s_add_u32 s92, s88, 0x50000
	s_addc_u32 s93, s89, 0
	s_nop 0
	global_load_dwordx4 v[96:99], v223, s[92:93]
	s_add_u32 s94, s88, 0x60000
	s_addc_u32 s95, s89, 0
	s_nop 0
	global_load_dwordx4 v[112:115], v223, s[94:95]
	s_add_u32 s92, s88, 0x70000
	s_addc_u32 s93, s89, 0
	s_nop 0
	global_load_dwordx4 v[116:119], v223, s[92:93]
	global_load_dwordx4 v[120:123], v223, s[90:91]
	s_add_u32 s94, s90, 0x10000
	s_addc_u32 s95, s91, 0
	s_nop 0
	global_load_dwordx4 v[124:127], v223, s[94:95]
	s_add_u32 s92, s90, 0x20000
	s_addc_u32 s93, s91, 0
	s_nop 0
	global_load_dwordx4 v[128:131], v223, s[92:93]
	s_add_u32 s94, s90, 0x30000
	s_addc_u32 s95, s91, 0
	s_nop 0
	global_load_dwordx4 v[132:135], v223, s[94:95]
	s_add_u32 s92, s90, 0x40000
	s_addc_u32 s93, s91, 0
	s_nop 0
	global_load_dwordx4 v[136:139], v223, s[92:93]
	s_add_u32 s94, s90, 0x50000
	s_addc_u32 s95, s91, 0
	s_nop 0
	global_load_dwordx4 v[140:143], v223, s[94:95]
	s_add_u32 s92, s90, 0x60000
	s_addc_u32 s93, s91, 0
	s_nop 0
	global_load_dwordx4 v[144:147], v223, s[92:93]
	s_add_u32 s94, s90, 0x70000
	s_addc_u32 s95, s91, 0
	s_nop 0
	global_load_dwordx4 v[148:151], v223, s[94:95]
	global_load_dwordx4 v[152:155], v223, s[88:89] offset:128
	s_add_u32 s92, s88, 0x10000
	s_addc_u32 s93, s89, 0
	s_nop 0
	global_load_dwordx4 v[156:159], v223, s[92:93] offset:128
	s_add_u32 s94, s88, 0x20000
	s_addc_u32 s95, s89, 0
	s_nop 0
	global_load_dwordx4 v[160:163], v223, s[94:95] offset:128
	s_add_u32 s92, s88, 0x30000
	s_addc_u32 s93, s89, 0
	s_nop 0
	global_load_dwordx4 v[164:167], v223, s[92:93] offset:128
	s_add_u32 s94, s88, 0x40000
	s_addc_u32 s95, s89, 0
	s_nop 0
	global_load_dwordx4 v[168:171], v223, s[94:95] offset:128
	s_add_u32 s92, s88, 0x50000
	s_addc_u32 s93, s89, 0
	s_nop 0
	global_load_dwordx4 v[172:175], v223, s[92:93] offset:128
	s_add_u32 s94, s88, 0x60000
	s_addc_u32 s95, s89, 0
	s_nop 0
	global_load_dwordx4 v[176:179], v223, s[94:95] offset:128
	s_add_u32 s92, s88, 0x70000
	s_addc_u32 s93, s89, 0
	s_nop 0
	global_load_dwordx4 v[180:183], v223, s[92:93] offset:128
	global_load_dwordx4 v[184:187], v223, s[90:91] offset:128
	s_add_u32 s94, s90, 0x10000
	s_addc_u32 s95, s91, 0
	s_nop 0
	global_load_dwordx4 v[188:191], v223, s[94:95] offset:128
	s_add_u32 s92, s90, 0x20000
	s_addc_u32 s93, s91, 0
	s_nop 0
	global_load_dwordx4 v[192:195], v223, s[92:93] offset:128
	s_add_u32 s94, s90, 0x30000
	s_addc_u32 s95, s91, 0
	s_nop 0
	global_load_dwordx4 v[196:199], v223, s[94:95] offset:128
	s_add_u32 s92, s90, 0x40000
	s_addc_u32 s93, s91, 0
	s_nop 0
	global_load_dwordx4 v[200:203], v223, s[92:93] offset:128
	s_add_u32 s94, s90, 0x50000
	s_addc_u32 s95, s91, 0
	s_nop 0
	global_load_dwordx4 v[204:207], v223, s[94:95] offset:128
	s_add_u32 s92, s90, 0x60000
	s_addc_u32 s93, s91, 0
	s_nop 0
	global_load_dwordx4 v[212:215], v223, s[92:93] offset:128
	s_add_u32 s94, s90, 0x70000
	s_addc_u32 s95, s91, 0
	s_nop 0
	global_load_dwordx4 v[216:219], v223, s[94:95] offset:128
	s_waitcnt vmcnt(24) lgkmcnt(0)
	ds_write_b128 v221, v[76:79]
	ds_write_b128 v221, v[80:83] offset:1152
	ds_write_b128 v221, v[84:87] offset:2304
	ds_write_b128 v221, v[88:91] offset:3456
	ds_write_b128 v221, v[92:95] offset:4608
	ds_write_b128 v221, v[96:99] offset:5760
	ds_write_b128 v221, v[112:115] offset:6912
	ds_write_b128 v221, v[116:119] offset:8064
	s_waitcnt lgkmcnt(0)
	ds_read_b128 v[76:79], v222
	ds_read_b128 v[80:83], v222 offset:32
	ds_read_b128 v[84:87], v222 offset:64
	ds_read_b128 v[88:91], v222 offset:96
	ds_read_b128 v[92:95], v222 offset:4608
	ds_read_b128 v[96:99], v222 offset:4640
	ds_read_b128 v[112:115], v222 offset:4672
	ds_read_b128 v[116:119], v222 offset:4704
	s_waitcnt vmcnt(16) lgkmcnt(0)
	ds_write_b128 v221, v[120:123]
	ds_write_b128 v221, v[124:127] offset:1152
	ds_write_b128 v221, v[128:131] offset:2304
	ds_write_b128 v221, v[132:135] offset:3456
	ds_write_b128 v221, v[136:139] offset:4608
	ds_write_b128 v221, v[140:143] offset:5760
	ds_write_b128 v221, v[144:147] offset:6912
	ds_write_b128 v221, v[148:151] offset:8064
	s_waitcnt lgkmcnt(0)
; DI f32x16 mfma32(bf16x8 a, bf16x8 b, f32x16 c) { return __builtin_amdgcn_mfma_f32_32x32x16_bf16(a, b, c, 0, 0, 0); }
; template <int EPI, int K, int LNI>
; DI void gemm_tail_unit(const Params& p, const bf16_t* __restrict__ A, const bf16_t* __restrict__ Bt, const int un, float* s_aux) {
;     ...
; #pragma unroll 8
;     for (int s = 0; s < KS / 16; ++s) {
;         const bf16x8 a0 = *(const bf16x8*)(ap + s * 16), a1 = *(const bf16x8*)(ap + (size_t)32 * K + s * 16);
;         const bf16x8 b0 = *(const bf16x8*)(bp + s * 16), b1 = *(const bf16x8*)(bp + (size_t)32 * K + s * 16);
;         acc[0][0] = mfma32(a0, b0, acc[0][0]); acc[0][1] = mfma32(a0, b1, acc[0][1]);
;         acc[1][0] = mfma32(a1, b0, acc[1][0]); acc[1][1] = mfma32(a1, b1, acc[1][1]);
;     }
	ds_read_b128 v[120:123], v222
	ds_read_b128 v[124:127], v222 offset:32
	ds_read_b128 v[128:131], v222 offset:64
	ds_read_b128 v[132:135], v222 offset:96
	ds_read_b128 v[136:139], v222 offset:4608
	ds_read_b128 v[140:143], v222 offset:4640
	ds_read_b128 v[144:147], v222 offset:4672
	ds_read_b128 v[148:151], v222 offset:4704
	s_waitcnt lgkmcnt(0)
	v_mfma_f32_32x32x16_bf16 v[0:15], v[76:79], v[120:123], v[0:15]
	v_mfma_f32_32x32x16_bf16 v[16:31], v[76:79], v[136:139], v[16:31]
	v_mfma_f32_32x32x16_bf16 v[32:47], v[92:95], v[120:123], v[32:47]
	v_mfma_f32_32x32x16_bf16 v[48:63], v[92:95], v[136:139], v[48:63]
	v_mfma_f32_32x32x16_bf16 v[0:15], v[80:83], v[124:127], v[0:15]
	v_mfma_f32_32x32x16_bf16 v[16:31], v[80:83], v[140:143], v[16:31]
	v_mfma_f32_32x32x16_bf16 v[32:47], v[96:99], v[124:127], v[32:47]
	v_mfma_f32_32x32x16_bf16 v[48:63], v[96:99], v[140:143], v[48:63]
	v_mfma_f32_32x32x16_bf16 v[0:15], v[84:87], v[128:131], v[0:15]
	v_mfma_f32_32x32x16_bf16 v[16:31], v[84:87], v[144:147], v[16:31]
	v_mfma_f32_32x32x16_bf16 v[32:47], v[112:115], v[128:131], v[32:47]
	v_mfma_f32_32x32x16_bf16 v[48:63], v[112:115], v[144:147], v[48:63]
	v_mfma_f32_32x32x16_bf16 v[0:15], v[88:91], v[132:135], v[0:15]
	v_mfma_f32_32x32x16_bf16 v[16:31], v[88:91], v[148:151], v[16:31]
	v_mfma_f32_32x32x16_bf16 v[32:47], v[116:119], v[132:135], v[32:47]
	v_mfma_f32_32x32x16_bf16 v[48:63], v[116:119], v[148:151], v[48:63]
	global_load_dwordx4 v[76:79], v223, s[88:89] offset:256
	s_add_u32 s92, s88, 0x10000
	s_addc_u32 s93, s89, 0
	s_nop 0
	global_load_dwordx4 v[80:83], v223, s[92:93] offset:256
	s_add_u32 s94, s88, 0x20000
	s_addc_u32 s95, s89, 0
	s_nop 0
	global_load_dwordx4 v[84:87], v223, s[94:95] offset:256
	s_add_u32 s92, s88, 0x30000
	s_addc_u32 s93, s89, 0
	s_nop 0
	global_load_dwordx4 v[88:91], v223, s[92:93] offset:256
	s_add_u32 s94, s88, 0x40000
	s_addc_u32 s95, s89, 0
	s_nop 0
	global_load_dwordx4 v[92:95], v223, s[94:95] offset:256
	s_add_u32 s92, s88, 0x50000
	s_addc_u32 s93, s89, 0
	s_nop 0
	global_load_dwordx4 v[96:99], v223, s[92:93] offset:256
	s_add_u32 s94, s88, 0x60000
	s_addc_u32 s95, s89, 0
	s_nop 0
	global_load_dwordx4 v[112:115], v223, s[94:95] offset:256
	s_add_u32 s92, s88, 0x70000
	s_addc_u32 s93, s89, 0
	s_nop 0
	global_load_dwordx4 v[116:119], v223, s[92:93] offset:256
	global_load_dwordx4 v[120:123], v223, s[90:91] offset:256
	s_add_u32 s94, s90, 0x10000
	s_addc_u32 s95, s91, 0
	s_nop 0
	global_load_dwordx4 v[124:127], v223, s[94:95] offset:256
	s_add_u32 s92, s90, 0x20000
	s_addc_u32 s93, s91, 0
	s_nop 0
	global_load_dwordx4 v[128:131], v223, s[92:93] offset:256
	s_add_u32 s94, s90, 0x30000
	s_addc_u32 s95, s91, 0
	s_nop 0
	global_load_dwordx4 v[132:135], v223, s[94:95] offset:256
	s_add_u32 s92, s90, 0x40000
	s_addc_u32 s93, s91, 0
	s_nop 0
	global_load_dwordx4 v[136:139], v223, s[92:93] offset:256
	s_add_u32 s94, s90, 0x50000
	s_addc_u32 s95, s91, 0
	s_nop 0
	global_load_dwordx4 v[140:143], v223, s[94:95] offset:256
	s_add_u32 s92, s90, 0x60000
	s_addc_u32 s93, s91, 0
	s_nop 0
	global_load_dwordx4 v[144:147], v223, s[92:93] offset:256
	s_add_u32 s94, s90, 0x70000
	s_addc_u32 s95, s91, 0
	s_nop 0
	global_load_dwordx4 v[148:151], v223, s[94:95] offset:256
	s_waitcnt vmcnt(24) lgkmcnt(0)
	ds_write_b128 v221, v[152:155]
	ds_write_b128 v221, v[156:159] offset:1152
	ds_write_b128 v221, v[160:163] offset:2304
	ds_write_b128 v221, v[164:167] offset:3456
	ds_write_b128 v221, v[168:171] offset:4608
	ds_write_b128 v221, v[172:175] offset:5760
	ds_write_b128 v221, v[176:179] offset:6912
	ds_write_b128 v221, v[180:183] offset:8064
	s_waitcnt lgkmcnt(0)
	ds_read_b128 v[152:155], v222
	ds_read_b128 v[156:159], v222 offset:32
	ds_read_b128 v[160:163], v222 offset:64
	ds_read_b128 v[164:167], v222 offset:96
	ds_read_b128 v[168:171], v222 offset:4608
	ds_read_b128 v[172:175], v222 offset:4640
	ds_read_b128 v[176:179], v222 offset:4672
	ds_read_b128 v[180:183], v222 offset:4704
	s_waitcnt vmcnt(16) lgkmcnt(0)
	ds_write_b128 v221, v[184:187]
	ds_write_b128 v221, v[188:191] offset:1152
	ds_write_b128 v221, v[192:195] offset:2304
	ds_write_b128 v221, v[196:199] offset:3456
	ds_write_b128 v221, v[200:203] offset:4608
	ds_write_b128 v221, v[204:207] offset:5760
	ds_write_b128 v221, v[212:215] offset:6912
	ds_write_b128 v221, v[216:219] offset:8064
	s_waitcnt lgkmcnt(0)
	ds_read_b128 v[184:187], v222
	ds_read_b128 v[188:191], v222 offset:32
	ds_read_b128 v[192:195], v222 offset:64
	ds_read_b128 v[196:199], v222 offset:96
	ds_read_b128 v[200:203], v222 offset:4608
	ds_read_b128 v[204:207], v222 offset:4640
	ds_read_b128 v[212:215], v222 offset:4672
	ds_read_b128 v[216:219], v222 offset:4704
	s_waitcnt lgkmcnt(0)
; DI f32x16 mfma32(bf16x8 a, bf16x8 b, f32x16 c) { return __builtin_amdgcn_mfma_f32_32x32x16_bf16(a, b, c, 0, 0, 0); }
; template <int EPI, int K, int LNI>
; DI void gemm_tail_unit(const Params& p, const bf16_t* __restrict__ A, const bf16_t* __restrict__ Bt, const int un, float* s_aux) {
;     ...
; #pragma unroll 8
;     for (int s = 0; s < KS / 16; ++s) {
;         const bf16x8 a0 = *(const bf16x8*)(ap + s * 16), a1 = *(const bf16x8*)(ap + (size_t)32 * K + s * 16);
;         const bf16x8 b0 = *(const bf16x8*)(bp + s * 16), b1 = *(const bf16x8*)(bp + (size_t)32 * K + s * 16);
;         acc[0][0] = mfma32(a0, b0, acc[0][0]); acc[0][1] = mfma32(a0, b1, acc[0][1]);
;         acc[1][0] = mfma32(a1, b0, acc[1][0]); acc[1][1] = mfma32(a1, b1, acc[1][1]);
;     }
	v_mfma_f32_32x32x16_bf16 v[0:15], v[152:155], v[184:187], v[0:15]
	v_mfma_f32_32x32x16_bf16 v[16:31], v[152:155], v[200:203], v[16:31]
	v_mfma_f32_32x32x16_bf16 v[32:47], v[168:171], v[184:187], v[32:47]
	v_mfma_f32_32x32x16_bf16 v[48:63], v[168:171], v[200:203], v[48:63]
	v_mfma_f32_32x32x16_bf16 v[0:15], v[156:159], v[188:191], v[0:15]
	v_mfma_f32_32x32x16_bf16 v[16:31], v[156:159], v[204:207], v[16:31]
	v_mfma_f32_32x32x16_bf16 v[32:47], v[172:175], v[188:191], v[32:47]
	v_mfma_f32_32x32x16_bf16 v[48:63], v[172:175], v[204:207], v[48:63]
	v_mfma_f32_32x32x16_bf16 v[0:15], v[160:163], v[192:195], v[0:15]
	v_mfma_f32_32x32x16_bf16 v[16:31], v[160:163], v[212:215], v[16:31]
	v_mfma_f32_32x32x16_bf16 v[32:47], v[176:179], v[192:195], v[32:47]
	v_mfma_f32_32x32x16_bf16 v[48:63], v[176:179], v[212:215], v[48:63]
	v_mfma_f32_32x32x16_bf16 v[0:15], v[164:167], v[196:199], v[0:15]
	v_mfma_f32_32x32x16_bf16 v[16:31], v[164:167], v[216:219], v[16:31]
	v_mfma_f32_32x32x16_bf16 v[32:47], v[180:183], v[196:199], v[32:47]
	v_mfma_f32_32x32x16_bf16 v[48:63], v[180:183], v[216:219], v[48:63]
	global_load_dwordx4 v[152:155], v223, s[88:89] offset:384
	s_add_u32 s92, s88, 0x10000
	s_addc_u32 s93, s89, 0
	s_nop 0
	global_load_dwordx4 v[156:159], v223, s[92:93] offset:384
	s_add_u32 s94, s88, 0x20000
	s_addc_u32 s95, s89, 0
	s_nop 0
	global_load_dwordx4 v[160:163], v223, s[94:95] offset:384
	s_add_u32 s92, s88, 0x30000
	s_addc_u32 s93, s89, 0
	s_nop 0
	global_load_dwordx4 v[164:167], v223, s[92:93] offset:384
	s_add_u32 s94, s88, 0x40000
	s_addc_u32 s95, s89, 0
	s_nop 0
	global_load_dwordx4 v[168:171], v223, s[94:95] offset:384
	s_add_u32 s92, s88, 0x50000
	s_addc_u32 s93, s89, 0
	s_nop 0
	global_load_dwordx4 v[172:175], v223, s[92:93] offset:384
	s_add_u32 s94, s88, 0x60000
	s_addc_u32 s95, s89, 0
	s_nop 0
	global_load_dwordx4 v[176:179], v223, s[94:95] offset:384
	s_add_u32 s92, s88, 0x70000
	s_addc_u32 s93, s89, 0
	s_nop 0
	global_load_dwordx4 v[180:183], v223, s[92:93] offset:384
	global_load_dwordx4 v[184:187], v223, s[90:91] offset:384
	s_add_u32 s94, s90, 0x10000
	s_addc_u32 s95, s91, 0
	s_nop 0
	global_load_dwordx4 v[188:191], v223, s[94:95] offset:384
	s_add_u32 s92, s90, 0x20000
	s_addc_u32 s93, s91, 0
	s_nop 0
	global_load_dwordx4 v[192:195], v223, s[92:93] offset:384
	s_add_u32 s94, s90, 0x30000
	s_addc_u32 s95, s91, 0
	s_nop 0
	global_load_dwordx4 v[196:199], v223, s[94:95] offset:384
	s_add_u32 s92, s90, 0x40000
	s_addc_u32 s93, s91, 0
	s_nop 0
	global_load_dwordx4 v[200:203], v223, s[92:93] offset:384
	s_add_u32 s94, s90, 0x50000
	s_addc_u32 s95, s91, 0
	s_nop 0
	global_load_dwordx4 v[204:207], v223, s[94:95] offset:384
	s_add_u32 s92, s90, 0x60000
	s_addc_u32 s93, s91, 0
	s_nop 0
	global_load_dwordx4 v[212:215], v223, s[92:93] offset:384
	s_add_u32 s94, s90, 0x70000
	s_addc_u32 s95, s91, 0
	s_nop 0
	global_load_dwordx4 v[216:219], v223, s[94:95] offset:384
	s_waitcnt vmcnt(24) lgkmcnt(0)
	ds_write_b128 v221, v[76:79]
	ds_write_b128 v221, v[80:83] offset:1152
	ds_write_b128 v221, v[84:87] offset:2304
	ds_write_b128 v221, v[88:91] offset:3456
	ds_write_b128 v221, v[92:95] offset:4608
	ds_write_b128 v221, v[96:99] offset:5760
	ds_write_b128 v221, v[112:115] offset:6912
	ds_write_b128 v221, v[116:119] offset:8064
	s_waitcnt lgkmcnt(0)
	ds_read_b128 v[76:79], v222
	ds_read_b128 v[80:83], v222 offset:32
	ds_read_b128 v[84:87], v222 offset:64
	ds_read_b128 v[88:91], v222 offset:96
	ds_read_b128 v[92:95], v222 offset:4608
	ds_read_b128 v[96:99], v222 offset:4640
	ds_read_b128 v[112:115], v222 offset:4672
	ds_read_b128 v[116:119], v222 offset:4704
	s_waitcnt vmcnt(16) lgkmcnt(0)
	ds_write_b128 v221, v[120:123]
	ds_write_b128 v221, v[124:127] offset:1152
	ds_write_b128 v221, v[128:131] offset:2304
	ds_write_b128 v221, v[132:135] offset:3456
	ds_write_b128 v221, v[136:139] offset:4608
	ds_write_b128 v221, v[140:143] offset:5760
	ds_write_b128 v221, v[144:147] offset:6912
	ds_write_b128 v221, v[148:151] offset:8064
	s_waitcnt lgkmcnt(0)
	ds_read_b128 v[120:123], v222
	ds_read_b128 v[124:127], v222 offset:32
	ds_read_b128 v[128:131], v222 offset:64
	ds_read_b128 v[132:135], v222 offset:96
	ds_read_b128 v[136:139], v222 offset:4608
	ds_read_b128 v[140:143], v222 offset:4640
	ds_read_b128 v[144:147], v222 offset:4672
	ds_read_b128 v[148:151], v222 offset:4704
	s_waitcnt lgkmcnt(0)
; DI f32x16 mfma32(bf16x8 a, bf16x8 b, f32x16 c) { return __builtin_amdgcn_mfma_f32_32x32x16_bf16(a, b, c, 0, 0, 0); }
; template <int EPI, int K, int LNI>
; DI void gemm_tail_unit(const Params& p, const bf16_t* __restrict__ A, const bf16_t* __restrict__ Bt, const int un, float* s_aux) {
;     ...
; #pragma unroll 8
;     for (int s = 0; s < KS / 16; ++s) {
;         const bf16x8 a0 = *(const bf16x8*)(ap + s * 16), a1 = *(const bf16x8*)(ap + (size_t)32 * K + s * 16);
;         const bf16x8 b0 = *(const bf16x8*)(bp + s * 16), b1 = *(const bf16x8*)(bp + (size_t)32 * K + s * 16);
;         acc[0][0] = mfma32(a0, b0, acc[0][0]); acc[0][1] = mfma32(a0, b1, acc[0][1]);
;         acc[1][0] = mfma32(a1, b0, acc[1][0]); acc[1][1] = mfma32(a1, b1, acc[1][1]);
;     }
	v_mfma_f32_32x32x16_bf16 v[0:15], v[76:79], v[120:123], v[0:15]
	v_mfma_f32_32x32x16_bf16 v[16:31], v[76:79], v[136:139], v[16:31]
	v_mfma_f32_32x32x16_bf16 v[32:47], v[92:95], v[120:123], v[32:47]
	v_mfma_f32_32x32x16_bf16 v[48:63], v[92:95], v[136:139], v[48:63]
	v_mfma_f32_32x32x16_bf16 v[0:15], v[80:83], v[124:127], v[0:15]
	v_mfma_f32_32x32x16_bf16 v[16:31], v[80:83], v[140:143], v[16:31]
	v_mfma_f32_32x32x16_bf16 v[32:47], v[96:99], v[124:127], v[32:47]
	v_mfma_f32_32x32x16_bf16 v[48:63], v[96:99], v[140:143], v[48:63]
	v_mfma_f32_32x32x16_bf16 v[0:15], v[84:87], v[128:131], v[0:15]
	v_mfma_f32_32x32x16_bf16 v[16:31], v[84:87], v[144:147], v[16:31]
	v_mfma_f32_32x32x16_bf16 v[32:47], v[112:115], v[128:131], v[32:47]
	v_mfma_f32_32x32x16_bf16 v[48:63], v[112:115], v[144:147], v[48:63]
	v_mfma_f32_32x32x16_bf16 v[0:15], v[88:91], v[132:135], v[0:15]
	v_mfma_f32_32x32x16_bf16 v[16:31], v[88:91], v[148:151], v[16:31]
	v_mfma_f32_32x32x16_bf16 v[32:47], v[116:119], v[132:135], v[32:47]
	v_mfma_f32_32x32x16_bf16 v[48:63], v[116:119], v[148:151], v[48:63]
	global_load_dwordx4 v[76:79], v223, s[88:89] offset:512
	s_add_u32 s92, s88, 0x10000
	s_addc_u32 s93, s89, 0
	s_nop 0
	global_load_dwordx4 v[80:83], v223, s[92:93] offset:512
	s_add_u32 s94, s88, 0x20000
	s_addc_u32 s95, s89, 0
	s_nop 0
	global_load_dwordx4 v[84:87], v223, s[94:95] offset:512
	s_add_u32 s92, s88, 0x30000
	s_addc_u32 s93, s89, 0
	s_nop 0
	global_load_dwordx4 v[88:91], v223, s[92:93] offset:512
	s_add_u32 s94, s88, 0x40000
	s_addc_u32 s95, s89, 0
	s_nop 0
	global_load_dwordx4 v[92:95], v223, s[94:95] offset:512
	s_add_u32 s92, s88, 0x50000
	s_addc_u32 s93, s89, 0
	s_nop 0
	global_load_dwordx4 v[96:99], v223, s[92:93] offset:512
	s_add_u32 s94, s88, 0x60000
	s_addc_u32 s95, s89, 0
	s_nop 0
	global_load_dwordx4 v[112:115], v223, s[94:95] offset:512
	s_add_u32 s92, s88, 0x70000
	s_addc_u32 s93, s89, 0
	s_nop 0
	global_load_dwordx4 v[116:119], v223, s[92:93] offset:512
	global_load_dwordx4 v[120:123], v223, s[90:91] offset:512
	s_add_u32 s94, s90, 0x10000
	s_addc_u32 s95, s91, 0
	s_nop 0
	global_load_dwordx4 v[124:127], v223, s[94:95] offset:512
	s_add_u32 s92, s90, 0x20000
	s_addc_u32 s93, s91, 0
	s_nop 0
	global_load_dwordx4 v[128:131], v223, s[92:93] offset:512
	s_add_u32 s94, s90, 0x30000
	s_addc_u32 s95, s91, 0
	s_nop 0
	global_load_dwordx4 v[132:135], v223, s[94:95] offset:512
	s_add_u32 s92, s90, 0x40000
	s_addc_u32 s93, s91, 0
	s_nop 0
	global_load_dwordx4 v[136:139], v223, s[92:93] offset:512
	s_add_u32 s94, s90, 0x50000
	s_addc_u32 s95, s91, 0
	s_nop 0
	global_load_dwordx4 v[140:143], v223, s[94:95] offset:512
	s_add_u32 s92, s90, 0x60000
	s_addc_u32 s93, s91, 0
	s_nop 0
	global_load_dwordx4 v[144:147], v223, s[92:93] offset:512
	s_add_u32 s94, s90, 0x70000
	s_addc_u32 s95, s91, 0
	s_nop 0
	global_load_dwordx4 v[148:151], v223, s[94:95] offset:512
	s_waitcnt vmcnt(24) lgkmcnt(0)
	ds_write_b128 v221, v[152:155]
	ds_write_b128 v221, v[156:159] offset:1152
	ds_write_b128 v221, v[160:163] offset:2304
	ds_write_b128 v221, v[164:167] offset:3456
	ds_write_b128 v221, v[168:171] offset:4608
	ds_write_b128 v221, v[172:175] offset:5760
	ds_write_b128 v221, v[176:179] offset:6912
	ds_write_b128 v221, v[180:183] offset:8064
	s_waitcnt lgkmcnt(0)
	ds_read_b128 v[152:155], v222
	ds_read_b128 v[156:159], v222 offset:32
	ds_read_b128 v[160:163], v222 offset:64
	ds_read_b128 v[164:167], v222 offset:96
	ds_read_b128 v[168:171], v222 offset:4608
	ds_read_b128 v[172:175], v222 offset:4640
	ds_read_b128 v[176:179], v222 offset:4672
	ds_read_b128 v[180:183], v222 offset:4704
	s_waitcnt vmcnt(16) lgkmcnt(0)
	ds_write_b128 v221, v[184:187]
	ds_write_b128 v221, v[188:191] offset:1152
	ds_write_b128 v221, v[192:195] offset:2304
	ds_write_b128 v221, v[196:199] offset:3456
	ds_write_b128 v221, v[200:203] offset:4608
	ds_write_b128 v221, v[204:207] offset:5760
	ds_write_b128 v221, v[212:215] offset:6912
	ds_write_b128 v221, v[216:219] offset:8064
	s_waitcnt lgkmcnt(0)
	ds_read_b128 v[184:187], v222
	ds_read_b128 v[188:191], v222 offset:32
	ds_read_b128 v[192:195], v222 offset:64
	ds_read_b128 v[196:199], v222 offset:96
	ds_read_b128 v[200:203], v222 offset:4608
	ds_read_b128 v[204:207], v222 offset:4640
	ds_read_b128 v[212:215], v222 offset:4672
	ds_read_b128 v[216:219], v222 offset:4704
	s_waitcnt lgkmcnt(0)
; DI f32x16 mfma32(bf16x8 a, bf16x8 b, f32x16 c) { return __builtin_amdgcn_mfma_f32_32x32x16_bf16(a, b, c, 0, 0, 0); }
; template <int EPI, int K, int LNI>
; DI void gemm_tail_unit(const Params& p, const bf16_t* __restrict__ A, const bf16_t* __restrict__ Bt, const int un, float* s_aux) {
;     ...
; #pragma unroll 8
;     for (int s = 0; s < KS / 16; ++s) {
;         const bf16x8 a0 = *(const bf16x8*)(ap + s * 16), a1 = *(const bf16x8*)(ap + (size_t)32 * K + s * 16);
;         const bf16x8 b0 = *(const bf16x8*)(bp + s * 16), b1 = *(const bf16x8*)(bp + (size_t)32 * K + s * 16);
;         acc[0][0] = mfma32(a0, b0, acc[0][0]); acc[0][1] = mfma32(a0, b1, acc[0][1]);
;         acc[1][0] = mfma32(a1, b0, acc[1][0]); acc[1][1] = mfma32(a1, b1, acc[1][1]);
;     }
	v_mfma_f32_32x32x16_bf16 v[0:15], v[152:155], v[184:187], v[0:15]
	v_mfma_f32_32x32x16_bf16 v[16:31], v[152:155], v[200:203], v[16:31]
	v_mfma_f32_32x32x16_bf16 v[32:47], v[168:171], v[184:187], v[32:47]
	v_mfma_f32_32x32x16_bf16 v[48:63], v[168:171], v[200:203], v[48:63]
	v_mfma_f32_32x32x16_bf16 v[0:15], v[156:159], v[188:191], v[0:15]
	v_mfma_f32_32x32x16_bf16 v[16:31], v[156:159], v[204:207], v[16:31]
	v_mfma_f32_32x32x16_bf16 v[32:47], v[172:175], v[188:191], v[32:47]
	v_mfma_f32_32x32x16_bf16 v[48:63], v[172:175], v[204:207], v[48:63]
	v_mfma_f32_32x32x16_bf16 v[0:15], v[160:163], v[192:195], v[0:15]
	v_mfma_f32_32x32x16_bf16 v[16:31], v[160:163], v[212:215], v[16:31]
	v_mfma_f32_32x32x16_bf16 v[32:47], v[176:179], v[192:195], v[32:47]
	v_mfma_f32_32x32x16_bf16 v[48:63], v[176:179], v[212:215], v[48:63]
	v_mfma_f32_32x32x16_bf16 v[0:15], v[164:167], v[196:199], v[0:15]
	v_mfma_f32_32x32x16_bf16 v[16:31], v[164:167], v[216:219], v[16:31]
	v_mfma_f32_32x32x16_bf16 v[32:47], v[180:183], v[196:199], v[32:47]
	v_mfma_f32_32x32x16_bf16 v[48:63], v[180:183], v[216:219], v[48:63]
	global_load_dwordx4 v[152:155], v223, s[88:89] offset:640
	s_add_u32 s92, s88, 0x10000
	s_addc_u32 s93, s89, 0
	s_nop 0
	global_load_dwordx4 v[156:159], v223, s[92:93] offset:640
	s_add_u32 s94, s88, 0x20000
	s_addc_u32 s95, s89, 0
	s_nop 0
	global_load_dwordx4 v[160:163], v223, s[94:95] offset:640
	s_add_u32 s92, s88, 0x30000
	s_addc_u32 s93, s89, 0
	s_nop 0
	global_load_dwordx4 v[164:167], v223, s[92:93] offset:640
	s_add_u32 s94, s88, 0x40000
	s_addc_u32 s95, s89, 0
	s_nop 0
	global_load_dwordx4 v[168:171], v223, s[94:95] offset:640
	s_add_u32 s92, s88, 0x50000
	s_addc_u32 s93, s89, 0
	s_nop 0
	global_load_dwordx4 v[172:175], v223, s[92:93] offset:640
	s_add_u32 s94, s88, 0x60000
	s_addc_u32 s95, s89, 0
	s_nop 0
	global_load_dwordx4 v[176:179], v223, s[94:95] offset:640
	s_add_u32 s92, s88, 0x70000
	s_addc_u32 s93, s89, 0
	s_nop 0
	global_load_dwordx4 v[180:183], v223, s[92:93] offset:640
	global_load_dwordx4 v[184:187], v223, s[90:91] offset:640
	s_add_u32 s94, s90, 0x10000
	s_addc_u32 s95, s91, 0
	s_nop 0
	global_load_dwordx4 v[188:191], v223, s[94:95] offset:640
	s_add_u32 s92, s90, 0x20000
	s_addc_u32 s93, s91, 0
	s_nop 0
	global_load_dwordx4 v[192:195], v223, s[92:93] offset:640
	s_add_u32 s94, s90, 0x30000
	s_addc_u32 s95, s91, 0
	s_nop 0
	global_load_dwordx4 v[196:199], v223, s[94:95] offset:640
	s_add_u32 s92, s90, 0x40000
	s_addc_u32 s93, s91, 0
	s_nop 0
	global_load_dwordx4 v[200:203], v223, s[92:93] offset:640
	s_add_u32 s94, s90, 0x50000
	s_addc_u32 s95, s91, 0
	s_nop 0
	global_load_dwordx4 v[204:207], v223, s[94:95] offset:640
	s_add_u32 s92, s90, 0x60000
	s_addc_u32 s93, s91, 0
	s_nop 0
	global_load_dwordx4 v[212:215], v223, s[92:93] offset:640
	s_add_u32 s94, s90, 0x70000
	s_addc_u32 s95, s91, 0
	s_nop 0
	global_load_dwordx4 v[216:219], v223, s[94:95] offset:640
	s_waitcnt vmcnt(24) lgkmcnt(0)
	ds_write_b128 v221, v[76:79]
	ds_write_b128 v221, v[80:83] offset:1152
	ds_write_b128 v221, v[84:87] offset:2304
	ds_write_b128 v221, v[88:91] offset:3456
	ds_write_b128 v221, v[92:95] offset:4608
	ds_write_b128 v221, v[96:99] offset:5760
	ds_write_b128 v221, v[112:115] offset:6912
	ds_write_b128 v221, v[116:119] offset:8064
	s_waitcnt lgkmcnt(0)
	ds_read_b128 v[76:79], v222
	ds_read_b128 v[80:83], v222 offset:32
	ds_read_b128 v[84:87], v222 offset:64
	ds_read_b128 v[88:91], v222 offset:96
	ds_read_b128 v[92:95], v222 offset:4608
	ds_read_b128 v[96:99], v222 offset:4640
	ds_read_b128 v[112:115], v222 offset:4672
	ds_read_b128 v[116:119], v222 offset:4704
	s_waitcnt vmcnt(16) lgkmcnt(0)
	ds_write_b128 v221, v[120:123]
	ds_write_b128 v221, v[124:127] offset:1152
	ds_write_b128 v221, v[128:131] offset:2304
	ds_write_b128 v221, v[132:135] offset:3456
	ds_write_b128 v221, v[136:139] offset:4608
	ds_write_b128 v221, v[140:143] offset:5760
	ds_write_b128 v221, v[144:147] offset:6912
	ds_write_b128 v221, v[148:151] offset:8064
	s_waitcnt lgkmcnt(0)
	ds_read_b128 v[120:123], v222
	ds_read_b128 v[124:127], v222 offset:32
	ds_read_b128 v[128:131], v222 offset:64
	ds_read_b128 v[132:135], v222 offset:96
	ds_read_b128 v[136:139], v222 offset:4608
	ds_read_b128 v[140:143], v222 offset:4640
	ds_read_b128 v[144:147], v222 offset:4672
	ds_read_b128 v[148:151], v222 offset:4704
	s_waitcnt lgkmcnt(0)
; DI f32x16 mfma32(bf16x8 a, bf16x8 b, f32x16 c) { return __builtin_amdgcn_mfma_f32_32x32x16_bf16(a, b, c, 0, 0, 0); }
; template <int EPI, int K, int LNI>
; DI void gemm_tail_unit(const Params& p, const bf16_t* __restrict__ A, const bf16_t* __restrict__ Bt, const int un, float* s_aux) {
;     ...
; #pragma unroll 8
;     for (int s = 0; s < KS / 16; ++s) {
;         const bf16x8 a0 = *(const bf16x8*)(ap + s * 16), a1 = *(const bf16x8*)(ap + (size_t)32 * K + s * 16);
;         const bf16x8 b0 = *(const bf16x8*)(bp + s * 16), b1 = *(const bf16x8*)(bp + (size_t)32 * K + s * 16);
;         acc[0][0] = mfma32(a0, b0, acc[0][0]); acc[0][1] = mfma32(a0, b1, acc[0][1]);
;         acc[1][0] = mfma32(a1, b0, acc[1][0]); acc[1][1] = mfma32(a1, b1, acc[1][1]);
;     }
	v_mfma_f32_32x32x16_bf16 v[0:15], v[76:79], v[120:123], v[0:15]
	v_mfma_f32_32x32x16_bf16 v[16:31], v[76:79], v[136:139], v[16:31]
	v_mfma_f32_32x32x16_bf16 v[32:47], v[92:95], v[120:123], v[32:47]
	v_mfma_f32_32x32x16_bf16 v[48:63], v[92:95], v[136:139], v[48:63]
	v_mfma_f32_32x32x16_bf16 v[0:15], v[80:83], v[124:127], v[0:15]
	v_mfma_f32_32x32x16_bf16 v[16:31], v[80:83], v[140:143], v[16:31]
	v_mfma_f32_32x32x16_bf16 v[32:47], v[96:99], v[124:127], v[32:47]
	v_mfma_f32_32x32x16_bf16 v[48:63], v[96:99], v[140:143], v[48:63]
	v_mfma_f32_32x32x16_bf16 v[0:15], v[84:87], v[128:131], v[0:15]
	v_mfma_f32_32x32x16_bf16 v[16:31], v[84:87], v[144:147], v[16:31]
	v_mfma_f32_32x32x16_bf16 v[32:47], v[112:115], v[128:131], v[32:47]
	v_mfma_f32_32x32x16_bf16 v[48:63], v[112:115], v[144:147], v[48:63]
	v_mfma_f32_32x32x16_bf16 v[0:15], v[88:91], v[132:135], v[0:15]
	v_mfma_f32_32x32x16_bf16 v[16:31], v[88:91], v[148:151], v[16:31]
	v_mfma_f32_32x32x16_bf16 v[32:47], v[116:119], v[132:135], v[32:47]
	v_mfma_f32_32x32x16_bf16 v[48:63], v[116:119], v[148:151], v[48:63]
	global_load_dwordx4 v[76:79], v223, s[88:89] offset:768
	s_add_u32 s92, s88, 0x10000
	s_addc_u32 s93, s89, 0
	s_nop 0
	global_load_dwordx4 v[80:83], v223, s[92:93] offset:768
	s_add_u32 s94, s88, 0x20000
	s_addc_u32 s95, s89, 0
	s_nop 0
	global_load_dwordx4 v[84:87], v223, s[94:95] offset:768
	s_add_u32 s92, s88, 0x30000
	s_addc_u32 s93, s89, 0
	s_nop 0
	global_load_dwordx4 v[88:91], v223, s[92:93] offset:768
	s_add_u32 s94, s88, 0x40000
	s_addc_u32 s95, s89, 0
	s_nop 0
	global_load_dwordx4 v[92:95], v223, s[94:95] offset:768
	s_add_u32 s92, s88, 0x50000
	s_addc_u32 s93, s89, 0
	s_nop 0
	global_load_dwordx4 v[96:99], v223, s[92:93] offset:768
	s_add_u32 s94, s88, 0x60000
	s_addc_u32 s95, s89, 0
	s_nop 0
	global_load_dwordx4 v[112:115], v223, s[94:95] offset:768
	s_add_u32 s92, s88, 0x70000
	s_addc_u32 s93, s89, 0
	s_nop 0
	global_load_dwordx4 v[116:119], v223, s[92:93] offset:768
	global_load_dwordx4 v[120:123], v223, s[90:91] offset:768
	s_add_u32 s94, s90, 0x10000
	s_addc_u32 s95, s91, 0
	s_nop 0
	global_load_dwordx4 v[124:127], v223, s[94:95] offset:768
	s_add_u32 s92, s90, 0x20000
	s_addc_u32 s93, s91, 0
	s_nop 0
	global_load_dwordx4 v[128:131], v223, s[92:93] offset:768
	s_add_u32 s94, s90, 0x30000
	s_addc_u32 s95, s91, 0
	s_nop 0
	global_load_dwordx4 v[132:135], v223, s[94:95] offset:768
	s_add_u32 s92, s90, 0x40000
	s_addc_u32 s93, s91, 0
	s_nop 0
	global_load_dwordx4 v[136:139], v223, s[92:93] offset:768
	s_add_u32 s94, s90, 0x50000
	s_addc_u32 s95, s91, 0
	s_nop 0
	global_load_dwordx4 v[140:143], v223, s[94:95] offset:768
	s_add_u32 s92, s90, 0x60000
	s_addc_u32 s93, s91, 0
	s_nop 0
	global_load_dwordx4 v[144:147], v223, s[92:93] offset:768
	s_add_u32 s94, s90, 0x70000
	s_addc_u32 s95, s91, 0
	s_nop 0
	global_load_dwordx4 v[148:151], v223, s[94:95] offset:768
	s_waitcnt vmcnt(24) lgkmcnt(0)
	ds_write_b128 v221, v[152:155]
	ds_write_b128 v221, v[156:159] offset:1152
	ds_write_b128 v221, v[160:163] offset:2304
	ds_write_b128 v221, v[164:167] offset:3456
	ds_write_b128 v221, v[168:171] offset:4608
	ds_write_b128 v221, v[172:175] offset:5760
	ds_write_b128 v221, v[176:179] offset:6912
	ds_write_b128 v221, v[180:183] offset:8064
	s_waitcnt lgkmcnt(0)
	ds_read_b128 v[152:155], v222
	ds_read_b128 v[156:159], v222 offset:32
	ds_read_b128 v[160:163], v222 offset:64
	ds_read_b128 v[164:167], v222 offset:96
	ds_read_b128 v[168:171], v222 offset:4608
	ds_read_b128 v[172:175], v222 offset:4640
	ds_read_b128 v[176:179], v222 offset:4672
	ds_read_b128 v[180:183], v222 offset:4704
	s_waitcnt vmcnt(16) lgkmcnt(0)
	ds_write_b128 v221, v[184:187]
	ds_write_b128 v221, v[188:191] offset:1152
	ds_write_b128 v221, v[192:195] offset:2304
	ds_write_b128 v221, v[196:199] offset:3456
	ds_write_b128 v221, v[200:203] offset:4608
	ds_write_b128 v221, v[204:207] offset:5760
	ds_write_b128 v221, v[212:215] offset:6912
	ds_write_b128 v221, v[216:219] offset:8064
	s_waitcnt lgkmcnt(0)
	ds_read_b128 v[184:187], v222
	ds_read_b128 v[188:191], v222 offset:32
	ds_read_b128 v[192:195], v222 offset:64
	ds_read_b128 v[196:199], v222 offset:96
	ds_read_b128 v[200:203], v222 offset:4608
	ds_read_b128 v[204:207], v222 offset:4640
	ds_read_b128 v[212:215], v222 offset:4672
	ds_read_b128 v[216:219], v222 offset:4704
	s_waitcnt lgkmcnt(0)
; DI f32x16 mfma32(bf16x8 a, bf16x8 b, f32x16 c) { return __builtin_amdgcn_mfma_f32_32x32x16_bf16(a, b, c, 0, 0, 0); }
; template <int EPI, int K, int LNI>
; DI void gemm_tail_unit(const Params& p, const bf16_t* __restrict__ A, const bf16_t* __restrict__ Bt, const int un, float* s_aux) {
;     ...
; #pragma unroll 8
;     for (int s = 0; s < KS / 16; ++s) {
;         const bf16x8 a0 = *(const bf16x8*)(ap + s * 16), a1 = *(const bf16x8*)(ap + (size_t)32 * K + s * 16);
;         const bf16x8 b0 = *(const bf16x8*)(bp + s * 16), b1 = *(const bf16x8*)(bp + (size_t)32 * K + s * 16);
;         acc[0][0] = mfma32(a0, b0, acc[0][0]); acc[0][1] = mfma32(a0, b1, acc[0][1]);
;         acc[1][0] = mfma32(a1, b0, acc[1][0]); acc[1][1] = mfma32(a1, b1, acc[1][1]);
;     }
	v_mfma_f32_32x32x16_bf16 v[0:15], v[152:155], v[184:187], v[0:15]
	v_mfma_f32_32x32x16_bf16 v[16:31], v[152:155], v[200:203], v[16:31]
	v_mfma_f32_32x32x16_bf16 v[32:47], v[168:171], v[184:187], v[32:47]
	v_mfma_f32_32x32x16_bf16 v[48:63], v[168:171], v[200:203], v[48:63]
	v_mfma_f32_32x32x16_bf16 v[0:15], v[156:159], v[188:191], v[0:15]
	v_mfma_f32_32x32x16_bf16 v[16:31], v[156:159], v[204:207], v[16:31]
	v_mfma_f32_32x32x16_bf16 v[32:47], v[172:175], v[188:191], v[32:47]
	v_mfma_f32_32x32x16_bf16 v[48:63], v[172:175], v[204:207], v[48:63]
	v_mfma_f32_32x32x16_bf16 v[0:15], v[160:163], v[192:195], v[0:15]
	v_mfma_f32_32x32x16_bf16 v[16:31], v[160:163], v[212:215], v[16:31]
	v_mfma_f32_32x32x16_bf16 v[32:47], v[176:179], v[192:195], v[32:47]
	v_mfma_f32_32x32x16_bf16 v[48:63], v[176:179], v[212:215], v[48:63]
	v_mfma_f32_32x32x16_bf16 v[0:15], v[164:167], v[196:199], v[0:15]
	v_mfma_f32_32x32x16_bf16 v[16:31], v[164:167], v[216:219], v[16:31]
	v_mfma_f32_32x32x16_bf16 v[32:47], v[180:183], v[196:199], v[32:47]
	v_mfma_f32_32x32x16_bf16 v[48:63], v[180:183], v[216:219], v[48:63]
	global_load_dwordx4 v[152:155], v223, s[88:89] offset:896
	s_add_u32 s92, s88, 0x10000
	s_addc_u32 s93, s89, 0
	s_nop 0
	global_load_dwordx4 v[156:159], v223, s[92:93] offset:896
	s_add_u32 s94, s88, 0x20000
	s_addc_u32 s95, s89, 0
	s_nop 0
	global_load_dwordx4 v[160:163], v223, s[94:95] offset:896
	s_add_u32 s92, s88, 0x30000
	s_addc_u32 s93, s89, 0
	s_nop 0
	global_load_dwordx4 v[164:167], v223, s[92:93] offset:896
	s_add_u32 s94, s88, 0x40000
	s_addc_u32 s95, s89, 0
	s_nop 0
	global_load_dwordx4 v[168:171], v223, s[94:95] offset:896
	s_add_u32 s92, s88, 0x50000
	s_addc_u32 s93, s89, 0
	s_nop 0
	global_load_dwordx4 v[172:175], v223, s[92:93] offset:896
	s_add_u32 s94, s88, 0x60000
	s_addc_u32 s95, s89, 0
	s_nop 0
	global_load_dwordx4 v[176:179], v223, s[94:95] offset:896
	s_add_u32 s92, s88, 0x70000
	s_addc_u32 s93, s89, 0
	s_nop 0
	global_load_dwordx4 v[180:183], v223, s[92:93] offset:896
	global_load_dwordx4 v[184:187], v223, s[90:91] offset:896
	s_add_u32 s94, s90, 0x10000
	s_addc_u32 s95, s91, 0
	s_nop 0
	global_load_dwordx4 v[188:191], v223, s[94:95] offset:896
	s_add_u32 s92, s90, 0x20000
	s_addc_u32 s93, s91, 0
	s_nop 0
	global_load_dwordx4 v[192:195], v223, s[92:93] offset:896
	s_add_u32 s94, s90, 0x30000
	s_addc_u32 s95, s91, 0
	s_nop 0
	global_load_dwordx4 v[196:199], v223, s[94:95] offset:896
	s_add_u32 s92, s90, 0x40000
	s_addc_u32 s93, s91, 0
	s_nop 0
	global_load_dwordx4 v[200:203], v223, s[92:93] offset:896
	s_add_u32 s94, s90, 0x50000
	s_addc_u32 s95, s91, 0
	s_nop 0
	global_load_dwordx4 v[204:207], v223, s[94:95] offset:896
	s_add_u32 s92, s90, 0x60000
	s_addc_u32 s93, s91, 0
	s_nop 0
	global_load_dwordx4 v[212:215], v223, s[92:93] offset:896
	s_add_u32 s94, s90, 0x70000
	s_addc_u32 s95, s91, 0
	s_nop 0
	global_load_dwordx4 v[216:219], v223, s[94:95] offset:896
	s_waitcnt vmcnt(24) lgkmcnt(0)
	ds_write_b128 v221, v[76:79]
	ds_write_b128 v221, v[80:83] offset:1152
	ds_write_b128 v221, v[84:87] offset:2304
	ds_write_b128 v221, v[88:91] offset:3456
	ds_write_b128 v221, v[92:95] offset:4608
	ds_write_b128 v221, v[96:99] offset:5760
	ds_write_b128 v221, v[112:115] offset:6912
	ds_write_b128 v221, v[116:119] offset:8064
	s_waitcnt lgkmcnt(0)
	ds_read_b128 v[76:79], v222
	ds_read_b128 v[80:83], v222 offset:32
	ds_read_b128 v[84:87], v222 offset:64
	ds_read_b128 v[88:91], v222 offset:96
	ds_read_b128 v[92:95], v222 offset:4608
	ds_read_b128 v[96:99], v222 offset:4640
	ds_read_b128 v[112:115], v222 offset:4672
	ds_read_b128 v[116:119], v222 offset:4704
	s_waitcnt vmcnt(16) lgkmcnt(0)
	ds_write_b128 v221, v[120:123]
	ds_write_b128 v221, v[124:127] offset:1152
	ds_write_b128 v221, v[128:131] offset:2304
	ds_write_b128 v221, v[132:135] offset:3456
	ds_write_b128 v221, v[136:139] offset:4608
	ds_write_b128 v221, v[140:143] offset:5760
	ds_write_b128 v221, v[144:147] offset:6912
	ds_write_b128 v221, v[148:151] offset:8064
	s_waitcnt lgkmcnt(0)
	ds_read_b128 v[120:123], v222
	ds_read_b128 v[124:127], v222 offset:32
	ds_read_b128 v[128:131], v222 offset:64
	ds_read_b128 v[132:135], v222 offset:96
	ds_read_b128 v[136:139], v222 offset:4608
	ds_read_b128 v[140:143], v222 offset:4640
	ds_read_b128 v[144:147], v222 offset:4672
	ds_read_b128 v[148:151], v222 offset:4704
	s_waitcnt lgkmcnt(0)
	v_mfma_f32_32x32x16_bf16 v[0:15], v[76:79], v[120:123], v[0:15]
	v_mfma_f32_32x32x16_bf16 v[16:31], v[76:79], v[136:139], v[16:31]
	v_mfma_f32_32x32x16_bf16 v[32:47], v[92:95], v[120:123], v[32:47]
	v_mfma_f32_32x32x16_bf16 v[48:63], v[92:95], v[136:139], v[48:63]
	v_mfma_f32_32x32x16_bf16 v[0:15], v[80:83], v[124:127], v[0:15]
	v_mfma_f32_32x32x16_bf16 v[16:31], v[80:83], v[140:143], v[16:31]
	v_mfma_f32_32x32x16_bf16 v[32:47], v[96:99], v[124:127], v[32:47]
	v_mfma_f32_32x32x16_bf16 v[48:63], v[96:99], v[140:143], v[48:63]
	v_mfma_f32_32x32x16_bf16 v[0:15], v[84:87], v[128:131], v[0:15]
	v_mfma_f32_32x32x16_bf16 v[16:31], v[84:87], v[144:147], v[16:31]
	v_mfma_f32_32x32x16_bf16 v[32:47], v[112:115], v[128:131], v[32:47]
	v_mfma_f32_32x32x16_bf16 v[48:63], v[112:115], v[144:147], v[48:63]
	v_mfma_f32_32x32x16_bf16 v[0:15], v[88:91], v[132:135], v[0:15]
	v_mfma_f32_32x32x16_bf16 v[16:31], v[88:91], v[148:151], v[16:31]
	v_mfma_f32_32x32x16_bf16 v[32:47], v[116:119], v[132:135], v[32:47]
	v_mfma_f32_32x32x16_bf16 v[48:63], v[116:119], v[148:151], v[48:63]
	s_waitcnt vmcnt(8) lgkmcnt(0)
	ds_write_b128 v221, v[152:155]
	ds_write_b128 v221, v[156:159] offset:1152
	ds_write_b128 v221, v[160:163] offset:2304
	ds_write_b128 v221, v[164:167] offset:3456
	ds_write_b128 v221, v[168:171] offset:4608
	ds_write_b128 v221, v[172:175] offset:5760
	ds_write_b128 v221, v[176:179] offset:6912
	ds_write_b128 v221, v[180:183] offset:8064
	s_waitcnt lgkmcnt(0)
; DI f32x16 mfma32(bf16x8 a, bf16x8 b, f32x16 c) { return __builtin_amdgcn_mfma_f32_32x32x16_bf16(a, b, c, 0, 0, 0); }
; template <int EPI, int K, int LNI>
; DI void gemm_tail_unit(const Params& p, const bf16_t* __restrict__ A, const bf16_t* __restrict__ Bt, const int un, float* s_aux) {
;     ...
; #pragma unroll 8
;     for (int s = 0; s < KS / 16; ++s) {
;         const bf16x8 a0 = *(const bf16x8*)(ap + s * 16), a1 = *(const bf16x8*)(ap + (size_t)32 * K + s * 16);
;         const bf16x8 b0 = *(const bf16x8*)(bp + s * 16), b1 = *(const bf16x8*)(bp + (size_t)32 * K + s * 16);
;         acc[0][0] = mfma32(a0, b0, acc[0][0]); acc[0][1] = mfma32(a0, b1, acc[0][1]);
;         acc[1][0] = mfma32(a1, b0, acc[1][0]); acc[1][1] = mfma32(a1, b1, acc[1][1]);
;     }
;     float* red = (float*)dsm;
; #pragma unroll
;     for (int i = 0; i < 2; ++i)
; #pragma unroll
;         for (int j = 0; j < 2; ++j)
; #pragma unroll
;             for (int reg = 0; reg < 16; ++reg) red[((w * 4 + i * 2 + j) * 16 + reg) * 64 + lane] = acc[i][j][reg];
;     __syncthreads();
	ds_read_b128 v[152:155], v222
	ds_read_b128 v[156:159], v222 offset:32
	ds_read_b128 v[160:163], v222 offset:64
	ds_read_b128 v[164:167], v222 offset:96
	ds_read_b128 v[168:171], v222 offset:4608
	ds_read_b128 v[172:175], v222 offset:4640
	ds_read_b128 v[176:179], v222 offset:4672
	ds_read_b128 v[180:183], v222 offset:4704
	s_waitcnt vmcnt(0) lgkmcnt(0)
	ds_write_b128 v221, v[184:187]
	ds_write_b128 v221, v[188:191] offset:1152
	ds_write_b128 v221, v[192:195] offset:2304
	ds_write_b128 v221, v[196:199] offset:3456
	ds_write_b128 v221, v[200:203] offset:4608
	ds_write_b128 v221, v[204:207] offset:5760
	ds_write_b128 v221, v[212:215] offset:6912
	ds_write_b128 v221, v[216:219] offset:8064
	s_waitcnt lgkmcnt(0)
	ds_read_b128 v[184:187], v222
	ds_read_b128 v[188:191], v222 offset:32
	ds_read_b128 v[192:195], v222 offset:64
	ds_read_b128 v[196:199], v222 offset:96
	ds_read_b128 v[200:203], v222 offset:4608
	ds_read_b128 v[204:207], v222 offset:4640
	ds_read_b128 v[212:215], v222 offset:4672
	ds_read_b128 v[216:219], v222 offset:4704
	s_waitcnt lgkmcnt(0)
	v_mfma_f32_32x32x16_bf16 v[0:15], v[152:155], v[184:187], v[0:15]
	v_mfma_f32_32x32x16_bf16 v[16:31], v[152:155], v[200:203], v[16:31]
	v_mfma_f32_32x32x16_bf16 v[32:47], v[168:171], v[184:187], v[32:47]
	v_mfma_f32_32x32x16_bf16 v[48:63], v[168:171], v[200:203], v[48:63]
	v_mfma_f32_32x32x16_bf16 v[0:15], v[156:159], v[188:191], v[0:15]
	v_mfma_f32_32x32x16_bf16 v[16:31], v[156:159], v[204:207], v[16:31]
	v_mfma_f32_32x32x16_bf16 v[32:47], v[172:175], v[188:191], v[32:47]
	v_mfma_f32_32x32x16_bf16 v[48:63], v[172:175], v[204:207], v[48:63]
	v_mfma_f32_32x32x16_bf16 v[0:15], v[160:163], v[192:195], v[0:15]
	v_mfma_f32_32x32x16_bf16 v[16:31], v[160:163], v[212:215], v[16:31]
	v_mfma_f32_32x32x16_bf16 v[32:47], v[176:179], v[192:195], v[32:47]
	v_mfma_f32_32x32x16_bf16 v[48:63], v[176:179], v[212:215], v[48:63]
	v_mfma_f32_32x32x16_bf16 v[0:15], v[164:167], v[196:199], v[0:15]
	v_mfma_f32_32x32x16_bf16 v[16:31], v[164:167], v[216:219], v[16:31]
	v_mfma_f32_32x32x16_bf16 v[32:47], v[180:183], v[196:199], v[32:47]
	v_mfma_f32_32x32x16_bf16 v[48:63], v[180:183], v[216:219], v[48:63]
	s_nop 7
	v_and_b32_e32 v64, 63, v71
	v_lshl_add_u32 v64, v64, 2, 0
	v_lshl_add_u32 v66, v72, 14, v64
	s_nop 2
	ds_write2st64_b32 v66, v0, v1 offset1:1
	ds_write2st64_b32 v66, v2, v3 offset0:2 offset1:3
	ds_write2st64_b32 v66, v4, v5 offset0:4 offset1:5
	ds_write2st64_b32 v66, v6, v7 offset0:6 offset1:7
	ds_write2st64_b32 v66, v8, v9 offset0:8 offset1:9
	ds_write2st64_b32 v66, v10, v11 offset0:10 offset1:11
	ds_write2st64_b32 v66, v12, v13 offset0:12 offset1:13
	ds_write2st64_b32 v66, v14, v15 offset0:14 offset1:15
	ds_write2st64_b32 v66, v16, v17 offset0:16 offset1:17
	ds_write2st64_b32 v66, v18, v19 offset0:18 offset1:19
	ds_write2st64_b32 v66, v20, v21 offset0:20 offset1:21
	ds_write2st64_b32 v66, v22, v23 offset0:22 offset1:23
	ds_write2st64_b32 v66, v24, v25 offset0:24 offset1:25
	ds_write2st64_b32 v66, v26, v27 offset0:26 offset1:27
	ds_write2st64_b32 v66, v28, v29 offset0:28 offset1:29
	ds_write2st64_b32 v66, v30, v31 offset0:30 offset1:31
	ds_write2st64_b32 v66, v32, v33 offset0:32 offset1:33
	ds_write2st64_b32 v66, v34, v35 offset0:34 offset1:35
	ds_write2st64_b32 v66, v36, v37 offset0:36 offset1:37
	ds_write2st64_b32 v66, v38, v39 offset0:38 offset1:39
	ds_write2st64_b32 v66, v40, v41 offset0:40 offset1:41
	ds_write2st64_b32 v66, v42, v43 offset0:42 offset1:43
	ds_write2st64_b32 v66, v44, v45 offset0:44 offset1:45
	ds_write2st64_b32 v66, v46, v47 offset0:46 offset1:47
	ds_write2st64_b32 v66, v48, v49 offset0:48 offset1:49
	ds_write2st64_b32 v66, v50, v51 offset0:50 offset1:51
	ds_write2st64_b32 v66, v52, v53 offset0:52 offset1:53
	ds_write2st64_b32 v66, v54, v55 offset0:54 offset1:55
	ds_write2st64_b32 v66, v56, v57 offset0:56 offset1:57
	ds_write2st64_b32 v66, v58, v59 offset0:58 offset1:59
	ds_write2st64_b32 v66, v60, v61 offset0:60 offset1:61
	ds_write2st64_b32 v66, v62, v63 offset0:62 offset1:63
	v_ashrrev_i32_e32 v0, 7, v71
	v_lshlrev_b32_e32 v1, 1, v72
	v_and_b32_e32 v34, 2, v1
	v_lshlrev_b32_e32 v35, 12, v0
	v_ashrrev_i32_e32 v1, 3, v71
	v_lshl_or_b32 v37, v34, 10, v35
	s_lshl_b32 s4, s2, 6
	v_and_b32_e32 v1, 0xffffffe0, v1
	v_lshrrev_b32_e32 v2, 3, v71
	v_lshlrev_b32_e32 v0, 5, v0
	v_add_u32_e32 v32, v64, v37
	s_waitcnt lgkmcnt(0)
	s_barrier
; DI float ex2(float x) { return __builtin_amdgcn_exp2f(x); }
;     ...
;         float* d = (float*)(p.ws + OFF_H) + (size_t)row0 * 1024 + col;
; #pragma unroll
;         for (int e = 0; e < 4; ++e) {
;             float hprev = d[(size_t)e * 1024];
;             if (LNI >= 0) hprev = (hprev - rs[e][0]) * rs[e][1] * gg + bb;
;             d[(size_t)e * 1024] = ALPHA * hprev + v[e];
; template <int EPI, int K, int LNI>
; DI void gemm_tail_unit(const Params& p, const bf16_t* __restrict__ A, const bf16_t* __restrict__ Bt, const int un, float* s_aux) {
;     ...
;     {
;         const int tile = w >> 1, i = tile >> 1, j = tile & 1;
; #pragma unroll
;         for (int gg = 0; gg < 2; ++gg) {
;             const int g = 2 * (w & 1) + gg;
;             float v[4];
; #pragma unroll
;             for (int e = 0; e < 4; ++e) {
;                 float sacc = 0.f;
; #pragma unroll
;                 for (int wv = 0; wv < 8; ++wv) sacc += red[((wv * 4 + tile) * 16 + 4 * g + e) * 64 + lane];
;                 v[e] = sacc;
;             }
;             const int lrow0 = i * 32 + 8 * g + 4 * h;
;             f32x2 rs[4]; float lng = 1.f, lnb = 0.f;
;             if (EPI == EPI_E5) {
;                 lng = log2f(1.f - ex2(-5.f - (float)((col0 >> 8) & 3)));
;                 const int idx_ = (((ROW0 + lrow0) % LT) + 48) & 63;
; #pragma unroll
;                 for (int e = 0; e < 4; ++e) rs[e] = (f32x2){ex2(lng * (float)(idx_ + e + 1)), 0.0625f * ex2(lng * (float)(63 - idx_ - e))};
;             }
;             if (EPI == EPI_RESID && LNI >= 0) {
;                 const f32x2* st_ = (const f32x2*)((unsigned char*)p.out + OFFO_STATS) + ROW0 + lrow0;
; #pragma unroll
;                 for (int e = 0; e < 4; ++e) rs[e] = st_[e];
;                 lng = p.ln_g[(LNI < 0 ? 0 : LNI) * 1024 + col0 + j * 32 + r]; lnb = p.ln_b[(LNI < 0 ? 0 : LNI) * 1024 + col0 + j * 32 + r];
;             }
;             epi_store<EPI, LNI>(p, ROW0 + lrow0, col0 + j * 32 + r, lrow0, v, s_aux, rs, lng, lnb);
	v_and_or_b32 v36, v2, 4, v1
	s_add_i32 s5, s4, 0x800
	v_and_b32_e32 v4, 32, v0
	ds_read2st64_b32 v[14:15], v32 offset1:1
	ds_read2st64_b32 v[16:17], v32 offset0:64 offset1:65
	v_or3_b32 v0, v4, s5, v70
	v_or3_b32 v4, v70, s4, v4
	v_lshl_or_b32 v24, v34, 3, v36
	v_ashrrev_i32_e32 v5, 31, v4
	v_ashrrev_i32_e32 v25, 31, v24
	v_ashrrev_i32_e32 v1, 31, v0
	v_lshl_add_u64 v[4:5], v[4:5], 2, s[16:17]
	v_lshl_add_u64 v[26:27], v[24:25], 3, s[0:1]
	v_lshlrev_b64 v[24:25], 12, v[24:25]
	v_lshlrev_b64 v[2:3], 2, v[0:1]
	s_waitcnt lgkmcnt(1)
	v_add_f32_e32 v6, 0, v14
	v_lshl_add_u64 v[24:25], v[4:5], 0, v[24:25]
	v_lshl_add_u64 v[0:1], s[62:63], 0, v[2:3]
	v_lshl_add_u64 v[2:3], s[64:65], 0, v[2:3]
	ds_read2st64_b32 v[18:19], v32 offset0:66 offset1:67
	ds_read2st64_b32 v[20:21], v32 offset0:2 offset1:3
	s_waitcnt lgkmcnt(2)
	v_add_f32_e32 v14, v6, v16
	ds_read2st64_b32 v[22:23], v32 offset0:128 offset1:129
	global_load_dwordx4 v[6:9], v[26:27], off offset:16
	global_load_dwordx4 v[10:13], v[26:27], off
	global_load_dword v16, v[0:1], off
	global_load_dword v38, v[2:3], off
	v_add_co_u32_e32 v26, vcc, s11, v24
	s_waitcnt lgkmcnt(1)
	v_add_f32_e32 v20, 0, v20
	v_addc_co_u32_e32 v27, vcc, 0, v25, vcc
	v_add_co_u32_e32 v24, vcc, s12, v24
	global_load_dword v39, v[26:27], off offset:-4096
	s_nop 0
	v_addc_co_u32_e32 v25, vcc, 0, v25, vcc
	ds_read2st64_b32 v[28:29], v32 offset0:192 offset1:193
	ds_read2st64_b32 v[30:31], v32 offset0:194 offset1:195
	ds_read2st64_b32 v[32:33], v32 offset0:130 offset1:131
	global_load_dword v40, v[24:25], off offset:-4096
	global_load_dword v43, v[24:25], off
	s_waitcnt lgkmcnt(3)
	v_add_f32_e32 v14, v14, v22
	global_load_dword v22, v[26:27], off
	s_waitcnt lgkmcnt(2)
	v_add_f32_e32 v14, v14, v28
	v_add_u32_e32 v28, 0x10000, v64
	v_add_u32_e32 v42, 0x14000, v64
	v_add_u32_e32 v45, 0x18000, v64
	v_add_u32_e32 v47, 0x1c000, v64
	v_or_b32_e32 v49, 0x100, v37
	v_add_f32_e32 v15, 0, v15
	v_add_f32_e32 v18, v20, v18
	v_add_u32_e32 v41, v28, v37
	v_add_u32_e32 v44, v42, v37
	v_add_u32_e32 v46, v45, v37
	v_add_u32_e32 v48, v47, v37
	v_add_u32_e32 v50, v28, v49
	v_add_u32_e32 v51, v42, v49
	v_add_u32_e32 v52, v45, v49
	v_add_u32_e32 v49, v47, v49
	v_add_f32_e32 v15, v15, v17
	s_waitcnt lgkmcnt(0)
	v_add_f32_e32 v18, v18, v32
	ds_read_b32 v41, v41
	ds_read_b32 v44, v44
	ds_read_b32 v46, v46
	ds_read_b32 v48, v48
	ds_read_b32 v50, v50
	ds_read_b32 v51, v51
	ds_read_b32 v52, v52
	ds_read_b32 v49, v49
	v_add_f32_e32 v15, v15, v23
	v_or_b32_e32 v17, 0x200, v37
	v_add_f32_e32 v18, v18, v30
	v_or_b32_e32 v30, 0x300, v37
	s_waitcnt lgkmcnt(7)
	v_add_f32_e32 v14, v14, v41
	v_add_f32_e32 v15, v15, v29
	v_add_u32_e32 v20, v28, v17
	v_add_u32_e32 v23, v42, v17
	v_add_u32_e32 v29, v45, v17
	v_add_u32_e32 v17, v47, v17
	v_add_u32_e32 v32, v28, v30
	v_add_u32_e32 v37, v42, v30
	v_add_u32_e32 v41, v45, v30
	v_add_u32_e32 v30, v47, v30
	ds_read_b32 v20, v20
	ds_read_b32 v23, v23
	ds_read_b32 v29, v29
	ds_read_b32 v17, v17
	ds_read_b32 v32, v32
	ds_read_b32 v37, v37
	ds_read_b32 v41, v41
	ds_read_b32 v30, v30
	s_waitcnt lgkmcnt(7)
	v_add_f32_e32 v18, v18, v20
	s_waitcnt lgkmcnt(6)
	v_add_f32_e32 v18, v18, v23
	s_waitcnt lgkmcnt(5)
	v_add_f32_e32 v18, v18, v29
	s_waitcnt lgkmcnt(4)
	v_add_f32_e32 v17, v18, v17
	v_add_f32_e32 v18, 0, v21
	v_add_f32_e32 v14, v14, v44
	v_add_f32_e32 v18, v18, v19
	v_add_f32_e32 v14, v14, v46
	v_add_f32_e32 v18, v18, v33
	v_add_f32_e32 v14, v14, v48
	v_add_f32_e32 v15, v15, v50
	v_add_f32_e32 v18, v18, v31
	v_add_f32_e32 v15, v15, v51
	s_waitcnt lgkmcnt(3)
	v_add_f32_e32 v18, v18, v32
	v_add_f32_e32 v15, v15, v52
	s_waitcnt lgkmcnt(2)
	v_add_f32_e32 v18, v18, v37
	v_add_f32_e32 v15, v15, v49
	s_waitcnt lgkmcnt(1)
	v_add_f32_e32 v18, v18, v41
	s_waitcnt lgkmcnt(0)
	v_add_f32_e32 v18, v18, v30
	s_add_i32 s2, s2, s58
	s_add_i32 s3, s3, s6
	s_cmp_lt_i32 s2, 16
	s_waitcnt vmcnt(3)
	v_sub_f32_e32 v10, v39, v10
	v_mul_f32_e32 v10, v11, v10
	v_fma_f32 v10, v16, v10, v38
	v_fmac_f32_e32 v14, 0x3fb504f3, v10
	s_waitcnt vmcnt(2)
	v_sub_f32_e32 v6, v40, v6
	v_mul_f32_e32 v6, v7, v6
	v_fma_f32 v6, v16, v6, v38
	s_waitcnt vmcnt(0)
; DI float ex2(float x) { return __builtin_amdgcn_exp2f(x); }
;     ...
;         float* d = (float*)(p.ws + OFF_H) + (size_t)row0 * 1024 + col;
; #pragma unroll
;         for (int e = 0; e < 4; ++e) {
;             float hprev = d[(size_t)e * 1024];
;             if (LNI >= 0) hprev = (hprev - rs[e][0]) * rs[e][1] * gg + bb;
;             d[(size_t)e * 1024] = ALPHA * hprev + v[e];
; template <int EPI, int K, int LNI>
; DI void gemm_tail_unit(const Params& p, const bf16_t* __restrict__ A, const bf16_t* __restrict__ Bt, const int un, float* s_aux) {
;     ...
;         const int tile = w >> 1, i = tile >> 1, j = tile & 1;
; #pragma unroll
;         for (int gg = 0; gg < 2; ++gg) {
;             const int g = 2 * (w & 1) + gg;
;             float v[4];
; #pragma unroll
;             for (int e = 0; e < 4; ++e) {
;                 float sacc = 0.f;
; #pragma unroll
;                 for (int wv = 0; wv < 8; ++wv) sacc += red[((wv * 4 + tile) * 16 + 4 * g + e) * 64 + lane];
;                 v[e] = sacc;
;             }
;             const int lrow0 = i * 32 + 8 * g + 4 * h;
;             f32x2 rs[4]; float lng = 1.f, lnb = 0.f;
;             if (EPI == EPI_E5) {
;                 lng = log2f(1.f - ex2(-5.f - (float)((col0 >> 8) & 3)));
;                 const int idx_ = (((ROW0 + lrow0) % LT) + 48) & 63;
; #pragma unroll
;                 for (int e = 0; e < 4; ++e) rs[e] = (f32x2){ex2(lng * (float)(idx_ + e + 1)), 0.0625f * ex2(lng * (float)(63 - idx_ - e))};
;             }
;             if (EPI == EPI_RESID && LNI >= 0) {
;                 const f32x2* st_ = (const f32x2*)((unsigned char*)p.out + OFFO_STATS) + ROW0 + lrow0;
; #pragma unroll
;                 for (int e = 0; e < 4; ++e) rs[e] = st_[e];
;                 lng = p.ln_g[(LNI < 0 ? 0 : LNI) * 1024 + col0 + j * 32 + r]; lnb = p.ln_b[(LNI < 0 ? 0 : LNI) * 1024 + col0 + j * 32 + r];
;             }
;             epi_store<EPI, LNI>(p, ROW0 + lrow0, col0 + j * 32 + r, lrow0, v, s_aux, rs, lng, lnb);
;         }
;     }
;     __syncthreads();
	v_sub_f32_e32 v10, v22, v12
	v_fmac_f32_e32 v17, 0x3fb504f3, v6
	v_sub_f32_e32 v6, v43, v8
	v_mul_f32_e32 v10, v13, v10
	v_mul_f32_e32 v6, v9, v6
	v_fma_f32 v10, v16, v10, v38
	v_fmac_f32_e32 v38, v16, v6
	v_or_b32_e32 v6, 1, v34
	v_fmac_f32_e32 v15, 0x3fb504f3, v10
	v_lshl_or_b32 v29, v6, 10, v35
	v_lshl_or_b32 v22, v6, 3, v36
	global_store_dword v[26:27], v14, off offset:-4096
	global_store_dword v[26:27], v15, off
	v_fmac_f32_e32 v18, 0x3fb504f3, v38
	v_add_u32_e32 v26, v64, v29
	v_ashrrev_i32_e32 v23, 31, v22
	global_store_dword v[24:25], v17, off offset:-4096
	ds_read2st64_b32 v[14:15], v26 offset1:1
	global_store_dword v[24:25], v18, off
	v_lshl_add_u64 v[24:25], v[22:23], 3, s[0:1]
	v_lshlrev_b64 v[22:23], 12, v[22:23]
	v_lshl_add_u64 v[4:5], v[4:5], 0, v[22:23]
	ds_read2st64_b32 v[16:17], v26 offset0:64 offset1:65
	ds_read2st64_b32 v[18:19], v26 offset0:66 offset1:67
	ds_read2st64_b32 v[20:21], v26 offset0:2 offset1:3
	global_load_dwordx4 v[6:9], v[24:25], off offset:16
	global_load_dwordx4 v[10:13], v[24:25], off
	v_add_co_u32_e32 v22, vcc, s11, v4
	s_waitcnt lgkmcnt(3)
	v_add_f32_e32 v14, 0, v14
	v_addc_co_u32_e32 v23, vcc, 0, v5, vcc
	global_load_dword v30, v[22:23], off offset:-4096
	global_load_dword v31, v[0:1], off
	global_load_dword v32, v[2:3], off
	s_waitcnt lgkmcnt(2)
	v_add_f32_e32 v14, v14, v16
	global_load_dword v16, v[22:23], off
	ds_read2st64_b32 v[0:1], v26 offset0:128 offset1:129
	v_add_co_u32_e32 v2, vcc, s12, v4
	v_or_b32_e32 v37, 0x100, v29
	s_nop 0
	v_addc_co_u32_e32 v3, vcc, 0, v5, vcc
	global_load_dword v33, v[2:3], off offset:-4096
	ds_read2st64_b32 v[4:5], v26 offset0:192 offset1:193
	ds_read2st64_b32 v[24:25], v26 offset0:194 offset1:195
	ds_read2st64_b32 v[26:27], v26 offset0:130 offset1:131
	s_waitcnt lgkmcnt(3)
	v_add_f32_e32 v0, v14, v0
	global_load_dword v14, v[2:3], off
	s_waitcnt lgkmcnt(2)
	v_add_f32_e32 v0, v0, v4
	v_add_u32_e32 v4, v28, v29
	v_add_u32_e32 v34, v42, v29
	v_add_u32_e32 v35, v45, v29
	v_add_u32_e32 v36, v47, v29
	v_add_u32_e32 v38, v28, v37
	v_add_u32_e32 v39, v42, v37
	v_add_u32_e32 v40, v45, v37
	v_add_u32_e32 v37, v47, v37
	ds_read_b32 v4, v4
	ds_read_b32 v34, v34
	ds_read_b32 v35, v35
	ds_read_b32 v36, v36
	ds_read_b32 v38, v38
	ds_read_b32 v39, v39
	ds_read_b32 v40, v40
	ds_read_b32 v37, v37
	s_waitcnt lgkmcnt(7)
	v_add_f32_e32 v0, v0, v4
	v_add_f32_e32 v4, 0, v15
	v_add_f32_e32 v4, v4, v17
	v_add_f32_e32 v1, v4, v1
	v_add_f32_e32 v1, v1, v5
	v_add_f32_e32 v5, 0, v20
	v_add_f32_e32 v5, v5, v18
	s_waitcnt lgkmcnt(6)
	v_add_f32_e32 v0, v0, v34
	v_or_b32_e32 v4, 0x200, v29
	v_add_f32_e32 v5, v5, v26
	v_or_b32_e32 v20, 0x300, v29
	s_waitcnt lgkmcnt(5)
	v_add_f32_e32 v0, v0, v35
	v_add_f32_e32 v5, v5, v24
	v_add_u32_e32 v15, v28, v4
	v_add_u32_e32 v17, v42, v4
	v_add_u32_e32 v18, v45, v4
	v_add_u32_e32 v4, v47, v4
	v_add_u32_e32 v24, v28, v20
	v_add_u32_e32 v26, v42, v20
	v_add_u32_e32 v28, v45, v20
	v_add_u32_e32 v20, v47, v20
	s_waitcnt lgkmcnt(4)
	v_add_f32_e32 v0, v0, v36
	ds_read_b32 v15, v15
	ds_read_b32 v17, v17
	ds_read_b32 v18, v18
	ds_read_b32 v4, v4
	ds_read_b32 v24, v24
	ds_read_b32 v26, v26
	ds_read_b32 v28, v28
	ds_read_b32 v20, v20
	s_waitcnt lgkmcnt(7)
	v_add_f32_e32 v5, v5, v15
	v_add_f32_e32 v1, v1, v38
	s_waitcnt lgkmcnt(6)
	v_add_f32_e32 v5, v5, v17
	v_add_f32_e32 v1, v1, v39
	s_waitcnt lgkmcnt(5)
	v_add_f32_e32 v5, v5, v18
	v_add_f32_e32 v1, v1, v40
	s_waitcnt lgkmcnt(4)
	v_add_f32_e32 v4, v5, v4
	v_add_f32_e32 v5, 0, v21
	v_add_f32_e32 v1, v1, v37
	v_add_f32_e32 v5, v5, v19
	v_add_f32_e32 v5, v5, v27
	v_add_f32_e32 v5, v5, v25
	s_waitcnt lgkmcnt(3)
	v_add_f32_e32 v5, v5, v24
	s_waitcnt lgkmcnt(2)
	v_add_f32_e32 v5, v5, v26
	s_waitcnt lgkmcnt(1)
	v_add_f32_e32 v5, v5, v28
	s_waitcnt lgkmcnt(0)
	v_add_f32_e32 v5, v5, v20
	s_waitcnt vmcnt(5)
	v_sub_f32_e32 v10, v30, v10
	v_mul_f32_e32 v10, v11, v10
	s_waitcnt vmcnt(3)
	v_fma_f32 v10, v31, v10, v32
	v_fmac_f32_e32 v0, 0x3fb504f3, v10
	global_store_dword v[22:23], v0, off offset:-4096
	s_waitcnt vmcnt(3)
	v_sub_f32_e32 v0, v16, v12
	v_mul_f32_e32 v0, v13, v0
	v_fma_f32 v0, v31, v0, v32
	v_fmac_f32_e32 v1, 0x3fb504f3, v0
	global_store_dword v[22:23], v1, off
	s_waitcnt vmcnt(3)
	v_sub_f32_e32 v0, v33, v6
	v_mul_f32_e32 v0, v7, v0
	v_fma_f32 v0, v31, v0, v32
	v_fmac_f32_e32 v4, 0x3fb504f3, v0
	s_waitcnt vmcnt(2)
	v_sub_f32_e32 v0, v14, v8
	v_mul_f32_e32 v0, v9, v0
	v_fmac_f32_e32 v32, v31, v0
	v_fmac_f32_e32 v5, 0x3fb504f3, v32
	global_store_dword v[2:3], v4, off offset:-4096
	global_store_dword v[2:3], v5, off
	s_barrier
	s_cbranch_scc1 .LBB0_1938
